# Z_E1_E2
# baseline (speedup 1.0000x reference)
; #define PG8_STAGE(bufoff, gbase, voff) do { _Pragma("unroll") for (int _i = 0; _i < 2; ++_i) \
;         __builtin_amdgcn_global_load_lds((const unsigned*)((const char*)(gbase) + (voff)[_i]), (PG8_LAS unsigned*)(lds + (bufoff) + ldsw + _i * 8192), 16, 0, 0); } while (0)
; #define PG8_LDA(dst, b, h) do { _Pragma("unroll") for (int m = 0; m < 4; ++m) _Pragma("unroll") for (int k = 0; k < 2; ++k) dst[m][k] = *(const PG8_LAS bf16x8*)(lds + PG8_SA(b, h) + aoff + m * 2048 + k * 1024); } while (0)
; #define PG8_LDB(dst, b, h) do { _Pragma("unroll") for (int n = 0; n < 2; ++n) _Pragma("unroll") for (int k = 0; k < 2; ++k) dst[n][k] = *(const PG8_LAS bf16x8*)(lds + PG8_SB(b, h) + boff + n * 2048 + k * 1024); } while (0)
; #define PG8_WAIT_V(n) asm volatile("s_waitcnt vmcnt(" #n ")" ::: "memory")
; #define PG8_WAIT_L(n) asm volatile("s_waitcnt lgkmcnt(" #n ")" ::: "memory")
; #define PG8_BAR __builtin_amdgcn_s_barrier()
; #define PG8_SCHED __builtin_amdgcn_sched_barrier(0)
; template <class Epi, class Sched, bool ALIGN_EPI = false, bool SP2 = false, bool DUAL = false>
; __device__ __forceinline__ void gemm_phase(PG8_LAS unsigned char* lds, const Gemm g, const Sched& S, const Epi& E) {
;     ...
;         const char* nA = has_next ? (const char*)((DUAL && nxt.sub) ? g.A2 : g.A) + (size_t)nxt.pm * tstep : cA; const char* nB = has_next ? (const char*)((DUAL && nxt.sub) ? g.Bt2 : g.Bt) + (size_t)nxt.pn * tstep : cB;
;         for (int t = 0; t < nt; t += 2) {
;             const bool last = (t == nt - 2);
;             const char* a1 = cA + (size_t)(t + 1) * kstep;
;             const char* a2 = last ? nA : cA + (size_t)(t + 2) * kstep; const char* b2 = last ? nB : cB + (size_t)(t + 2) * kstep;
;             const char* a3 = a2 + kstep; const char* b3 = b2 + kstep;
;             if (last && has_next) S.a_ready(nxt);
;             if constexpr (SP2) {
;             PG8_LDB(B0, 0, 0); PG8_LDB(B1, 0, 1); PG8_SCHED; PG8_LDA(At, 0, 0); PG8_STAGE(PG8_SA(1, 1), a1 + hstep, voffA);
;             PG8_WAIT_V(8); PG8_WAIT_L(0); PG8_BAR; PG8_MMA(0, 0, At, B0); PG8_MMA(0, 1, At, B1); PG8_BAR; PG8_SCHED;
;             PG8_LDA(At, 0, 1); PG8_STAGE(PG8_SB(0, 0), b2, voffB); PG8_STAGE(PG8_SB(0, 1), b2 + hstep, voffB); PG8_STAGE(PG8_SA(0, 0), a2, voffA);
;             PG8_WAIT_V(8); PG8_WAIT_L(0); PG8_BAR; PG8_MMA(1, 0, At, B0); PG8_MMA(1, 1, At, B1); PG8_BAR; PG8_SCHED;
.LBB0_251:
	s_ashr_i32 s87, s86, 31
	s_lshl_b64 s[16:17], s[86:87], 20
	s_add_u32 s92, s58, s16
	s_addc_u32 s93, s59, s17
	s_and_b64 s[16:17], s[4:5], exec
	s_cselect_b32 s7, s93, s11
	s_cselect_b32 s9, s92, s10
	s_ashr_i32 s1, s0, 31
	s_lshl_b64 s[16:17], s[0:1], 20
	s_add_u32 s88, s90, s16
	s_addc_u32 s89, s91, s17
	s_and_b64 s[16:17], s[4:5], exec
	s_cselect_b32 s1, s89, s15
	s_cselect_b32 s45, s88, s14
	s_add_u32 s10, s10, 0x80080
	s_addc_u32 s11, s11, 0
	s_add_u32 s46, s14, 0x100
	s_addc_u32 s47, s15, 0
	s_mov_b32 s48, -2
	ds_read_b128 v[80:83], v199
	ds_read_b128 v[84:87], v199 offset:1024
	ds_read_b128 v[88:91], v199 offset:2048
	ds_read_b128 v[92:95], v199 offset:3072
	ds_read_b128 v[144:147], v202
	ds_read_b128 v[148:151], v202 offset:1024
	ds_read_b128 v[152:155], v202 offset:2048
	ds_read_b128 v[156:159], v202 offset:3072
	s_add_u32 s14, s10, 0xfff80080
	s_addc_u32 s15, s11, -1
	s_cmp_eq_u32 s48, 28
	s_cselect_b32 s17, s7, s15
	s_cselect_b32 s16, s9, s14
	s_cselect_b32 s15, s1, s47
	s_cselect_b32 s14, s45, s46
	v_lshl_add_u64 v[192:193], s[10:11], 0, v[186:187]
	s_add_i32 m0, s19, 0xc000
	ds_read_b128 v[208:211], v203
	ds_read_b128 v[212:215], v203 offset:1024
	ds_read_b128 v[216:219], v203 offset:2048
	ds_read_b128 v[220:223], v203 offset:3072
	ds_read_b128 v[232:235], v203 offset:4096
	ds_read_b128 v[236:239], v203 offset:5120
	ds_read_b128 v[240:243], v203 offset:6144
	ds_read_b128 v[244:247], v203 offset:7168
	global_load_lds_dwordx4 v[192:193], off
	v_lshl_add_u64 v[192:193], s[10:11], 0, v[188:189]
	s_add_i32 m0, s19, 0xe000
	s_nop 0
	global_load_lds_dwordx4 v[192:193], off
	s_waitcnt vmcnt(8)
	s_waitcnt lgkmcnt(0)
	s_setprio 1
	s_barrier
	v_mfma_f32_16x16x32_bf16 v[140:143], v[80:83], v[208:211], 0
	v_mfma_f32_16x16x32_bf16 v[132:135], v[88:91], v[208:211], 0
	v_mfma_f32_16x16x32_bf16 v[124:127], v[80:83], v[216:219], 0
	v_mfma_f32_16x16x32_bf16 v[120:123], v[88:91], v[216:219], 0
	v_mfma_f32_16x16x32_bf16 v[108:111], v[80:83], v[232:235], 0
	v_mfma_f32_16x16x32_bf16 v[104:107], v[88:91], v[232:235], 0
	v_mfma_f32_16x16x32_bf16 v[76:79], v[80:83], v[240:243], 0
	v_mfma_f32_16x16x32_bf16 v[72:75], v[88:91], v[240:243], 0
	v_mfma_f32_16x16x32_bf16 v[140:143], v[84:87], v[212:215], v[140:143]
	v_mfma_f32_16x16x32_bf16 v[132:135], v[92:95], v[212:215], v[132:135]
	v_mfma_f32_16x16x32_bf16 v[124:127], v[84:87], v[220:223], v[124:127]
	v_mfma_f32_16x16x32_bf16 v[120:123], v[92:95], v[220:223], v[120:123]
	v_mfma_f32_16x16x32_bf16 v[108:111], v[84:87], v[236:239], v[108:111]
	v_mfma_f32_16x16x32_bf16 v[104:107], v[92:95], v[236:239], v[104:107]
	v_mfma_f32_16x16x32_bf16 v[76:79], v[84:87], v[244:247], v[76:79]
	v_mfma_f32_16x16x32_bf16 v[72:75], v[92:95], v[244:247], v[72:75]
	v_mfma_f32_16x16x32_bf16 v[136:139], v[144:147], v[208:211], 0
	v_mfma_f32_16x16x32_bf16 v[128:131], v[152:155], v[208:211], 0
	v_mfma_f32_16x16x32_bf16 v[116:119], v[144:147], v[216:219], 0
	v_mfma_f32_16x16x32_bf16 v[112:115], v[152:155], v[216:219], 0
	v_mfma_f32_16x16x32_bf16 v[100:103], v[144:147], v[232:235], 0
	v_mfma_f32_16x16x32_bf16 v[96:99], v[152:155], v[232:235], 0
	v_mfma_f32_16x16x32_bf16 v[68:71], v[144:147], v[240:243], 0
	v_mfma_f32_16x16x32_bf16 v[64:67], v[152:155], v[240:243], 0
	v_mfma_f32_16x16x32_bf16 v[136:139], v[148:151], v[212:215], v[136:139]
	v_mfma_f32_16x16x32_bf16 v[128:131], v[156:159], v[212:215], v[128:131]
	v_mfma_f32_16x16x32_bf16 v[116:119], v[148:151], v[220:223], v[116:119]
	v_mfma_f32_16x16x32_bf16 v[112:115], v[156:159], v[220:223], v[112:115]
	v_mfma_f32_16x16x32_bf16 v[100:103], v[148:151], v[236:239], v[100:103]
	v_mfma_f32_16x16x32_bf16 v[96:99], v[156:159], v[236:239], v[96:99]
	v_mfma_f32_16x16x32_bf16 v[68:71], v[148:151], v[244:247], v[68:71]
	v_mfma_f32_16x16x32_bf16 v[64:67], v[156:159], v[244:247], v[64:67]
	s_barrier
	s_setprio 0
	s_add_i32 s49, s31, s18
	v_lshl_add_u64 v[192:193], s[14:15], 0, v[166:167]
	s_mov_b32 m0, s49
	ds_read_b128 v[208:211], v203 offset:16384
	ds_read_b128 v[212:215], v203 offset:17408
	ds_read_b128 v[216:219], v203 offset:18432
	ds_read_b128 v[220:223], v203 offset:19456
	ds_read_b128 v[232:235], v203 offset:20480
	ds_read_b128 v[236:239], v203 offset:21504
	ds_read_b128 v[240:243], v203 offset:22528
	ds_read_b128 v[244:247], v203 offset:23552
	global_load_lds_dwordx4 v[192:193], off
	s_add_i32 m0, s49, 0x2000
	s_add_u32 s50, s14, 0x80000
	v_lshl_add_u64 v[248:249], s[14:15], 0, v[170:171]
	s_addc_u32 s51, s15, 0
	s_add_i32 s49, s34, s18
	global_load_lds_dwordx4 v[248:249], off
	v_lshl_add_u64 v[250:251], s[50:51], 0, v[166:167]
	s_mov_b32 m0, s49
	v_lshl_add_u64 v[252:253], s[16:17], 0, v[168:169]
	global_load_lds_dwordx4 v[250:251], off
	v_lshl_add_u64 v[250:251], s[50:51], 0, v[170:171]
	s_add_i32 m0, s49, 0x2000
	s_nop 0
	global_load_lds_dwordx4 v[250:251], off
	v_lshl_add_u64 v[250:251], s[16:17], 0, v[164:165]
	s_mov_b32 m0, s19
	s_nop 0
	global_load_lds_dwordx4 v[250:251], off
	s_mov_b32 m0, s20
	s_nop 0
	global_load_lds_dwordx4 v[252:253], off
	s_waitcnt vmcnt(8)
	s_waitcnt lgkmcnt(0)
	s_setprio 1
	s_barrier
; #define PG8_STAGE(bufoff, gbase, voff) do { _Pragma("unroll") for (int _i = 0; _i < 2; ++_i) \
;         __builtin_amdgcn_global_load_lds((const unsigned*)((const char*)(gbase) + (voff)[_i]), (PG8_LAS unsigned*)(lds + (bufoff) + ldsw + _i * 8192), 16, 0, 0); } while (0)
; #define PG8_LDA(dst, b, h) do { _Pragma("unroll") for (int m = 0; m < 4; ++m) _Pragma("unroll") for (int k = 0; k < 2; ++k) dst[m][k] = *(const PG8_LAS bf16x8*)(lds + PG8_SA(b, h) + aoff + m * 2048 + k * 1024); } while (0)
; #define PG8_LDB(dst, b, h) do { _Pragma("unroll") for (int n = 0; n < 2; ++n) _Pragma("unroll") for (int k = 0; k < 2; ++k) dst[n][k] = *(const PG8_LAS bf16x8*)(lds + PG8_SB(b, h) + boff + n * 2048 + k * 1024); } while (0)
; #define PG8_MMA(ai, bj, At, Bt) do { __builtin_amdgcn_s_setprio(1); _Pragma("unroll") for (int m = 0; m < 4; ++m) _Pragma("unroll") for (int n = 0; n < 2; ++n) _Pragma("unroll") for (int k = 0; k < 2; ++k) \
;         acc[ai][bj][m][n] = __builtin_amdgcn_mfma_f32_16x16x32_bf16(Bt[n][k], At[m][k], acc[ai][bj][m][n], 0, 0, 0); __builtin_amdgcn_s_setprio(0); } while (0)
; #define PG8_WAIT_V(n) asm volatile("s_waitcnt vmcnt(" #n ")" ::: "memory")
; #define PG8_WAIT_L(n) asm volatile("s_waitcnt lgkmcnt(" #n ")" ::: "memory")
; #define PG8_BAR __builtin_amdgcn_s_barrier()
; #define PG8_SCHED __builtin_amdgcn_sched_barrier(0)
; template <class Epi, class Sched, bool ALIGN_EPI = false, bool SP2 = false, bool DUAL = false>
; __device__ __forceinline__ void gemm_phase(PG8_LAS unsigned char* lds, const Gemm g, const Sched& S, const Epi& E) {
;     ...
;             PG8_WAIT_V(8); PG8_WAIT_L(0); PG8_BAR; PG8_MMA(1, 0, At, B0); PG8_MMA(1, 1, At, B1); PG8_BAR; PG8_SCHED;
;             PG8_LDB(B0, 1, 0); PG8_LDB(B1, 1, 1); PG8_SCHED; PG8_LDA(At, 1, 0); PG8_STAGE(PG8_SA(0, 1), a2 + hstep, voffA);
;             PG8_WAIT_V(8); PG8_WAIT_L(0); PG8_BAR; PG8_MMA(0, 0, At, B0); PG8_MMA(0, 1, At, B1); PG8_BAR; PG8_SCHED;
	v_mfma_f32_16x16x32_bf16 v[60:63], v[80:83], v[208:211], 0
	v_mfma_f32_16x16x32_bf16 v[56:59], v[88:91], v[208:211], 0
	v_mfma_f32_16x16x32_bf16 v[44:47], v[80:83], v[216:219], 0
	v_mfma_f32_16x16x32_bf16 v[40:43], v[88:91], v[216:219], 0
	v_mfma_f32_16x16x32_bf16 v[28:31], v[80:83], v[232:235], 0
	v_mfma_f32_16x16x32_bf16 v[24:27], v[88:91], v[232:235], 0
	v_mfma_f32_16x16x32_bf16 v[12:15], v[80:83], v[240:243], 0
	v_mfma_f32_16x16x32_bf16 v[8:11], v[88:91], v[240:243], 0
	v_mfma_f32_16x16x32_bf16 v[60:63], v[84:87], v[212:215], v[60:63]
	v_mfma_f32_16x16x32_bf16 v[56:59], v[92:95], v[212:215], v[56:59]
	v_mfma_f32_16x16x32_bf16 v[44:47], v[84:87], v[220:223], v[44:47]
	v_mfma_f32_16x16x32_bf16 v[40:43], v[92:95], v[220:223], v[40:43]
	v_mfma_f32_16x16x32_bf16 v[28:31], v[84:87], v[236:239], v[28:31]
	v_mfma_f32_16x16x32_bf16 v[24:27], v[92:95], v[236:239], v[24:27]
	v_mfma_f32_16x16x32_bf16 v[12:15], v[84:87], v[244:247], v[12:15]
	v_mfma_f32_16x16x32_bf16 v[8:11], v[92:95], v[244:247], v[8:11]
	v_mfma_f32_16x16x32_bf16 v[52:55], v[144:147], v[208:211], 0
	v_mfma_f32_16x16x32_bf16 v[48:51], v[152:155], v[208:211], 0
	v_mfma_f32_16x16x32_bf16 v[36:39], v[144:147], v[216:219], 0
	v_mfma_f32_16x16x32_bf16 v[32:35], v[152:155], v[216:219], 0
	v_mfma_f32_16x16x32_bf16 v[20:23], v[144:147], v[232:235], 0
	v_mfma_f32_16x16x32_bf16 v[16:19], v[152:155], v[232:235], 0
	v_mfma_f32_16x16x32_bf16 v[4:7], v[144:147], v[240:243], 0
	v_mfma_f32_16x16x32_bf16 v[0:3], v[152:155], v[240:243], 0
	v_mfma_f32_16x16x32_bf16 v[52:55], v[148:151], v[212:215], v[52:55]
	v_mfma_f32_16x16x32_bf16 v[48:51], v[156:159], v[212:215], v[48:51]
	v_mfma_f32_16x16x32_bf16 v[36:39], v[148:151], v[220:223], v[36:39]
	v_mfma_f32_16x16x32_bf16 v[32:35], v[156:159], v[220:223], v[32:35]
	v_mfma_f32_16x16x32_bf16 v[20:23], v[148:151], v[236:239], v[20:23]
	v_mfma_f32_16x16x32_bf16 v[16:19], v[156:159], v[236:239], v[16:19]
	v_mfma_f32_16x16x32_bf16 v[4:7], v[148:151], v[244:247], v[4:7]
	v_mfma_f32_16x16x32_bf16 v[0:3], v[156:159], v[244:247], v[0:3]
	s_barrier
	s_setprio 0
	s_add_i32 s49, 0, 0x18000
	s_add_i32 s50, 0, 0x1c000
	v_add_u32_e32 v92, s49, v196
	v_add_u32_e32 v156, s50, v196
	ds_read_b128 v[80:83], v92
	ds_read_b128 v[84:87], v92 offset:1024
	ds_read_b128 v[88:91], v92 offset:2048
	ds_read_b128 v[92:95], v92 offset:3072
	ds_read_b128 v[144:147], v156
	ds_read_b128 v[148:151], v156 offset:1024
	ds_read_b128 v[152:155], v156 offset:2048
	ds_read_b128 v[156:159], v156 offset:3072
	s_add_u32 s16, s16, 0x80000
	s_addc_u32 s17, s17, 0
	s_mov_b32 m0, s21
	v_lshl_add_u64 v[228:229], s[16:17], 0, v[164:165]
	ds_read_b128 v[208:211], v203 offset:32768
	ds_read_b128 v[212:215], v203 offset:33792
	ds_read_b128 v[216:219], v203 offset:34816
	ds_read_b128 v[220:223], v203 offset:35840
	ds_read_b128 v[232:235], v203 offset:36864
	ds_read_b128 v[236:239], v203 offset:37888
	ds_read_b128 v[240:243], v203 offset:38912
	ds_read_b128 v[244:247], v203 offset:39936
	global_load_lds_dwordx4 v[228:229], off
	v_lshl_add_u64 v[228:229], s[16:17], 0, v[168:169]
	s_mov_b32 m0, s22
	s_nop 0
	global_load_lds_dwordx4 v[228:229], off
	s_waitcnt vmcnt(8)
	s_waitcnt lgkmcnt(0)
	s_setprio 1
	s_barrier
	v_mfma_f32_16x16x32_bf16 v[140:143], v[80:83], v[208:211], v[140:143]
	v_mfma_f32_16x16x32_bf16 v[132:135], v[88:91], v[208:211], v[132:135]
	v_mfma_f32_16x16x32_bf16 v[124:127], v[80:83], v[216:219], v[124:127]
	v_mfma_f32_16x16x32_bf16 v[120:123], v[88:91], v[216:219], v[120:123]
	v_mfma_f32_16x16x32_bf16 v[108:111], v[80:83], v[232:235], v[108:111]
	v_mfma_f32_16x16x32_bf16 v[104:107], v[88:91], v[232:235], v[104:107]
	v_mfma_f32_16x16x32_bf16 v[76:79], v[80:83], v[240:243], v[76:79]
	v_mfma_f32_16x16x32_bf16 v[72:75], v[88:91], v[240:243], v[72:75]
	v_mfma_f32_16x16x32_bf16 v[140:143], v[84:87], v[212:215], v[140:143]
	v_mfma_f32_16x16x32_bf16 v[132:135], v[92:95], v[212:215], v[132:135]
	v_mfma_f32_16x16x32_bf16 v[124:127], v[84:87], v[220:223], v[124:127]
	v_mfma_f32_16x16x32_bf16 v[120:123], v[92:95], v[220:223], v[120:123]
	v_mfma_f32_16x16x32_bf16 v[108:111], v[84:87], v[236:239], v[108:111]
	v_mfma_f32_16x16x32_bf16 v[104:107], v[92:95], v[236:239], v[104:107]
	v_mfma_f32_16x16x32_bf16 v[76:79], v[84:87], v[244:247], v[76:79]
	v_mfma_f32_16x16x32_bf16 v[72:75], v[92:95], v[244:247], v[72:75]
	v_mfma_f32_16x16x32_bf16 v[136:139], v[144:147], v[208:211], v[136:139]
	v_mfma_f32_16x16x32_bf16 v[128:131], v[152:155], v[208:211], v[128:131]
	v_mfma_f32_16x16x32_bf16 v[116:119], v[144:147], v[216:219], v[116:119]
	v_mfma_f32_16x16x32_bf16 v[112:115], v[152:155], v[216:219], v[112:115]
	v_mfma_f32_16x16x32_bf16 v[100:103], v[144:147], v[232:235], v[100:103]
	v_mfma_f32_16x16x32_bf16 v[96:99], v[152:155], v[232:235], v[96:99]
	v_mfma_f32_16x16x32_bf16 v[68:71], v[144:147], v[240:243], v[68:71]
	v_mfma_f32_16x16x32_bf16 v[64:67], v[152:155], v[240:243], v[64:67]
	v_mfma_f32_16x16x32_bf16 v[136:139], v[148:151], v[212:215], v[136:139]
	v_mfma_f32_16x16x32_bf16 v[128:131], v[156:159], v[212:215], v[128:131]
	v_mfma_f32_16x16x32_bf16 v[116:119], v[148:151], v[220:223], v[116:119]
	v_mfma_f32_16x16x32_bf16 v[112:115], v[156:159], v[220:223], v[112:115]
	v_mfma_f32_16x16x32_bf16 v[100:103], v[148:151], v[236:239], v[100:103]
	v_mfma_f32_16x16x32_bf16 v[96:99], v[156:159], v[236:239], v[96:99]
	v_mfma_f32_16x16x32_bf16 v[68:71], v[148:151], v[244:247], v[68:71]
	v_mfma_f32_16x16x32_bf16 v[64:67], v[156:159], v[244:247], v[64:67]
	s_barrier
; #define PG8_STAGE(bufoff, gbase, voff) do { _Pragma("unroll") for (int _i = 0; _i < 2; ++_i) \
;         __builtin_amdgcn_global_load_lds((const unsigned*)((const char*)(gbase) + (voff)[_i]), (PG8_LAS unsigned*)(lds + (bufoff) + ldsw + _i * 8192), 16, 0, 0); } while (0)
; #define PG8_LDA(dst, b, h) do { _Pragma("unroll") for (int m = 0; m < 4; ++m) _Pragma("unroll") for (int k = 0; k < 2; ++k) dst[m][k] = *(const PG8_LAS bf16x8*)(lds + PG8_SA(b, h) + aoff + m * 2048 + k * 1024); } while (0)
; #define PG8_LDB(dst, b, h) do { _Pragma("unroll") for (int n = 0; n < 2; ++n) _Pragma("unroll") for (int k = 0; k < 2; ++k) dst[n][k] = *(const PG8_LAS bf16x8*)(lds + PG8_SB(b, h) + boff + n * 2048 + k * 1024); } while (0)
; #define PG8_MMA(ai, bj, At, Bt) do { __builtin_amdgcn_s_setprio(1); _Pragma("unroll") for (int m = 0; m < 4; ++m) _Pragma("unroll") for (int n = 0; n < 2; ++n) _Pragma("unroll") for (int k = 0; k < 2; ++k) \
;         acc[ai][bj][m][n] = __builtin_amdgcn_mfma_f32_16x16x32_bf16(Bt[n][k], At[m][k], acc[ai][bj][m][n], 0, 0, 0); __builtin_amdgcn_s_setprio(0); } while (0)
; #define PG8_WAIT_V(n) asm volatile("s_waitcnt vmcnt(" #n ")" ::: "memory")
; #define PG8_WAIT_L(n) asm volatile("s_waitcnt lgkmcnt(" #n ")" ::: "memory")
; #define PG8_BAR __builtin_amdgcn_s_barrier()
; #define PG8_SCHED __builtin_amdgcn_sched_barrier(0)
; template <class Epi, class Sched, bool ALIGN_EPI = false, bool SP2 = false, bool DUAL = false>
; __device__ __forceinline__ void gemm_phase(PG8_LAS unsigned char* lds, const Gemm g, const Sched& S, const Epi& E) {
;     ...
;             PG8_LDB(B0, 0, 0); PG8_LDB(B1, 0, 1); PG8_SCHED; PG8_LDA(At, 0, 0); PG8_STAGE(PG8_SA(1, 1), a1 + hstep, voffA);
;             PG8_WAIT_V(8); PG8_WAIT_L(0); PG8_BAR; PG8_MMA(0, 0, At, B0); PG8_MMA(0, 1, At, B1); PG8_BAR; PG8_SCHED;
;     ...
;             PG8_LDA(At, 1, 1); PG8_STAGE(PG8_SB(1, 0), b3, voffB); PG8_STAGE(PG8_SB(1, 1), b3 + hstep, voffB); PG8_STAGE(PG8_SA(1, 0), a3, voffA);
;             PG8_WAIT_V(8); PG8_WAIT_L(0); PG8_BAR; PG8_MMA(1, 0, At, B0); PG8_MMA(1, 1, At, B1); PG8_BAR; PG8_SCHED;
	s_setprio 0
	s_add_i32 s16, s49, s18
	v_lshl_add_u64 v[192:193], v[192:193], 0, s[76:77]
	s_mov_b32 m0, s16
	ds_read_b128 v[208:211], v203 offset:49152
	ds_read_b128 v[212:215], v203 offset:50176
	ds_read_b128 v[216:219], v203 offset:51200
	ds_read_b128 v[220:223], v203 offset:52224
	ds_read_b128 v[232:235], v203 offset:53248
	ds_read_b128 v[236:239], v203 offset:54272
	ds_read_b128 v[240:243], v203 offset:55296
	ds_read_b128 v[244:247], v203 offset:56320
	global_load_lds_dwordx4 v[192:193], off
	s_add_i32 m0, s16, 0x2000
	s_add_u32 s14, s14, 0x80080
	v_lshl_add_u64 v[192:193], v[248:249], 0, s[76:77]
	s_addc_u32 s15, s15, 0
	s_add_i32 s16, s50, s18
	global_load_lds_dwordx4 v[192:193], off
	v_lshl_add_u64 v[192:193], s[14:15], 0, v[166:167]
	s_mov_b32 m0, s16
	s_nop 0
	global_load_lds_dwordx4 v[192:193], off
	v_lshl_add_u64 v[192:193], s[14:15], 0, v[170:171]
	s_add_i32 m0, s16, 0x2000
	s_nop 0
	global_load_lds_dwordx4 v[192:193], off
	v_lshl_add_u64 v[192:193], v[250:251], 0, s[76:77]
	s_mov_b32 m0, s27
	s_nop 0
	global_load_lds_dwordx4 v[192:193], off
	v_lshl_add_u64 v[192:193], v[252:253], 0, s[76:77]
	s_mov_b32 m0, s28
	s_nop 0
	global_load_lds_dwordx4 v[192:193], off
	s_waitcnt vmcnt(8)
	s_waitcnt lgkmcnt(0)
	s_setprio 1
	s_barrier
	v_mfma_f32_16x16x32_bf16 v[60:63], v[80:83], v[208:211], v[60:63]
	v_mfma_f32_16x16x32_bf16 v[56:59], v[88:91], v[208:211], v[56:59]
	v_mfma_f32_16x16x32_bf16 v[44:47], v[80:83], v[216:219], v[44:47]
	v_mfma_f32_16x16x32_bf16 v[40:43], v[88:91], v[216:219], v[40:43]
	v_mfma_f32_16x16x32_bf16 v[28:31], v[80:83], v[232:235], v[28:31]
	v_mfma_f32_16x16x32_bf16 v[24:27], v[88:91], v[232:235], v[24:27]
	v_mfma_f32_16x16x32_bf16 v[12:15], v[80:83], v[240:243], v[12:15]
	v_mfma_f32_16x16x32_bf16 v[8:11], v[88:91], v[240:243], v[8:11]
	v_mfma_f32_16x16x32_bf16 v[60:63], v[84:87], v[212:215], v[60:63]
	v_mfma_f32_16x16x32_bf16 v[56:59], v[92:95], v[212:215], v[56:59]
	v_mfma_f32_16x16x32_bf16 v[44:47], v[84:87], v[220:223], v[44:47]
	v_mfma_f32_16x16x32_bf16 v[40:43], v[92:95], v[220:223], v[40:43]
	v_mfma_f32_16x16x32_bf16 v[28:31], v[84:87], v[236:239], v[28:31]
	v_mfma_f32_16x16x32_bf16 v[24:27], v[92:95], v[236:239], v[24:27]
	v_mfma_f32_16x16x32_bf16 v[12:15], v[84:87], v[244:247], v[12:15]
	v_mfma_f32_16x16x32_bf16 v[8:11], v[92:95], v[244:247], v[8:11]
	v_mfma_f32_16x16x32_bf16 v[52:55], v[144:147], v[208:211], v[52:55]
	v_mfma_f32_16x16x32_bf16 v[48:51], v[152:155], v[208:211], v[48:51]
	v_mfma_f32_16x16x32_bf16 v[36:39], v[144:147], v[216:219], v[36:39]
	v_mfma_f32_16x16x32_bf16 v[32:35], v[152:155], v[216:219], v[32:35]
	v_mfma_f32_16x16x32_bf16 v[20:23], v[144:147], v[232:235], v[20:23]
	v_mfma_f32_16x16x32_bf16 v[16:19], v[152:155], v[232:235], v[16:19]
	v_mfma_f32_16x16x32_bf16 v[4:7], v[144:147], v[240:243], v[4:7]
	v_mfma_f32_16x16x32_bf16 v[0:3], v[152:155], v[240:243], v[0:3]
	v_mfma_f32_16x16x32_bf16 v[52:55], v[148:151], v[212:215], v[52:55]
	v_mfma_f32_16x16x32_bf16 v[48:51], v[156:159], v[212:215], v[48:51]
	v_mfma_f32_16x16x32_bf16 v[36:39], v[148:151], v[220:223], v[36:39]
	v_mfma_f32_16x16x32_bf16 v[32:35], v[156:159], v[220:223], v[32:35]
	v_mfma_f32_16x16x32_bf16 v[20:23], v[148:151], v[236:239], v[20:23]
	v_mfma_f32_16x16x32_bf16 v[16:19], v[156:159], v[236:239], v[16:19]
	v_mfma_f32_16x16x32_bf16 v[4:7], v[148:151], v[244:247], v[4:7]
	v_mfma_f32_16x16x32_bf16 v[0:3], v[156:159], v[244:247], v[0:3]
	s_barrier
	s_setprio 0
	s_add_i32 s48, s48, 2
	s_add_u32 s10, s10, 0x100
	s_addc_u32 s11, s11, 0
	s_add_u32 s46, s46, 0x100
	s_addc_u32 s47, s47, 0
.LBB0_252:
	ds_read_b128 v[80:83], v199
	ds_read_b128 v[84:87], v199 offset:1024
	ds_read_b128 v[88:91], v199 offset:2048
	ds_read_b128 v[92:95], v199 offset:3072
	ds_read_b128 v[144:147], v202
	ds_read_b128 v[148:151], v202 offset:1024
	ds_read_b128 v[152:155], v202 offset:2048
	ds_read_b128 v[156:159], v202 offset:3072
	s_add_u32 s14, s10, 0xfff80080
	s_addc_u32 s15, s11, -1
	s_cmp_eq_u32 s48, 28
	s_cselect_b32 s17, s7, s15
	s_cselect_b32 s16, s9, s14
	s_cselect_b32 s15, s1, s47
	s_cselect_b32 s14, s45, s46
	v_lshl_add_u64 v[192:193], s[10:11], 0, v[186:187]
	s_add_i32 m0, s19, 0xc000
	ds_read_b128 v[208:211], v203
	ds_read_b128 v[212:215], v203 offset:1024
	ds_read_b128 v[216:219], v203 offset:2048
	ds_read_b128 v[220:223], v203 offset:3072
	ds_read_b128 v[232:235], v203 offset:4096
	ds_read_b128 v[236:239], v203 offset:5120
	ds_read_b128 v[240:243], v203 offset:6144
	ds_read_b128 v[244:247], v203 offset:7168
	global_load_lds_dwordx4 v[192:193], off
	v_lshl_add_u64 v[192:193], s[10:11], 0, v[188:189]
	s_add_i32 m0, s19, 0xe000
	s_nop 0
	global_load_lds_dwordx4 v[192:193], off
	s_waitcnt vmcnt(8)
	s_waitcnt lgkmcnt(0)
	s_setprio 1
	s_barrier
; #define PG8_STAGE(bufoff, gbase, voff) do { _Pragma("unroll") for (int _i = 0; _i < 2; ++_i) \
;         __builtin_amdgcn_global_load_lds((const unsigned*)((const char*)(gbase) + (voff)[_i]), (PG8_LAS unsigned*)(lds + (bufoff) + ldsw + _i * 8192), 16, 0, 0); } while (0)
; #define PG8_LDA(dst, b, h) do { _Pragma("unroll") for (int m = 0; m < 4; ++m) _Pragma("unroll") for (int k = 0; k < 2; ++k) dst[m][k] = *(const PG8_LAS bf16x8*)(lds + PG8_SA(b, h) + aoff + m * 2048 + k * 1024); } while (0)
; #define PG8_MMA(ai, bj, At, Bt) do { __builtin_amdgcn_s_setprio(1); _Pragma("unroll") for (int m = 0; m < 4; ++m) _Pragma("unroll") for (int n = 0; n < 2; ++n) _Pragma("unroll") for (int k = 0; k < 2; ++k) \
;         acc[ai][bj][m][n] = __builtin_amdgcn_mfma_f32_16x16x32_bf16(Bt[n][k], At[m][k], acc[ai][bj][m][n], 0, 0, 0); __builtin_amdgcn_s_setprio(0); } while (0)
; #define PG8_WAIT_V(n) asm volatile("s_waitcnt vmcnt(" #n ")" ::: "memory")
; #define PG8_WAIT_L(n) asm volatile("s_waitcnt lgkmcnt(" #n ")" ::: "memory")
; #define PG8_BAR __builtin_amdgcn_s_barrier()
; #define PG8_SCHED __builtin_amdgcn_sched_barrier(0)
; template <class Epi, class Sched, bool ALIGN_EPI = false, bool SP2 = false, bool DUAL = false>
; __device__ __forceinline__ void gemm_phase(PG8_LAS unsigned char* lds, const Gemm g, const Sched& S, const Epi& E) {
;     ...
;             PG8_WAIT_V(8); PG8_WAIT_L(0); PG8_BAR; PG8_MMA(0, 0, At, B0); PG8_MMA(0, 1, At, B1); PG8_BAR; PG8_SCHED;
;             PG8_LDA(At, 0, 1); PG8_STAGE(PG8_SB(0, 0), b2, voffB); PG8_STAGE(PG8_SB(0, 1), b2 + hstep, voffB); PG8_STAGE(PG8_SA(0, 0), a2, voffA);
;             PG8_WAIT_V(8); PG8_WAIT_L(0); PG8_BAR; PG8_MMA(1, 0, At, B0); PG8_MMA(1, 1, At, B1); PG8_BAR; PG8_SCHED;
	v_mfma_f32_16x16x32_bf16 v[140:143], v[80:83], v[208:211], v[140:143]
	v_mfma_f32_16x16x32_bf16 v[132:135], v[88:91], v[208:211], v[132:135]
	v_mfma_f32_16x16x32_bf16 v[124:127], v[80:83], v[216:219], v[124:127]
	v_mfma_f32_16x16x32_bf16 v[120:123], v[88:91], v[216:219], v[120:123]
	v_mfma_f32_16x16x32_bf16 v[108:111], v[80:83], v[232:235], v[108:111]
	v_mfma_f32_16x16x32_bf16 v[104:107], v[88:91], v[232:235], v[104:107]
	v_mfma_f32_16x16x32_bf16 v[76:79], v[80:83], v[240:243], v[76:79]
	v_mfma_f32_16x16x32_bf16 v[72:75], v[88:91], v[240:243], v[72:75]
	v_mfma_f32_16x16x32_bf16 v[140:143], v[84:87], v[212:215], v[140:143]
	v_mfma_f32_16x16x32_bf16 v[132:135], v[92:95], v[212:215], v[132:135]
	v_mfma_f32_16x16x32_bf16 v[124:127], v[84:87], v[220:223], v[124:127]
	v_mfma_f32_16x16x32_bf16 v[120:123], v[92:95], v[220:223], v[120:123]
	v_mfma_f32_16x16x32_bf16 v[108:111], v[84:87], v[236:239], v[108:111]
	v_mfma_f32_16x16x32_bf16 v[104:107], v[92:95], v[236:239], v[104:107]
	v_mfma_f32_16x16x32_bf16 v[76:79], v[84:87], v[244:247], v[76:79]
	v_mfma_f32_16x16x32_bf16 v[72:75], v[92:95], v[244:247], v[72:75]
	v_mfma_f32_16x16x32_bf16 v[136:139], v[144:147], v[208:211], v[136:139]
	v_mfma_f32_16x16x32_bf16 v[128:131], v[152:155], v[208:211], v[128:131]
	v_mfma_f32_16x16x32_bf16 v[116:119], v[144:147], v[216:219], v[116:119]
	v_mfma_f32_16x16x32_bf16 v[112:115], v[152:155], v[216:219], v[112:115]
	v_mfma_f32_16x16x32_bf16 v[100:103], v[144:147], v[232:235], v[100:103]
	v_mfma_f32_16x16x32_bf16 v[96:99], v[152:155], v[232:235], v[96:99]
	v_mfma_f32_16x16x32_bf16 v[68:71], v[144:147], v[240:243], v[68:71]
	v_mfma_f32_16x16x32_bf16 v[64:67], v[152:155], v[240:243], v[64:67]
	v_mfma_f32_16x16x32_bf16 v[136:139], v[148:151], v[212:215], v[136:139]
	v_mfma_f32_16x16x32_bf16 v[128:131], v[156:159], v[212:215], v[128:131]
	v_mfma_f32_16x16x32_bf16 v[116:119], v[148:151], v[220:223], v[116:119]
	v_mfma_f32_16x16x32_bf16 v[112:115], v[156:159], v[220:223], v[112:115]
	v_mfma_f32_16x16x32_bf16 v[100:103], v[148:151], v[236:239], v[100:103]
	v_mfma_f32_16x16x32_bf16 v[96:99], v[156:159], v[236:239], v[96:99]
	v_mfma_f32_16x16x32_bf16 v[68:71], v[148:151], v[244:247], v[68:71]
	v_mfma_f32_16x16x32_bf16 v[64:67], v[156:159], v[244:247], v[64:67]
	s_barrier
	s_setprio 0
	s_add_i32 s49, s31, s18
	v_lshl_add_u64 v[192:193], s[14:15], 0, v[166:167]
	s_mov_b32 m0, s49
	ds_read_b128 v[208:211], v203 offset:16384
	ds_read_b128 v[212:215], v203 offset:17408
	ds_read_b128 v[216:219], v203 offset:18432
	ds_read_b128 v[220:223], v203 offset:19456
	ds_read_b128 v[232:235], v203 offset:20480
	ds_read_b128 v[236:239], v203 offset:21504
	ds_read_b128 v[240:243], v203 offset:22528
	ds_read_b128 v[244:247], v203 offset:23552
	global_load_lds_dwordx4 v[192:193], off
	s_add_i32 m0, s49, 0x2000
	s_add_u32 s50, s14, 0x80000
	v_lshl_add_u64 v[248:249], s[14:15], 0, v[170:171]
	s_addc_u32 s51, s15, 0
	s_add_i32 s49, s34, s18
	global_load_lds_dwordx4 v[248:249], off
	v_lshl_add_u64 v[250:251], s[50:51], 0, v[166:167]
	s_mov_b32 m0, s49
	v_lshl_add_u64 v[252:253], s[16:17], 0, v[168:169]
	global_load_lds_dwordx4 v[250:251], off
	v_lshl_add_u64 v[250:251], s[50:51], 0, v[170:171]
	s_add_i32 m0, s49, 0x2000
	s_nop 0
	global_load_lds_dwordx4 v[250:251], off
	v_lshl_add_u64 v[250:251], s[16:17], 0, v[164:165]
	s_mov_b32 m0, s19
	s_nop 0
	global_load_lds_dwordx4 v[250:251], off
	s_mov_b32 m0, s20
	s_nop 0
	global_load_lds_dwordx4 v[252:253], off
	s_waitcnt vmcnt(8)
	s_waitcnt lgkmcnt(0)
	s_setprio 1
	s_barrier
	v_mfma_f32_16x16x32_bf16 v[60:63], v[80:83], v[208:211], v[60:63]
	v_mfma_f32_16x16x32_bf16 v[56:59], v[88:91], v[208:211], v[56:59]
	v_mfma_f32_16x16x32_bf16 v[44:47], v[80:83], v[216:219], v[44:47]
	v_mfma_f32_16x16x32_bf16 v[40:43], v[88:91], v[216:219], v[40:43]
	v_mfma_f32_16x16x32_bf16 v[28:31], v[80:83], v[232:235], v[28:31]
	v_mfma_f32_16x16x32_bf16 v[24:27], v[88:91], v[232:235], v[24:27]
	v_mfma_f32_16x16x32_bf16 v[12:15], v[80:83], v[240:243], v[12:15]
	v_mfma_f32_16x16x32_bf16 v[8:11], v[88:91], v[240:243], v[8:11]
	v_mfma_f32_16x16x32_bf16 v[60:63], v[84:87], v[212:215], v[60:63]
	v_mfma_f32_16x16x32_bf16 v[56:59], v[92:95], v[212:215], v[56:59]
	v_mfma_f32_16x16x32_bf16 v[44:47], v[84:87], v[220:223], v[44:47]
	v_mfma_f32_16x16x32_bf16 v[40:43], v[92:95], v[220:223], v[40:43]
	v_mfma_f32_16x16x32_bf16 v[28:31], v[84:87], v[236:239], v[28:31]
	v_mfma_f32_16x16x32_bf16 v[24:27], v[92:95], v[236:239], v[24:27]
	v_mfma_f32_16x16x32_bf16 v[12:15], v[84:87], v[244:247], v[12:15]
	v_mfma_f32_16x16x32_bf16 v[8:11], v[92:95], v[244:247], v[8:11]
	v_mfma_f32_16x16x32_bf16 v[52:55], v[144:147], v[208:211], v[52:55]
	v_mfma_f32_16x16x32_bf16 v[48:51], v[152:155], v[208:211], v[48:51]
	v_mfma_f32_16x16x32_bf16 v[36:39], v[144:147], v[216:219], v[36:39]
	v_mfma_f32_16x16x32_bf16 v[32:35], v[152:155], v[216:219], v[32:35]
	v_mfma_f32_16x16x32_bf16 v[20:23], v[144:147], v[232:235], v[20:23]
	v_mfma_f32_16x16x32_bf16 v[16:19], v[152:155], v[232:235], v[16:19]
	v_mfma_f32_16x16x32_bf16 v[4:7], v[144:147], v[240:243], v[4:7]
	v_mfma_f32_16x16x32_bf16 v[0:3], v[152:155], v[240:243], v[0:3]
	v_mfma_f32_16x16x32_bf16 v[52:55], v[148:151], v[212:215], v[52:55]
	v_mfma_f32_16x16x32_bf16 v[48:51], v[156:159], v[212:215], v[48:51]
	v_mfma_f32_16x16x32_bf16 v[36:39], v[148:151], v[220:223], v[36:39]
	v_mfma_f32_16x16x32_bf16 v[32:35], v[156:159], v[220:223], v[32:35]
	v_mfma_f32_16x16x32_bf16 v[20:23], v[148:151], v[236:239], v[20:23]
	v_mfma_f32_16x16x32_bf16 v[16:19], v[156:159], v[236:239], v[16:19]
	v_mfma_f32_16x16x32_bf16 v[4:7], v[148:151], v[244:247], v[4:7]
	v_mfma_f32_16x16x32_bf16 v[0:3], v[156:159], v[244:247], v[0:3]
	s_barrier
; #define PG8_STAGE(bufoff, gbase, voff) do { _Pragma("unroll") for (int _i = 0; _i < 2; ++_i) \
;         __builtin_amdgcn_global_load_lds((const unsigned*)((const char*)(gbase) + (voff)[_i]), (PG8_LAS unsigned*)(lds + (bufoff) + ldsw + _i * 8192), 16, 0, 0); } while (0)
; #define PG8_LDA(dst, b, h) do { _Pragma("unroll") for (int m = 0; m < 4; ++m) _Pragma("unroll") for (int k = 0; k < 2; ++k) dst[m][k] = *(const PG8_LAS bf16x8*)(lds + PG8_SA(b, h) + aoff + m * 2048 + k * 1024); } while (0)
; #define PG8_LDB(dst, b, h) do { _Pragma("unroll") for (int n = 0; n < 2; ++n) _Pragma("unroll") for (int k = 0; k < 2; ++k) dst[n][k] = *(const PG8_LAS bf16x8*)(lds + PG8_SB(b, h) + boff + n * 2048 + k * 1024); } while (0)
; #define PG8_MMA(ai, bj, At, Bt) do { __builtin_amdgcn_s_setprio(1); _Pragma("unroll") for (int m = 0; m < 4; ++m) _Pragma("unroll") for (int n = 0; n < 2; ++n) _Pragma("unroll") for (int k = 0; k < 2; ++k) \
;         acc[ai][bj][m][n] = __builtin_amdgcn_mfma_f32_16x16x32_bf16(Bt[n][k], At[m][k], acc[ai][bj][m][n], 0, 0, 0); __builtin_amdgcn_s_setprio(0); } while (0)
; #define PG8_WAIT_V(n) asm volatile("s_waitcnt vmcnt(" #n ")" ::: "memory")
; #define PG8_WAIT_L(n) asm volatile("s_waitcnt lgkmcnt(" #n ")" ::: "memory")
; #define PG8_BAR __builtin_amdgcn_s_barrier()
; #define PG8_SCHED __builtin_amdgcn_sched_barrier(0)
; template <class Epi, class Sched, bool ALIGN_EPI = false, bool SP2 = false, bool DUAL = false>
; __device__ __forceinline__ void gemm_phase(PG8_LAS unsigned char* lds, const Gemm g, const Sched& S, const Epi& E) {
;     ...
;             PG8_LDB(B0, 1, 0); PG8_LDB(B1, 1, 1); PG8_SCHED; PG8_LDA(At, 1, 0); PG8_STAGE(PG8_SA(0, 1), a2 + hstep, voffA);
;             PG8_WAIT_V(8); PG8_WAIT_L(0); PG8_BAR; PG8_MMA(0, 0, At, B0); PG8_MMA(0, 1, At, B1); PG8_BAR; PG8_SCHED;
	s_setprio 0
	s_add_i32 s49, 0, 0x18000
	s_add_i32 s50, 0, 0x1c000
	v_add_u32_e32 v92, s49, v196
	v_add_u32_e32 v156, s50, v196
	ds_read_b128 v[80:83], v92
	ds_read_b128 v[84:87], v92 offset:1024
	ds_read_b128 v[88:91], v92 offset:2048
	ds_read_b128 v[92:95], v92 offset:3072
	ds_read_b128 v[144:147], v156
	ds_read_b128 v[148:151], v156 offset:1024
	ds_read_b128 v[152:155], v156 offset:2048
	ds_read_b128 v[156:159], v156 offset:3072
	s_add_u32 s16, s16, 0x80000
	s_addc_u32 s17, s17, 0
	s_mov_b32 m0, s21
	v_lshl_add_u64 v[228:229], s[16:17], 0, v[164:165]
	ds_read_b128 v[208:211], v203 offset:32768
	ds_read_b128 v[212:215], v203 offset:33792
	ds_read_b128 v[216:219], v203 offset:34816
	ds_read_b128 v[220:223], v203 offset:35840
	ds_read_b128 v[232:235], v203 offset:36864
	ds_read_b128 v[236:239], v203 offset:37888
	ds_read_b128 v[240:243], v203 offset:38912
	ds_read_b128 v[244:247], v203 offset:39936
	global_load_lds_dwordx4 v[228:229], off
	v_lshl_add_u64 v[228:229], s[16:17], 0, v[168:169]
	s_mov_b32 m0, s22
	s_nop 0
	global_load_lds_dwordx4 v[228:229], off
	s_waitcnt vmcnt(8)
	s_waitcnt lgkmcnt(0)
	s_setprio 1
	s_barrier
	v_mfma_f32_16x16x32_bf16 v[140:143], v[80:83], v[208:211], v[140:143]
	v_mfma_f32_16x16x32_bf16 v[132:135], v[88:91], v[208:211], v[132:135]
	v_mfma_f32_16x16x32_bf16 v[124:127], v[80:83], v[216:219], v[124:127]
	v_mfma_f32_16x16x32_bf16 v[120:123], v[88:91], v[216:219], v[120:123]
	v_mfma_f32_16x16x32_bf16 v[108:111], v[80:83], v[232:235], v[108:111]
	v_mfma_f32_16x16x32_bf16 v[104:107], v[88:91], v[232:235], v[104:107]
	v_mfma_f32_16x16x32_bf16 v[76:79], v[80:83], v[240:243], v[76:79]
	v_mfma_f32_16x16x32_bf16 v[72:75], v[88:91], v[240:243], v[72:75]
	v_mfma_f32_16x16x32_bf16 v[140:143], v[84:87], v[212:215], v[140:143]
	v_mfma_f32_16x16x32_bf16 v[132:135], v[92:95], v[212:215], v[132:135]
	v_mfma_f32_16x16x32_bf16 v[124:127], v[84:87], v[220:223], v[124:127]
	v_mfma_f32_16x16x32_bf16 v[120:123], v[92:95], v[220:223], v[120:123]
	v_mfma_f32_16x16x32_bf16 v[108:111], v[84:87], v[236:239], v[108:111]
	v_mfma_f32_16x16x32_bf16 v[104:107], v[92:95], v[236:239], v[104:107]
	v_mfma_f32_16x16x32_bf16 v[76:79], v[84:87], v[244:247], v[76:79]
	v_mfma_f32_16x16x32_bf16 v[72:75], v[92:95], v[244:247], v[72:75]
	v_mfma_f32_16x16x32_bf16 v[136:139], v[144:147], v[208:211], v[136:139]
	v_mfma_f32_16x16x32_bf16 v[128:131], v[152:155], v[208:211], v[128:131]
	v_mfma_f32_16x16x32_bf16 v[116:119], v[144:147], v[216:219], v[116:119]
	v_mfma_f32_16x16x32_bf16 v[112:115], v[152:155], v[216:219], v[112:115]
	v_mfma_f32_16x16x32_bf16 v[100:103], v[144:147], v[232:235], v[100:103]
	v_mfma_f32_16x16x32_bf16 v[96:99], v[152:155], v[232:235], v[96:99]
	v_mfma_f32_16x16x32_bf16 v[68:71], v[144:147], v[240:243], v[68:71]
	v_mfma_f32_16x16x32_bf16 v[64:67], v[152:155], v[240:243], v[64:67]
	v_mfma_f32_16x16x32_bf16 v[136:139], v[148:151], v[212:215], v[136:139]
	v_mfma_f32_16x16x32_bf16 v[128:131], v[156:159], v[212:215], v[128:131]
	v_mfma_f32_16x16x32_bf16 v[116:119], v[148:151], v[220:223], v[116:119]
	v_mfma_f32_16x16x32_bf16 v[112:115], v[156:159], v[220:223], v[112:115]
	v_mfma_f32_16x16x32_bf16 v[100:103], v[148:151], v[236:239], v[100:103]
	v_mfma_f32_16x16x32_bf16 v[96:99], v[156:159], v[236:239], v[96:99]
	v_mfma_f32_16x16x32_bf16 v[68:71], v[148:151], v[244:247], v[68:71]
	v_mfma_f32_16x16x32_bf16 v[64:67], v[156:159], v[244:247], v[64:67]
	s_barrier
; #define PG8_STAGE(bufoff, gbase, voff) do { _Pragma("unroll") for (int _i = 0; _i < 2; ++_i) \
;         __builtin_amdgcn_global_load_lds((const unsigned*)((const char*)(gbase) + (voff)[_i]), (PG8_LAS unsigned*)(lds + (bufoff) + ldsw + _i * 8192), 16, 0, 0); } while (0)
; #define PG8_LDA(dst, b, h) do { _Pragma("unroll") for (int m = 0; m < 4; ++m) _Pragma("unroll") for (int k = 0; k < 2; ++k) dst[m][k] = *(const PG8_LAS bf16x8*)(lds + PG8_SA(b, h) + aoff + m * 2048 + k * 1024); } while (0)
; #define PG8_MMA(ai, bj, At, Bt) do { __builtin_amdgcn_s_setprio(1); _Pragma("unroll") for (int m = 0; m < 4; ++m) _Pragma("unroll") for (int n = 0; n < 2; ++n) _Pragma("unroll") for (int k = 0; k < 2; ++k) \
;         acc[ai][bj][m][n] = __builtin_amdgcn_mfma_f32_16x16x32_bf16(Bt[n][k], At[m][k], acc[ai][bj][m][n], 0, 0, 0); __builtin_amdgcn_s_setprio(0); } while (0)
; #define PG8_WAIT_V(n) asm volatile("s_waitcnt vmcnt(" #n ")" ::: "memory")
; #define PG8_WAIT_L(n) asm volatile("s_waitcnt lgkmcnt(" #n ")" ::: "memory")
; #define PG8_BAR __builtin_amdgcn_s_barrier()
; #define PG8_SCHED __builtin_amdgcn_sched_barrier(0)
; template <class Epi, class Sched, bool ALIGN_EPI = false, bool SP2 = false, bool DUAL = false>
; __device__ __forceinline__ void gemm_phase(PG8_LAS unsigned char* lds, const Gemm g, const Sched& S, const Epi& E) {
;     ...
;             PG8_LDA(At, 1, 1); PG8_STAGE(PG8_SB(1, 0), b3, voffB); PG8_STAGE(PG8_SB(1, 1), b3 + hstep, voffB); PG8_STAGE(PG8_SA(1, 0), a3, voffA);
;             PG8_WAIT_V(8); PG8_WAIT_L(0); PG8_BAR; PG8_MMA(1, 0, At, B0); PG8_MMA(1, 1, At, B1); PG8_BAR; PG8_SCHED;
;     ...
;         if constexpr (ALIGN_EPI) { if (wr == 0) PG8_BAR; }
	s_setprio 0
	s_add_i32 s16, s49, s18
	v_lshl_add_u64 v[192:193], v[192:193], 0, s[76:77]
	s_mov_b32 m0, s16
	ds_read_b128 v[208:211], v203 offset:49152
	ds_read_b128 v[212:215], v203 offset:50176
	ds_read_b128 v[216:219], v203 offset:51200
	ds_read_b128 v[220:223], v203 offset:52224
	ds_read_b128 v[232:235], v203 offset:53248
	ds_read_b128 v[236:239], v203 offset:54272
	ds_read_b128 v[240:243], v203 offset:55296
	ds_read_b128 v[244:247], v203 offset:56320
	global_load_lds_dwordx4 v[192:193], off
	s_add_i32 m0, s16, 0x2000
	s_add_u32 s14, s14, 0x80080
	v_lshl_add_u64 v[192:193], v[248:249], 0, s[76:77]
	s_addc_u32 s15, s15, 0
	s_add_i32 s16, s50, s18
	global_load_lds_dwordx4 v[192:193], off
	v_lshl_add_u64 v[192:193], s[14:15], 0, v[166:167]
	s_mov_b32 m0, s16
	s_nop 0
	global_load_lds_dwordx4 v[192:193], off
	v_lshl_add_u64 v[192:193], s[14:15], 0, v[170:171]
	s_add_i32 m0, s16, 0x2000
	s_nop 0
	global_load_lds_dwordx4 v[192:193], off
	v_lshl_add_u64 v[192:193], v[250:251], 0, s[76:77]
	s_mov_b32 m0, s27
	s_nop 0
	global_load_lds_dwordx4 v[192:193], off
	v_lshl_add_u64 v[192:193], v[252:253], 0, s[76:77]
	s_mov_b32 m0, s28
	s_nop 0
	global_load_lds_dwordx4 v[192:193], off
	s_waitcnt vmcnt(8)
	s_waitcnt lgkmcnt(0)
	s_setprio 1
	s_barrier
	v_mfma_f32_16x16x32_bf16 v[60:63], v[80:83], v[208:211], v[60:63]
	v_mfma_f32_16x16x32_bf16 v[56:59], v[88:91], v[208:211], v[56:59]
	v_mfma_f32_16x16x32_bf16 v[44:47], v[80:83], v[216:219], v[44:47]
	v_mfma_f32_16x16x32_bf16 v[40:43], v[88:91], v[216:219], v[40:43]
	v_mfma_f32_16x16x32_bf16 v[28:31], v[80:83], v[232:235], v[28:31]
	v_mfma_f32_16x16x32_bf16 v[24:27], v[88:91], v[232:235], v[24:27]
	v_mfma_f32_16x16x32_bf16 v[12:15], v[80:83], v[240:243], v[12:15]
	v_mfma_f32_16x16x32_bf16 v[8:11], v[88:91], v[240:243], v[8:11]
	v_mfma_f32_16x16x32_bf16 v[60:63], v[84:87], v[212:215], v[60:63]
	v_mfma_f32_16x16x32_bf16 v[56:59], v[92:95], v[212:215], v[56:59]
	v_mfma_f32_16x16x32_bf16 v[44:47], v[84:87], v[220:223], v[44:47]
	v_mfma_f32_16x16x32_bf16 v[40:43], v[92:95], v[220:223], v[40:43]
	v_mfma_f32_16x16x32_bf16 v[28:31], v[84:87], v[236:239], v[28:31]
	v_mfma_f32_16x16x32_bf16 v[24:27], v[92:95], v[236:239], v[24:27]
	v_mfma_f32_16x16x32_bf16 v[12:15], v[84:87], v[244:247], v[12:15]
	v_mfma_f32_16x16x32_bf16 v[8:11], v[92:95], v[244:247], v[8:11]
	v_mfma_f32_16x16x32_bf16 v[52:55], v[144:147], v[208:211], v[52:55]
	v_mfma_f32_16x16x32_bf16 v[48:51], v[152:155], v[208:211], v[48:51]
	v_mfma_f32_16x16x32_bf16 v[36:39], v[144:147], v[216:219], v[36:39]
	v_mfma_f32_16x16x32_bf16 v[32:35], v[152:155], v[216:219], v[32:35]
	v_mfma_f32_16x16x32_bf16 v[20:23], v[144:147], v[232:235], v[20:23]
	v_mfma_f32_16x16x32_bf16 v[16:19], v[152:155], v[232:235], v[16:19]
	v_mfma_f32_16x16x32_bf16 v[4:7], v[144:147], v[240:243], v[4:7]
	v_mfma_f32_16x16x32_bf16 v[0:3], v[152:155], v[240:243], v[0:3]
	v_mfma_f32_16x16x32_bf16 v[52:55], v[148:151], v[212:215], v[52:55]
	v_mfma_f32_16x16x32_bf16 v[48:51], v[156:159], v[212:215], v[48:51]
	v_mfma_f32_16x16x32_bf16 v[36:39], v[148:151], v[220:223], v[36:39]
	v_mfma_f32_16x16x32_bf16 v[32:35], v[156:159], v[220:223], v[32:35]
	v_mfma_f32_16x16x32_bf16 v[20:23], v[148:151], v[236:239], v[20:23]
	v_mfma_f32_16x16x32_bf16 v[16:19], v[156:159], v[236:239], v[16:19]
	v_mfma_f32_16x16x32_bf16 v[4:7], v[148:151], v[244:247], v[4:7]
	v_mfma_f32_16x16x32_bf16 v[0:3], v[156:159], v[244:247], v[0:3]
	s_barrier
	s_setprio 0
	s_add_i32 s48, s48, 2
	s_add_u32 s10, s10, 0x100
	s_addc_u32 s11, s11, 0
	s_add_u32 s46, s46, 0x100
	s_addc_u32 s47, s47, 0
	s_cmp_gt_u32 s48, 29
	s_cbranch_scc0 .LBB0_252
	s_and_b64 vcc, exec, s[38:39]
	s_cbranch_vccz .LBB0_255
	s_barrier

; #define PG8_STAGE(bufoff, gbase, voff) do { _Pragma("unroll") for (int _i = 0; _i < 2; ++_i) \
;         __builtin_amdgcn_global_load_lds((const unsigned*)((const char*)(gbase) + (voff)[_i]), (PG8_LAS unsigned*)(lds + (bufoff) + ldsw + _i * 8192), 16, 0, 0); } while (0)
; #define PG8_LDA(dst, b, h) do { _Pragma("unroll") for (int m = 0; m < 4; ++m) _Pragma("unroll") for (int k = 0; k < 2; ++k) dst[m][k] = *(const PG8_LAS bf16x8*)(lds + PG8_SA(b, h) + aoff + m * 2048 + k * 1024); } while (0)
; #define PG8_LDB(dst, b, h) do { _Pragma("unroll") for (int n = 0; n < 2; ++n) _Pragma("unroll") for (int k = 0; k < 2; ++k) dst[n][k] = *(const PG8_LAS bf16x8*)(lds + PG8_SB(b, h) + boff + n * 2048 + k * 1024); } while (0)
; #define PG8_MMA(ai, bj, At, Bt) do { __builtin_amdgcn_s_setprio(1); _Pragma("unroll") for (int m = 0; m < 4; ++m) _Pragma("unroll") for (int n = 0; n < 2; ++n) _Pragma("unroll") for (int k = 0; k < 2; ++k) \
;         acc[ai][bj][m][n] = __builtin_amdgcn_mfma_f32_16x16x32_bf16(Bt[n][k], At[m][k], acc[ai][bj][m][n], 0, 0, 0); __builtin_amdgcn_s_setprio(0); } while (0)
; #define PG8_WAIT_V(n) asm volatile("s_waitcnt vmcnt(" #n ")" ::: "memory")
; #define PG8_WAIT_L(n) asm volatile("s_waitcnt lgkmcnt(" #n ")" ::: "memory")
; #define PG8_BAR __builtin_amdgcn_s_barrier()
; #define PG8_SCHED __builtin_amdgcn_sched_barrier(0)
; template <class Epi, class Sched, bool ALIGN_EPI = false, bool SP2 = false, bool DUAL = false>
; __device__ __forceinline__ void gemm_phase(PG8_LAS unsigned char* lds, const Gemm g, const Sched& S, const Epi& E) {
;     ...
;             PG8_LDB(B0, 0, 0); PG8_LDB(B1, 0, 1); PG8_SCHED; PG8_LDA(At, 0, 0); PG8_STAGE(PG8_SA(1, 1), a1 + hstep, voffA);
;             PG8_WAIT_V(8); PG8_WAIT_L(0); PG8_BAR; PG8_MMA(0, 0, At, B0); PG8_MMA(0, 1, At, B1); PG8_BAR; PG8_SCHED;
;             PG8_LDA(At, 0, 1); PG8_STAGE(PG8_SB(0, 0), b2, voffB); PG8_STAGE(PG8_SB(0, 1), b2 + hstep, voffB); PG8_STAGE(PG8_SA(0, 0), a2, voffA);
;             PG8_WAIT_V(8); PG8_WAIT_L(0); PG8_BAR; PG8_MMA(1, 0, At, B0); PG8_MMA(1, 1, At, B1); PG8_BAR; PG8_SCHED;
.LBB0_805:
	v_add_u32_e32 v1, s44, v235
	ds_read_b128 v[132:135], v1
	ds_read_b128 v[136:139], v1 offset:1024
	ds_read_b128 v[140:143], v1 offset:2048
	ds_read_b128 v[144:147], v1 offset:3072
	v_add_u32_e32 v1, s45, v235
	ds_read_b128 v[148:151], v1
	ds_read_b128 v[152:155], v1 offset:1024
	ds_read_b128 v[156:159], v1 offset:2048
	ds_read_b128 v[160:163], v1 offset:3072
	s_add_u32 s16, s14, 0xfff80080
	s_addc_u32 s17, s15, -1
	s_cmp_eq_u32 s75, 28
	s_cselect_b32 s19, s50, s17
	s_cselect_b32 s18, s51, s16
	s_cselect_b32 s17, s65, s73
	s_cselect_b32 s16, s67, s72
	v_lshl_add_u64 v[2:3], s[14:15], 0, v[192:193]
	s_add_i32 m0, s28, 0xc000
	ds_read_b128 v[164:167], v237
	ds_read_b128 v[168:171], v237 offset:1024
	ds_read_b128 v[172:175], v237 offset:2048
	ds_read_b128 v[176:179], v237 offset:3072
	ds_read_b128 v[180:183], v237 offset:4096
	ds_read_b128 v[202:205], v237 offset:5120
	ds_read_b128 v[206:209], v237 offset:6144
	ds_read_b128 v[210:213], v237 offset:7168
	global_load_lds_dwordx4 v[2:3], off
	v_lshl_add_u64 v[2:3], s[14:15], 0, v[194:195]
	s_add_i32 m0, s28, 0xe000
	s_nop 0
	global_load_lds_dwordx4 v[2:3], off
	s_waitcnt vmcnt(8)
	s_waitcnt lgkmcnt(0)
	s_setprio 1
	s_barrier
	v_mfma_f32_16x16x32_bf16 v[128:131], v[132:135], v[164:167], v[128:131]
	v_mfma_f32_16x16x32_bf16 v[124:127], v[140:143], v[164:167], v[124:127]
	v_mfma_f32_16x16x32_bf16 v[120:123], v[132:135], v[172:175], v[120:123]
	v_mfma_f32_16x16x32_bf16 v[116:119], v[140:143], v[172:175], v[116:119]
	v_mfma_f32_16x16x32_bf16 v[112:115], v[132:135], v[180:183], v[112:115]
	v_mfma_f32_16x16x32_bf16 v[108:111], v[140:143], v[180:183], v[108:111]
	v_mfma_f32_16x16x32_bf16 v[104:107], v[132:135], v[206:209], v[104:107]
	v_mfma_f32_16x16x32_bf16 v[100:103], v[140:143], v[206:209], v[100:103]
	v_mfma_f32_16x16x32_bf16 v[128:131], v[136:139], v[168:171], v[128:131]
	v_mfma_f32_16x16x32_bf16 v[124:127], v[144:147], v[168:171], v[124:127]
	v_mfma_f32_16x16x32_bf16 v[120:123], v[136:139], v[176:179], v[120:123]
	v_mfma_f32_16x16x32_bf16 v[116:119], v[144:147], v[176:179], v[116:119]
	v_mfma_f32_16x16x32_bf16 v[112:115], v[136:139], v[202:205], v[112:115]
	v_mfma_f32_16x16x32_bf16 v[108:111], v[144:147], v[202:205], v[108:111]
	v_mfma_f32_16x16x32_bf16 v[104:107], v[136:139], v[210:213], v[104:107]
	v_mfma_f32_16x16x32_bf16 v[100:103], v[144:147], v[210:213], v[100:103]
	v_mfma_f32_16x16x32_bf16 v[96:99], v[148:151], v[164:167], v[96:99]
	v_mfma_f32_16x16x32_bf16 v[92:95], v[156:159], v[164:167], v[92:95]
	v_mfma_f32_16x16x32_bf16 v[88:91], v[148:151], v[172:175], v[88:91]
	v_mfma_f32_16x16x32_bf16 v[84:87], v[156:159], v[172:175], v[84:87]
	v_mfma_f32_16x16x32_bf16 v[80:83], v[148:151], v[180:183], v[80:83]
	v_mfma_f32_16x16x32_bf16 v[76:79], v[156:159], v[180:183], v[76:79]
	v_mfma_f32_16x16x32_bf16 v[72:75], v[148:151], v[206:209], v[72:75]
	v_mfma_f32_16x16x32_bf16 v[68:71], v[156:159], v[206:209], v[68:71]
	v_mfma_f32_16x16x32_bf16 v[96:99], v[152:155], v[168:171], v[96:99]
	v_mfma_f32_16x16x32_bf16 v[92:95], v[160:163], v[168:171], v[92:95]
	v_mfma_f32_16x16x32_bf16 v[88:91], v[152:155], v[176:179], v[88:91]
	v_mfma_f32_16x16x32_bf16 v[84:87], v[160:163], v[176:179], v[84:87]
	v_mfma_f32_16x16x32_bf16 v[80:83], v[152:155], v[202:205], v[80:83]
	v_mfma_f32_16x16x32_bf16 v[76:79], v[160:163], v[202:205], v[76:79]
	v_mfma_f32_16x16x32_bf16 v[72:75], v[152:155], v[210:213], v[72:75]
	v_mfma_f32_16x16x32_bf16 v[68:71], v[160:163], v[210:213], v[68:71]
	s_barrier
	s_setprio 0
	s_add_i32 s76, s44, s27
	v_lshl_add_u64 v[214:215], s[16:17], 0, v[186:187]
	s_mov_b32 m0, s76
	ds_read_b128 v[164:167], v237 offset:16384
	ds_read_b128 v[168:171], v237 offset:17408
	ds_read_b128 v[172:175], v237 offset:18432
	ds_read_b128 v[176:179], v237 offset:19456
	ds_read_b128 v[180:183], v237 offset:20480
	ds_read_b128 v[202:205], v237 offset:21504
	ds_read_b128 v[206:209], v237 offset:22528
	ds_read_b128 v[210:213], v237 offset:23552
	global_load_lds_dwordx4 v[214:215], off
	s_add_i32 m0, s76, 0x2000
	s_add_u32 s76, s16, 0x80000
	v_lshl_add_u64 v[216:217], s[16:17], 0, v[190:191]
	s_addc_u32 s77, s17, 0
	s_add_i32 s78, s45, s27
	global_load_lds_dwordx4 v[216:217], off
	v_lshl_add_u64 v[2:3], s[76:77], 0, v[186:187]
	s_mov_b32 m0, s78
	v_lshl_add_u64 v[218:219], s[18:19], 0, v[184:185]
	global_load_lds_dwordx4 v[2:3], off
	v_lshl_add_u64 v[2:3], s[76:77], 0, v[190:191]
	s_add_i32 m0, s78, 0x2000
	v_lshl_add_u64 v[220:221], s[18:19], 0, v[188:189]
	global_load_lds_dwordx4 v[2:3], off
	s_mov_b32 m0, s28
	s_nop 0
	global_load_lds_dwordx4 v[218:219], off
	s_mov_b32 m0, s29
	s_nop 0
	global_load_lds_dwordx4 v[220:221], off
	s_waitcnt vmcnt(8)
	s_waitcnt lgkmcnt(0)
	s_setprio 1
	s_barrier
; #define PG8_STAGE(bufoff, gbase, voff) do { _Pragma("unroll") for (int _i = 0; _i < 2; ++_i) \
;         __builtin_amdgcn_global_load_lds((const unsigned*)((const char*)(gbase) + (voff)[_i]), (PG8_LAS unsigned*)(lds + (bufoff) + ldsw + _i * 8192), 16, 0, 0); } while (0)
; #define PG8_LDA(dst, b, h) do { _Pragma("unroll") for (int m = 0; m < 4; ++m) _Pragma("unroll") for (int k = 0; k < 2; ++k) dst[m][k] = *(const PG8_LAS bf16x8*)(lds + PG8_SA(b, h) + aoff + m * 2048 + k * 1024); } while (0)
; #define PG8_LDB(dst, b, h) do { _Pragma("unroll") for (int n = 0; n < 2; ++n) _Pragma("unroll") for (int k = 0; k < 2; ++k) dst[n][k] = *(const PG8_LAS bf16x8*)(lds + PG8_SB(b, h) + boff + n * 2048 + k * 1024); } while (0)
; #define PG8_MMA(ai, bj, At, Bt) do { __builtin_amdgcn_s_setprio(1); _Pragma("unroll") for (int m = 0; m < 4; ++m) _Pragma("unroll") for (int n = 0; n < 2; ++n) _Pragma("unroll") for (int k = 0; k < 2; ++k) \
;         acc[ai][bj][m][n] = __builtin_amdgcn_mfma_f32_16x16x32_bf16(Bt[n][k], At[m][k], acc[ai][bj][m][n], 0, 0, 0); __builtin_amdgcn_s_setprio(0); } while (0)
; #define PG8_WAIT_V(n) asm volatile("s_waitcnt vmcnt(" #n ")" ::: "memory")
; #define PG8_WAIT_L(n) asm volatile("s_waitcnt lgkmcnt(" #n ")" ::: "memory")
; #define PG8_BAR __builtin_amdgcn_s_barrier()
; #define PG8_SCHED __builtin_amdgcn_sched_barrier(0)
; template <class Epi, class Sched, bool ALIGN_EPI = false, bool SP2 = false, bool DUAL = false>
; __device__ __forceinline__ void gemm_phase(PG8_LAS unsigned char* lds, const Gemm g, const Sched& S, const Epi& E) {
;     ...
;             PG8_WAIT_V(8); PG8_WAIT_L(0); PG8_BAR; PG8_MMA(1, 0, At, B0); PG8_MMA(1, 1, At, B1); PG8_BAR; PG8_SCHED;
;             PG8_LDB(B0, 1, 0); PG8_LDB(B1, 1, 1); PG8_SCHED; PG8_LDA(At, 1, 0); PG8_STAGE(PG8_SA(0, 1), a2 + hstep, voffA);
;             PG8_WAIT_V(8); PG8_WAIT_L(0); PG8_BAR; PG8_MMA(0, 0, At, B0); PG8_MMA(0, 1, At, B1); PG8_BAR; PG8_SCHED;
	v_mfma_f32_16x16x32_bf16 v[64:67], v[132:135], v[164:167], v[64:67]
	v_mfma_f32_16x16x32_bf16 v[60:63], v[140:143], v[164:167], v[60:63]
	v_mfma_f32_16x16x32_bf16 v[56:59], v[132:135], v[172:175], v[56:59]
	v_mfma_f32_16x16x32_bf16 v[52:55], v[140:143], v[172:175], v[52:55]
	v_mfma_f32_16x16x32_bf16 v[48:51], v[132:135], v[180:183], v[48:51]
	v_mfma_f32_16x16x32_bf16 v[44:47], v[140:143], v[180:183], v[44:47]
	v_mfma_f32_16x16x32_bf16 v[40:43], v[132:135], v[206:209], v[40:43]
	v_mfma_f32_16x16x32_bf16 v[36:39], v[140:143], v[206:209], v[36:39]
	v_mfma_f32_16x16x32_bf16 v[64:67], v[136:139], v[168:171], v[64:67]
	v_mfma_f32_16x16x32_bf16 v[60:63], v[144:147], v[168:171], v[60:63]
	v_mfma_f32_16x16x32_bf16 v[56:59], v[136:139], v[176:179], v[56:59]
	v_mfma_f32_16x16x32_bf16 v[52:55], v[144:147], v[176:179], v[52:55]
	v_mfma_f32_16x16x32_bf16 v[48:51], v[136:139], v[202:205], v[48:51]
	v_mfma_f32_16x16x32_bf16 v[44:47], v[144:147], v[202:205], v[44:47]
	v_mfma_f32_16x16x32_bf16 v[40:43], v[136:139], v[210:213], v[40:43]
	v_mfma_f32_16x16x32_bf16 v[36:39], v[144:147], v[210:213], v[36:39]
	v_mfma_f32_16x16x32_bf16 v[32:35], v[148:151], v[164:167], v[32:35]
	v_mfma_f32_16x16x32_bf16 v[28:31], v[156:159], v[164:167], v[28:31]
	v_mfma_f32_16x16x32_bf16 v[24:27], v[148:151], v[172:175], v[24:27]
	v_mfma_f32_16x16x32_bf16 v[20:23], v[156:159], v[172:175], v[20:23]
	v_mfma_f32_16x16x32_bf16 v[16:19], v[148:151], v[180:183], v[16:19]
	v_mfma_f32_16x16x32_bf16 v[12:15], v[156:159], v[180:183], v[12:15]
	v_mfma_f32_16x16x32_bf16 v[8:11], v[148:151], v[206:209], v[8:11]
	v_mfma_f32_16x16x32_bf16 v[2:5], v[156:159], v[206:209], v[4:7]
	v_mfma_f32_16x16x32_bf16 v[32:35], v[152:155], v[168:171], v[32:35]
	v_mfma_f32_16x16x32_bf16 v[28:31], v[160:163], v[168:171], v[28:31]
	v_mfma_f32_16x16x32_bf16 v[24:27], v[152:155], v[176:179], v[24:27]
	v_mfma_f32_16x16x32_bf16 v[20:23], v[160:163], v[176:179], v[20:23]
	v_mfma_f32_16x16x32_bf16 v[16:19], v[152:155], v[202:205], v[16:19]
	v_mfma_f32_16x16x32_bf16 v[12:15], v[160:163], v[202:205], v[12:15]
	v_mfma_f32_16x16x32_bf16 v[8:11], v[152:155], v[210:213], v[8:11]
	v_mfma_f32_16x16x32_bf16 v[2:5], v[160:163], v[210:213], v[2:5]
	s_barrier
	s_setprio 0
	s_add_i32 s76, 0, 0x18000
	v_add_u32_e32 v1, s76, v235
	s_add_i32 s77, 0, 0x1c000
	ds_read_b128 v[132:135], v1
	ds_read_b128 v[136:139], v1 offset:1024
	ds_read_b128 v[140:143], v1 offset:2048
	ds_read_b128 v[144:147], v1 offset:3072
	v_add_u32_e32 v1, s77, v235
	ds_read_b128 v[148:151], v1
	ds_read_b128 v[152:155], v1 offset:1024
	ds_read_b128 v[156:159], v1 offset:2048
	ds_read_b128 v[160:163], v1 offset:3072
	s_add_u32 s18, s18, 0x80000
	s_addc_u32 s19, s19, 0
	s_mov_b32 m0, s34
	v_lshl_add_u64 v[6:7], s[18:19], 0, v[184:185]
	ds_read_b128 v[164:167], v237 offset:32768
	ds_read_b128 v[168:171], v237 offset:33792
	ds_read_b128 v[172:175], v237 offset:34816
	ds_read_b128 v[176:179], v237 offset:35840
	ds_read_b128 v[180:183], v237 offset:36864
	ds_read_b128 v[202:205], v237 offset:37888
	ds_read_b128 v[206:209], v237 offset:38912
	ds_read_b128 v[210:213], v237 offset:39936
	global_load_lds_dwordx4 v[6:7], off
	v_lshl_add_u64 v[6:7], s[18:19], 0, v[188:189]
	s_mov_b32 m0, s35
	s_nop 0
	global_load_lds_dwordx4 v[6:7], off
	s_waitcnt vmcnt(8)
	s_waitcnt lgkmcnt(0)
	s_setprio 1
	s_barrier
	v_mfma_f32_16x16x32_bf16 v[128:131], v[132:135], v[164:167], v[128:131]
	v_mfma_f32_16x16x32_bf16 v[124:127], v[140:143], v[164:167], v[124:127]
	v_mfma_f32_16x16x32_bf16 v[120:123], v[132:135], v[172:175], v[120:123]
	v_mfma_f32_16x16x32_bf16 v[116:119], v[140:143], v[172:175], v[116:119]
	v_mfma_f32_16x16x32_bf16 v[112:115], v[132:135], v[180:183], v[112:115]
	v_mfma_f32_16x16x32_bf16 v[108:111], v[140:143], v[180:183], v[108:111]
	v_mfma_f32_16x16x32_bf16 v[104:107], v[132:135], v[206:209], v[104:107]
	v_mfma_f32_16x16x32_bf16 v[100:103], v[140:143], v[206:209], v[100:103]
	v_mfma_f32_16x16x32_bf16 v[128:131], v[136:139], v[168:171], v[128:131]
	v_mfma_f32_16x16x32_bf16 v[124:127], v[144:147], v[168:171], v[124:127]
	v_mfma_f32_16x16x32_bf16 v[120:123], v[136:139], v[176:179], v[120:123]
	v_mfma_f32_16x16x32_bf16 v[116:119], v[144:147], v[176:179], v[116:119]
	v_mfma_f32_16x16x32_bf16 v[112:115], v[136:139], v[202:205], v[112:115]
	v_mfma_f32_16x16x32_bf16 v[108:111], v[144:147], v[202:205], v[108:111]
	v_mfma_f32_16x16x32_bf16 v[104:107], v[136:139], v[210:213], v[104:107]
	v_mfma_f32_16x16x32_bf16 v[100:103], v[144:147], v[210:213], v[100:103]
	v_mfma_f32_16x16x32_bf16 v[96:99], v[148:151], v[164:167], v[96:99]
	v_mfma_f32_16x16x32_bf16 v[92:95], v[156:159], v[164:167], v[92:95]
	v_mfma_f32_16x16x32_bf16 v[88:91], v[148:151], v[172:175], v[88:91]
	v_mfma_f32_16x16x32_bf16 v[84:87], v[156:159], v[172:175], v[84:87]
	v_mfma_f32_16x16x32_bf16 v[80:83], v[148:151], v[180:183], v[80:83]
	v_mfma_f32_16x16x32_bf16 v[76:79], v[156:159], v[180:183], v[76:79]
	v_mfma_f32_16x16x32_bf16 v[72:75], v[148:151], v[206:209], v[72:75]
	v_mfma_f32_16x16x32_bf16 v[68:71], v[156:159], v[206:209], v[68:71]
	v_mfma_f32_16x16x32_bf16 v[96:99], v[152:155], v[168:171], v[96:99]
	v_mfma_f32_16x16x32_bf16 v[92:95], v[160:163], v[168:171], v[92:95]
	v_mfma_f32_16x16x32_bf16 v[88:91], v[152:155], v[176:179], v[88:91]
	v_mfma_f32_16x16x32_bf16 v[84:87], v[160:163], v[176:179], v[84:87]
	v_mfma_f32_16x16x32_bf16 v[80:83], v[152:155], v[202:205], v[80:83]
	v_mfma_f32_16x16x32_bf16 v[76:79], v[160:163], v[202:205], v[76:79]
	v_mfma_f32_16x16x32_bf16 v[72:75], v[152:155], v[210:213], v[72:75]
	v_mfma_f32_16x16x32_bf16 v[68:71], v[160:163], v[210:213], v[68:71]
	s_barrier
; #define PG8_STAGE(bufoff, gbase, voff) do { _Pragma("unroll") for (int _i = 0; _i < 2; ++_i) \
;         __builtin_amdgcn_global_load_lds((const unsigned*)((const char*)(gbase) + (voff)[_i]), (PG8_LAS unsigned*)(lds + (bufoff) + ldsw + _i * 8192), 16, 0, 0); } while (0)
; #define PG8_LDA(dst, b, h) do { _Pragma("unroll") for (int m = 0; m < 4; ++m) _Pragma("unroll") for (int k = 0; k < 2; ++k) dst[m][k] = *(const PG8_LAS bf16x8*)(lds + PG8_SA(b, h) + aoff + m * 2048 + k * 1024); } while (0)
; #define PG8_MMA(ai, bj, At, Bt) do { __builtin_amdgcn_s_setprio(1); _Pragma("unroll") for (int m = 0; m < 4; ++m) _Pragma("unroll") for (int n = 0; n < 2; ++n) _Pragma("unroll") for (int k = 0; k < 2; ++k) \
;         acc[ai][bj][m][n] = __builtin_amdgcn_mfma_f32_16x16x32_bf16(Bt[n][k], At[m][k], acc[ai][bj][m][n], 0, 0, 0); __builtin_amdgcn_s_setprio(0); } while (0)
; #define PG8_WAIT_V(n) asm volatile("s_waitcnt vmcnt(" #n ")" ::: "memory")
; #define PG8_WAIT_L(n) asm volatile("s_waitcnt lgkmcnt(" #n ")" ::: "memory")
; #define PG8_BAR __builtin_amdgcn_s_barrier()
; #define PG8_SCHED __builtin_amdgcn_sched_barrier(0)
; template <class Epi, class Sched, bool ALIGN_EPI = false, bool SP2 = false, bool DUAL = false>
; __device__ __forceinline__ void gemm_phase(PG8_LAS unsigned char* lds, const Gemm g, const Sched& S, const Epi& E) {
;     ...
;             PG8_LDA(At, 1, 1); PG8_STAGE(PG8_SB(1, 0), b3, voffB); PG8_STAGE(PG8_SB(1, 1), b3 + hstep, voffB); PG8_STAGE(PG8_SA(1, 0), a3, voffA);
;             PG8_WAIT_V(8); PG8_WAIT_L(0); PG8_BAR; PG8_MMA(1, 0, At, B0); PG8_MMA(1, 1, At, B1); PG8_BAR; PG8_SCHED;
;     ...
;         if constexpr (ALIGN_EPI) { if (wr == 0) PG8_BAR; }
	s_setprio 0
	s_add_i32 s18, s76, s27
	v_lshl_add_u64 v[6:7], v[214:215], 0, s[36:37]
	s_mov_b32 m0, s18
	ds_read_b128 v[164:167], v237 offset:49152
	ds_read_b128 v[168:171], v237 offset:50176
	ds_read_b128 v[172:175], v237 offset:51200
	ds_read_b128 v[176:179], v237 offset:52224
	ds_read_b128 v[180:183], v237 offset:53248
	ds_read_b128 v[202:205], v237 offset:54272
	ds_read_b128 v[206:209], v237 offset:55296
	ds_read_b128 v[210:213], v237 offset:56320
	global_load_lds_dwordx4 v[6:7], off
	s_add_i32 m0, s18, 0x2000
	s_add_u32 s16, s16, 0x80080
	v_lshl_add_u64 v[6:7], v[216:217], 0, s[36:37]
	s_addc_u32 s17, s17, 0
	s_add_i32 s18, s77, s27
	global_load_lds_dwordx4 v[6:7], off
	v_lshl_add_u64 v[6:7], s[16:17], 0, v[186:187]
	s_mov_b32 m0, s18
	s_nop 0
	global_load_lds_dwordx4 v[6:7], off
	v_lshl_add_u64 v[6:7], s[16:17], 0, v[190:191]
	s_add_i32 m0, s18, 0x2000
	s_nop 0
	global_load_lds_dwordx4 v[6:7], off
	v_lshl_add_u64 v[6:7], v[218:219], 0, s[36:37]
	s_mov_b32 m0, s42
	s_nop 0
	global_load_lds_dwordx4 v[6:7], off
	v_lshl_add_u64 v[6:7], v[220:221], 0, s[36:37]
	s_mov_b32 m0, s43
	s_nop 0
	global_load_lds_dwordx4 v[6:7], off
	s_waitcnt vmcnt(8)
	s_waitcnt lgkmcnt(0)
	s_setprio 1
	s_barrier
	v_mfma_f32_16x16x32_bf16 v[64:67], v[132:135], v[164:167], v[64:67]
	v_mfma_f32_16x16x32_bf16 v[60:63], v[140:143], v[164:167], v[60:63]
	v_mfma_f32_16x16x32_bf16 v[56:59], v[132:135], v[172:175], v[56:59]
	v_mfma_f32_16x16x32_bf16 v[52:55], v[140:143], v[172:175], v[52:55]
	v_mfma_f32_16x16x32_bf16 v[48:51], v[132:135], v[180:183], v[48:51]
	v_mfma_f32_16x16x32_bf16 v[44:47], v[140:143], v[180:183], v[44:47]
	v_mfma_f32_16x16x32_bf16 v[40:43], v[132:135], v[206:209], v[40:43]
	v_mfma_f32_16x16x32_bf16 v[36:39], v[140:143], v[206:209], v[36:39]
	v_mfma_f32_16x16x32_bf16 v[64:67], v[136:139], v[168:171], v[64:67]
	v_mfma_f32_16x16x32_bf16 v[60:63], v[144:147], v[168:171], v[60:63]
	v_mfma_f32_16x16x32_bf16 v[56:59], v[136:139], v[176:179], v[56:59]
	v_mfma_f32_16x16x32_bf16 v[52:55], v[144:147], v[176:179], v[52:55]
	v_mfma_f32_16x16x32_bf16 v[48:51], v[136:139], v[202:205], v[48:51]
	v_mfma_f32_16x16x32_bf16 v[44:47], v[144:147], v[202:205], v[44:47]
	v_mfma_f32_16x16x32_bf16 v[40:43], v[136:139], v[210:213], v[40:43]
	v_mfma_f32_16x16x32_bf16 v[36:39], v[144:147], v[210:213], v[36:39]
	v_mfma_f32_16x16x32_bf16 v[32:35], v[148:151], v[164:167], v[32:35]
	v_mfma_f32_16x16x32_bf16 v[28:31], v[156:159], v[164:167], v[28:31]
	v_mfma_f32_16x16x32_bf16 v[24:27], v[148:151], v[172:175], v[24:27]
	v_mfma_f32_16x16x32_bf16 v[20:23], v[156:159], v[172:175], v[20:23]
	v_mfma_f32_16x16x32_bf16 v[16:19], v[148:151], v[180:183], v[16:19]
	v_mfma_f32_16x16x32_bf16 v[12:15], v[156:159], v[180:183], v[12:15]
	v_mfma_f32_16x16x32_bf16 v[6:9], v[148:151], v[206:209], v[8:11]
	v_mfma_f32_16x16x32_bf16 v[2:5], v[156:159], v[206:209], v[2:5]
	v_mfma_f32_16x16x32_bf16 v[32:35], v[152:155], v[168:171], v[32:35]
	v_mfma_f32_16x16x32_bf16 v[28:31], v[160:163], v[168:171], v[28:31]
	v_mfma_f32_16x16x32_bf16 v[24:27], v[152:155], v[176:179], v[24:27]
	v_mfma_f32_16x16x32_bf16 v[20:23], v[160:163], v[176:179], v[20:23]
	v_mfma_f32_16x16x32_bf16 v[16:19], v[152:155], v[202:205], v[16:19]
	v_mfma_f32_16x16x32_bf16 v[12:15], v[160:163], v[202:205], v[12:15]
	v_mfma_f32_16x16x32_bf16 v[8:11], v[152:155], v[210:213], v[6:9]
	v_mfma_f32_16x16x32_bf16 v[4:7], v[160:163], v[210:213], v[2:5]
	s_barrier
	s_setprio 0
	s_add_i32 s75, s75, 2
	s_add_u32 s14, s14, 0x100
	s_addc_u32 s15, s15, 0
	s_add_u32 s72, s72, 0x100
	s_addc_u32 s73, s73, 0
	s_cmp_gt_u32 s75, 29
	s_cbranch_scc0 .LBB0_805
	s_and_b64 vcc, exec, s[38:39]
	s_cbranch_vccz .LBB0_808
	s_barrier

; #define PG8_STAGE(bufoff, gbase, voff) do { _Pragma("unroll") for (int _i = 0; _i < 2; ++_i) \
;         __builtin_amdgcn_global_load_lds((const unsigned*)((const char*)(gbase) + (voff)[_i]), (PG8_LAS unsigned*)(lds + (bufoff) + ldsw + _i * 8192), 16, 0, 0); } while (0)
; #define PG8_LDA(dst, b, h) do { _Pragma("unroll") for (int m = 0; m < 4; ++m) _Pragma("unroll") for (int k = 0; k < 2; ++k) dst[m][k] = *(const PG8_LAS bf16x8*)(lds + PG8_SA(b, h) + aoff + m * 2048 + k * 1024); } while (0)
; #define PG8_LDB(dst, b, h) do { _Pragma("unroll") for (int n = 0; n < 2; ++n) _Pragma("unroll") for (int k = 0; k < 2; ++k) dst[n][k] = *(const PG8_LAS bf16x8*)(lds + PG8_SB(b, h) + boff + n * 2048 + k * 1024); } while (0)
; #define PG8_WAIT_V(n) asm volatile("s_waitcnt vmcnt(" #n ")" ::: "memory")
; #define PG8_WAIT_L(n) asm volatile("s_waitcnt lgkmcnt(" #n ")" ::: "memory")
; #define PG8_BAR __builtin_amdgcn_s_barrier()
; #define PG8_SCHED __builtin_amdgcn_sched_barrier(0)
; template <class Epi, class Sched, bool ALIGN_EPI = false, bool SP2 = false, bool DUAL = false>
; __device__ __forceinline__ void gemm_phase(PG8_LAS unsigned char* lds, const Gemm g, const Sched& S, const Epi& E) {
;     ...
;         const char* nA = has_next ? (const char*)((DUAL && nxt.sub) ? g.A2 : g.A) + (size_t)nxt.pm * tstep : cA; const char* nB = has_next ? (const char*)((DUAL && nxt.sub) ? g.Bt2 : g.Bt) + (size_t)nxt.pn * tstep : cB;
;         for (int t = 0; t < nt; t += 2) {
;             const bool last = (t == nt - 2);
;             const char* a1 = cA + (size_t)(t + 1) * kstep;
;             const char* a2 = last ? nA : cA + (size_t)(t + 2) * kstep; const char* b2 = last ? nB : cB + (size_t)(t + 2) * kstep;
;             const char* a3 = a2 + kstep; const char* b3 = b2 + kstep;
;             if (last && has_next) S.a_ready(nxt);
;             if constexpr (SP2) {
;             PG8_LDB(B0, 0, 0); PG8_LDB(B1, 0, 1); PG8_SCHED; PG8_LDA(At, 0, 0); PG8_STAGE(PG8_SA(1, 1), a1 + hstep, voffA);
;             PG8_WAIT_V(8); PG8_WAIT_L(0); PG8_BAR; PG8_MMA(0, 0, At, B0); PG8_MMA(0, 1, At, B1); PG8_BAR; PG8_SCHED;
;             PG8_LDA(At, 0, 1); PG8_STAGE(PG8_SB(0, 0), b2, voffB); PG8_STAGE(PG8_SB(0, 1), b2 + hstep, voffB); PG8_STAGE(PG8_SA(0, 0), a2, voffA);
;             PG8_WAIT_V(8); PG8_WAIT_L(0); PG8_BAR; PG8_MMA(1, 0, At, B0); PG8_MMA(1, 1, At, B1); PG8_BAR; PG8_SCHED;
.LBB0_895:
	s_ashr_i32 s61, s60, 31
	s_lshl_b64 s[18:19], s[60:61], 20
	s_add_u32 s62, s10, s18
	s_addc_u32 s63, s11, s19
	s_and_b64 s[18:19], s[6:7], exec
	s_cselect_b32 s18, s63, s17
	s_cselect_b32 s19, s62, s16
	s_ashr_i32 s41, s40, 31
	s_lshl_b64 s[64:65], s[40:41], 20
	s_add_u32 s64, s12, s64
	s_addc_u32 s65, s13, s65
	s_and_b64 s[68:69], s[6:7], exec
	s_cselect_b32 s41, s65, s15
	s_cselect_b32 s61, s64, s14
	s_add_u32 s68, s16, 0x80080
	s_addc_u32 s69, s17, 0
	s_add_u32 s67, s14, 0x100
	s_addc_u32 s70, s15, 0
	s_mov_b32 s71, -2
	s_waitcnt lgkmcnt(0)
	ds_read_b128 v[128:131], v218
	ds_read_b128 v[132:135], v218 offset:1024
	ds_read_b128 v[136:139], v218 offset:2048
	ds_read_b128 v[140:143], v218 offset:3072
	ds_read_b128 v[144:147], v219
	ds_read_b128 v[148:151], v219 offset:1024
	ds_read_b128 v[152:155], v219 offset:2048
	ds_read_b128 v[156:159], v219 offset:3072
	s_add_u32 s14, s68, 0xfff80080
	s_addc_u32 s15, s69, -1
	s_cmp_eq_u32 s71, 28
	s_cselect_b32 s17, s18, s15
	s_cselect_b32 s16, s19, s14
	s_cselect_b32 s15, s41, s70
	s_cselect_b32 s14, s61, s67
	v_lshl_add_u64 v[222:223], s[68:69], 0, v[188:189]
	s_add_i32 m0, s27, 0xc000
	ds_read_b128 v[160:163], v220
	ds_read_b128 v[164:167], v220 offset:1024
	ds_read_b128 v[168:171], v220 offset:2048
	ds_read_b128 v[172:175], v220 offset:3072
	ds_read_b128 v[196:199], v220 offset:4096
	ds_read_b128 v[202:205], v220 offset:5120
	ds_read_b128 v[206:209], v220 offset:6144
	ds_read_b128 v[232:235], v220 offset:7168
	global_load_lds_dwordx4 v[222:223], off
	v_lshl_add_u64 v[222:223], s[68:69], 0, v[190:191]
	s_add_i32 m0, s27, 0xe000
	s_nop 0
	global_load_lds_dwordx4 v[222:223], off
	s_waitcnt vmcnt(8)
	s_waitcnt lgkmcnt(0)
	s_setprio 1
	s_barrier
	v_mfma_f32_16x16x32_bf16 v[124:127], v[128:131], v[160:163], 0
	v_mfma_f32_16x16x32_bf16 v[120:123], v[136:139], v[160:163], 0
	v_mfma_f32_16x16x32_bf16 v[108:111], v[128:131], v[168:171], 0
	v_mfma_f32_16x16x32_bf16 v[104:107], v[136:139], v[168:171], 0
	v_mfma_f32_16x16x32_bf16 v[92:95], v[128:131], v[196:199], 0
	v_mfma_f32_16x16x32_bf16 v[88:91], v[136:139], v[196:199], 0
	v_mfma_f32_16x16x32_bf16 v[76:79], v[128:131], v[206:209], 0
	v_mfma_f32_16x16x32_bf16 v[72:75], v[136:139], v[206:209], 0
	v_mfma_f32_16x16x32_bf16 v[124:127], v[132:135], v[164:167], v[124:127]
	v_mfma_f32_16x16x32_bf16 v[120:123], v[140:143], v[164:167], v[120:123]
	v_mfma_f32_16x16x32_bf16 v[108:111], v[132:135], v[172:175], v[108:111]
	v_mfma_f32_16x16x32_bf16 v[104:107], v[140:143], v[172:175], v[104:107]
	v_mfma_f32_16x16x32_bf16 v[92:95], v[132:135], v[202:205], v[92:95]
	v_mfma_f32_16x16x32_bf16 v[88:91], v[140:143], v[202:205], v[88:91]
	v_mfma_f32_16x16x32_bf16 v[76:79], v[132:135], v[232:235], v[76:79]
	v_mfma_f32_16x16x32_bf16 v[72:75], v[140:143], v[232:235], v[72:75]
	v_mfma_f32_16x16x32_bf16 v[116:119], v[144:147], v[160:163], 0
	v_mfma_f32_16x16x32_bf16 v[112:115], v[152:155], v[160:163], 0
	v_mfma_f32_16x16x32_bf16 v[100:103], v[144:147], v[168:171], 0
	v_mfma_f32_16x16x32_bf16 v[96:99], v[152:155], v[168:171], 0
	v_mfma_f32_16x16x32_bf16 v[84:87], v[144:147], v[196:199], 0
	v_mfma_f32_16x16x32_bf16 v[80:83], v[152:155], v[196:199], 0
	v_mfma_f32_16x16x32_bf16 v[68:71], v[144:147], v[206:209], 0
	v_mfma_f32_16x16x32_bf16 v[64:67], v[152:155], v[206:209], 0
	v_mfma_f32_16x16x32_bf16 v[116:119], v[148:151], v[164:167], v[116:119]
	v_mfma_f32_16x16x32_bf16 v[112:115], v[156:159], v[164:167], v[112:115]
	v_mfma_f32_16x16x32_bf16 v[100:103], v[148:151], v[172:175], v[100:103]
	v_mfma_f32_16x16x32_bf16 v[96:99], v[156:159], v[172:175], v[96:99]
	v_mfma_f32_16x16x32_bf16 v[84:87], v[148:151], v[202:205], v[84:87]
	v_mfma_f32_16x16x32_bf16 v[80:83], v[156:159], v[202:205], v[80:83]
	v_mfma_f32_16x16x32_bf16 v[68:71], v[148:151], v[232:235], v[68:71]
	v_mfma_f32_16x16x32_bf16 v[64:67], v[156:159], v[232:235], v[64:67]
	s_barrier
	s_setprio 0
	s_add_i32 s72, s48, s26
	v_lshl_add_u64 v[222:223], s[14:15], 0, v[182:183]
	s_mov_b32 m0, s72
	ds_read_b128 v[160:163], v220 offset:16384
	ds_read_b128 v[164:167], v220 offset:17408
	ds_read_b128 v[168:171], v220 offset:18432
	ds_read_b128 v[172:175], v220 offset:19456
	ds_read_b128 v[196:199], v220 offset:20480
	ds_read_b128 v[202:205], v220 offset:21504
	ds_read_b128 v[206:209], v220 offset:22528
	ds_read_b128 v[232:235], v220 offset:23552
	global_load_lds_dwordx4 v[222:223], off
	s_add_i32 m0, s72, 0x2000
	s_add_u32 s72, s14, 0x80000
	v_lshl_add_u64 v[228:229], s[14:15], 0, v[186:187]
	s_addc_u32 s73, s15, 0
	s_add_i32 s74, s49, s26
	global_load_lds_dwordx4 v[228:229], off
	v_lshl_add_u64 v[236:237], s[72:73], 0, v[182:183]
	s_mov_b32 m0, s74
	v_lshl_add_u64 v[238:239], s[16:17], 0, v[184:185]
	global_load_lds_dwordx4 v[236:237], off
	v_lshl_add_u64 v[236:237], s[72:73], 0, v[186:187]
	s_add_i32 m0, s74, 0x2000
	s_nop 0
	global_load_lds_dwordx4 v[236:237], off
	v_lshl_add_u64 v[236:237], s[16:17], 0, v[180:181]
	s_mov_b32 m0, s27
	s_nop 0
	global_load_lds_dwordx4 v[236:237], off
	s_mov_b32 m0, s28
	s_nop 0
	global_load_lds_dwordx4 v[238:239], off
	s_waitcnt vmcnt(8)
	s_waitcnt lgkmcnt(0)
	s_setprio 1
	s_barrier
; #define PG8_STAGE(bufoff, gbase, voff) do { _Pragma("unroll") for (int _i = 0; _i < 2; ++_i) \
;         __builtin_amdgcn_global_load_lds((const unsigned*)((const char*)(gbase) + (voff)[_i]), (PG8_LAS unsigned*)(lds + (bufoff) + ldsw + _i * 8192), 16, 0, 0); } while (0)
; #define PG8_LDA(dst, b, h) do { _Pragma("unroll") for (int m = 0; m < 4; ++m) _Pragma("unroll") for (int k = 0; k < 2; ++k) dst[m][k] = *(const PG8_LAS bf16x8*)(lds + PG8_SA(b, h) + aoff + m * 2048 + k * 1024); } while (0)
; #define PG8_LDB(dst, b, h) do { _Pragma("unroll") for (int n = 0; n < 2; ++n) _Pragma("unroll") for (int k = 0; k < 2; ++k) dst[n][k] = *(const PG8_LAS bf16x8*)(lds + PG8_SB(b, h) + boff + n * 2048 + k * 1024); } while (0)
; #define PG8_MMA(ai, bj, At, Bt) do { __builtin_amdgcn_s_setprio(1); _Pragma("unroll") for (int m = 0; m < 4; ++m) _Pragma("unroll") for (int n = 0; n < 2; ++n) _Pragma("unroll") for (int k = 0; k < 2; ++k) \
;         acc[ai][bj][m][n] = __builtin_amdgcn_mfma_f32_16x16x32_bf16(Bt[n][k], At[m][k], acc[ai][bj][m][n], 0, 0, 0); __builtin_amdgcn_s_setprio(0); } while (0)
; #define PG8_WAIT_V(n) asm volatile("s_waitcnt vmcnt(" #n ")" ::: "memory")
; #define PG8_WAIT_L(n) asm volatile("s_waitcnt lgkmcnt(" #n ")" ::: "memory")
; #define PG8_BAR __builtin_amdgcn_s_barrier()
; #define PG8_SCHED __builtin_amdgcn_sched_barrier(0)
; template <class Epi, class Sched, bool ALIGN_EPI = false, bool SP2 = false, bool DUAL = false>
; __device__ __forceinline__ void gemm_phase(PG8_LAS unsigned char* lds, const Gemm g, const Sched& S, const Epi& E) {
;     ...
;             PG8_WAIT_V(8); PG8_WAIT_L(0); PG8_BAR; PG8_MMA(1, 0, At, B0); PG8_MMA(1, 1, At, B1); PG8_BAR; PG8_SCHED;
;             PG8_LDB(B0, 1, 0); PG8_LDB(B1, 1, 1); PG8_SCHED; PG8_LDA(At, 1, 0); PG8_STAGE(PG8_SA(0, 1), a2 + hstep, voffA);
;             PG8_WAIT_V(8); PG8_WAIT_L(0); PG8_BAR; PG8_MMA(0, 0, At, B0); PG8_MMA(0, 1, At, B1); PG8_BAR; PG8_SCHED;
	v_mfma_f32_16x16x32_bf16 v[60:63], v[128:131], v[160:163], 0
	v_mfma_f32_16x16x32_bf16 v[56:59], v[136:139], v[160:163], 0
	v_mfma_f32_16x16x32_bf16 v[44:47], v[128:131], v[168:171], 0
	v_mfma_f32_16x16x32_bf16 v[40:43], v[136:139], v[168:171], 0
	v_mfma_f32_16x16x32_bf16 v[28:31], v[128:131], v[196:199], 0
	v_mfma_f32_16x16x32_bf16 v[24:27], v[136:139], v[196:199], 0
	v_mfma_f32_16x16x32_bf16 v[12:15], v[128:131], v[206:209], 0
	v_mfma_f32_16x16x32_bf16 v[8:11], v[136:139], v[206:209], 0
	v_mfma_f32_16x16x32_bf16 v[60:63], v[132:135], v[164:167], v[60:63]
	v_mfma_f32_16x16x32_bf16 v[56:59], v[140:143], v[164:167], v[56:59]
	v_mfma_f32_16x16x32_bf16 v[44:47], v[132:135], v[172:175], v[44:47]
	v_mfma_f32_16x16x32_bf16 v[40:43], v[140:143], v[172:175], v[40:43]
	v_mfma_f32_16x16x32_bf16 v[28:31], v[132:135], v[202:205], v[28:31]
	v_mfma_f32_16x16x32_bf16 v[24:27], v[140:143], v[202:205], v[24:27]
	v_mfma_f32_16x16x32_bf16 v[12:15], v[132:135], v[232:235], v[12:15]
	v_mfma_f32_16x16x32_bf16 v[8:11], v[140:143], v[232:235], v[8:11]
	v_mfma_f32_16x16x32_bf16 v[52:55], v[144:147], v[160:163], 0
	v_mfma_f32_16x16x32_bf16 v[48:51], v[152:155], v[160:163], 0
	v_mfma_f32_16x16x32_bf16 v[36:39], v[144:147], v[168:171], 0
	v_mfma_f32_16x16x32_bf16 v[32:35], v[152:155], v[168:171], 0
	v_mfma_f32_16x16x32_bf16 v[20:23], v[144:147], v[196:199], 0
	v_mfma_f32_16x16x32_bf16 v[16:19], v[152:155], v[196:199], 0
	v_mfma_f32_16x16x32_bf16 v[4:7], v[144:147], v[206:209], 0
	v_mfma_f32_16x16x32_bf16 v[0:3], v[152:155], v[206:209], 0
	v_mfma_f32_16x16x32_bf16 v[52:55], v[148:151], v[164:167], v[52:55]
	v_mfma_f32_16x16x32_bf16 v[48:51], v[156:159], v[164:167], v[48:51]
	v_mfma_f32_16x16x32_bf16 v[36:39], v[148:151], v[172:175], v[36:39]
	v_mfma_f32_16x16x32_bf16 v[32:35], v[156:159], v[172:175], v[32:35]
	v_mfma_f32_16x16x32_bf16 v[20:23], v[148:151], v[202:205], v[20:23]
	v_mfma_f32_16x16x32_bf16 v[16:19], v[156:159], v[202:205], v[16:19]
	v_mfma_f32_16x16x32_bf16 v[4:7], v[148:151], v[232:235], v[4:7]
	v_mfma_f32_16x16x32_bf16 v[0:3], v[156:159], v[232:235], v[0:3]
	s_barrier
	s_setprio 0
	s_add_i32 s72, 0, 0x18000
	s_add_i32 s73, 0, 0x1c000
	v_add_u32_e32 v140, s72, v216
	v_add_u32_e32 v156, s73, v216
	ds_read_b128 v[128:131], v140
	ds_read_b128 v[132:135], v140 offset:1024
	ds_read_b128 v[136:139], v140 offset:2048
	ds_read_b128 v[140:143], v140 offset:3072
	ds_read_b128 v[144:147], v156
	ds_read_b128 v[148:151], v156 offset:1024
	ds_read_b128 v[152:155], v156 offset:2048
	ds_read_b128 v[156:159], v156 offset:3072
	s_add_u32 s16, s16, 0x80000
	s_addc_u32 s17, s17, 0
	s_mov_b32 m0, s29
	v_lshl_add_u64 v[240:241], s[16:17], 0, v[180:181]
	ds_read_b128 v[160:163], v220 offset:32768
	ds_read_b128 v[164:167], v220 offset:33792
	ds_read_b128 v[168:171], v220 offset:34816
	ds_read_b128 v[172:175], v220 offset:35840
	ds_read_b128 v[196:199], v220 offset:36864
	ds_read_b128 v[202:205], v220 offset:37888
	ds_read_b128 v[206:209], v220 offset:38912
	ds_read_b128 v[232:235], v220 offset:39936
	global_load_lds_dwordx4 v[240:241], off
	v_lshl_add_u64 v[240:241], s[16:17], 0, v[184:185]
	s_mov_b32 m0, s34
	s_nop 0
	global_load_lds_dwordx4 v[240:241], off
	s_waitcnt vmcnt(8)
	s_waitcnt lgkmcnt(0)
	s_setprio 1
	s_barrier
	v_mfma_f32_16x16x32_bf16 v[124:127], v[128:131], v[160:163], v[124:127]
	v_mfma_f32_16x16x32_bf16 v[120:123], v[136:139], v[160:163], v[120:123]
	v_mfma_f32_16x16x32_bf16 v[108:111], v[128:131], v[168:171], v[108:111]
	v_mfma_f32_16x16x32_bf16 v[104:107], v[136:139], v[168:171], v[104:107]
	v_mfma_f32_16x16x32_bf16 v[92:95], v[128:131], v[196:199], v[92:95]
	v_mfma_f32_16x16x32_bf16 v[88:91], v[136:139], v[196:199], v[88:91]
	v_mfma_f32_16x16x32_bf16 v[76:79], v[128:131], v[206:209], v[76:79]
	v_mfma_f32_16x16x32_bf16 v[72:75], v[136:139], v[206:209], v[72:75]
	v_mfma_f32_16x16x32_bf16 v[124:127], v[132:135], v[164:167], v[124:127]
	v_mfma_f32_16x16x32_bf16 v[120:123], v[140:143], v[164:167], v[120:123]
	v_mfma_f32_16x16x32_bf16 v[108:111], v[132:135], v[172:175], v[108:111]
	v_mfma_f32_16x16x32_bf16 v[104:107], v[140:143], v[172:175], v[104:107]
	v_mfma_f32_16x16x32_bf16 v[92:95], v[132:135], v[202:205], v[92:95]
	v_mfma_f32_16x16x32_bf16 v[88:91], v[140:143], v[202:205], v[88:91]
	v_mfma_f32_16x16x32_bf16 v[76:79], v[132:135], v[232:235], v[76:79]
	v_mfma_f32_16x16x32_bf16 v[72:75], v[140:143], v[232:235], v[72:75]
	v_mfma_f32_16x16x32_bf16 v[116:119], v[144:147], v[160:163], v[116:119]
	v_mfma_f32_16x16x32_bf16 v[112:115], v[152:155], v[160:163], v[112:115]
	v_mfma_f32_16x16x32_bf16 v[100:103], v[144:147], v[168:171], v[100:103]
	v_mfma_f32_16x16x32_bf16 v[96:99], v[152:155], v[168:171], v[96:99]
	v_mfma_f32_16x16x32_bf16 v[84:87], v[144:147], v[196:199], v[84:87]
	v_mfma_f32_16x16x32_bf16 v[80:83], v[152:155], v[196:199], v[80:83]
	v_mfma_f32_16x16x32_bf16 v[68:71], v[144:147], v[206:209], v[68:71]
	v_mfma_f32_16x16x32_bf16 v[64:67], v[152:155], v[206:209], v[64:67]
	v_mfma_f32_16x16x32_bf16 v[116:119], v[148:151], v[164:167], v[116:119]
	v_mfma_f32_16x16x32_bf16 v[112:115], v[156:159], v[164:167], v[112:115]
	v_mfma_f32_16x16x32_bf16 v[100:103], v[148:151], v[172:175], v[100:103]
	v_mfma_f32_16x16x32_bf16 v[96:99], v[156:159], v[172:175], v[96:99]
	v_mfma_f32_16x16x32_bf16 v[84:87], v[148:151], v[202:205], v[84:87]
	v_mfma_f32_16x16x32_bf16 v[80:83], v[156:159], v[202:205], v[80:83]
	v_mfma_f32_16x16x32_bf16 v[68:71], v[148:151], v[232:235], v[68:71]
	v_mfma_f32_16x16x32_bf16 v[64:67], v[156:159], v[232:235], v[64:67]
	s_barrier
; #define PG8_STAGE(bufoff, gbase, voff) do { _Pragma("unroll") for (int _i = 0; _i < 2; ++_i) \
;         __builtin_amdgcn_global_load_lds((const unsigned*)((const char*)(gbase) + (voff)[_i]), (PG8_LAS unsigned*)(lds + (bufoff) + ldsw + _i * 8192), 16, 0, 0); } while (0)
; #define PG8_LDA(dst, b, h) do { _Pragma("unroll") for (int m = 0; m < 4; ++m) _Pragma("unroll") for (int k = 0; k < 2; ++k) dst[m][k] = *(const PG8_LAS bf16x8*)(lds + PG8_SA(b, h) + aoff + m * 2048 + k * 1024); } while (0)
; #define PG8_LDB(dst, b, h) do { _Pragma("unroll") for (int n = 0; n < 2; ++n) _Pragma("unroll") for (int k = 0; k < 2; ++k) dst[n][k] = *(const PG8_LAS bf16x8*)(lds + PG8_SB(b, h) + boff + n * 2048 + k * 1024); } while (0)
; #define PG8_MMA(ai, bj, At, Bt) do { __builtin_amdgcn_s_setprio(1); _Pragma("unroll") for (int m = 0; m < 4; ++m) _Pragma("unroll") for (int n = 0; n < 2; ++n) _Pragma("unroll") for (int k = 0; k < 2; ++k) \
;         acc[ai][bj][m][n] = __builtin_amdgcn_mfma_f32_16x16x32_bf16(Bt[n][k], At[m][k], acc[ai][bj][m][n], 0, 0, 0); __builtin_amdgcn_s_setprio(0); } while (0)
; #define PG8_WAIT_V(n) asm volatile("s_waitcnt vmcnt(" #n ")" ::: "memory")
; #define PG8_WAIT_L(n) asm volatile("s_waitcnt lgkmcnt(" #n ")" ::: "memory")
; #define PG8_BAR __builtin_amdgcn_s_barrier()
; #define PG8_SCHED __builtin_amdgcn_sched_barrier(0)
; template <class Epi, class Sched, bool ALIGN_EPI = false, bool SP2 = false, bool DUAL = false>
; __device__ __forceinline__ void gemm_phase(PG8_LAS unsigned char* lds, const Gemm g, const Sched& S, const Epi& E) {
;     ...
;             PG8_LDB(B0, 0, 0); PG8_LDB(B1, 0, 1); PG8_SCHED; PG8_LDA(At, 0, 0); PG8_STAGE(PG8_SA(1, 1), a1 + hstep, voffA);
;             PG8_WAIT_V(8); PG8_WAIT_L(0); PG8_BAR; PG8_MMA(0, 0, At, B0); PG8_MMA(0, 1, At, B1); PG8_BAR; PG8_SCHED;
;     ...
;             PG8_LDA(At, 1, 1); PG8_STAGE(PG8_SB(1, 0), b3, voffB); PG8_STAGE(PG8_SB(1, 1), b3 + hstep, voffB); PG8_STAGE(PG8_SA(1, 0), a3, voffA);
;             PG8_WAIT_V(8); PG8_WAIT_L(0); PG8_BAR; PG8_MMA(1, 0, At, B0); PG8_MMA(1, 1, At, B1); PG8_BAR; PG8_SCHED;
	s_setprio 0
	s_add_i32 s16, s72, s26
	v_lshl_add_u64 v[222:223], v[222:223], 0, s[36:37]
	s_mov_b32 m0, s16
	ds_read_b128 v[160:163], v220 offset:49152
	ds_read_b128 v[164:167], v220 offset:50176
	ds_read_b128 v[168:171], v220 offset:51200
	ds_read_b128 v[172:175], v220 offset:52224
	ds_read_b128 v[196:199], v220 offset:53248
	ds_read_b128 v[202:205], v220 offset:54272
	ds_read_b128 v[206:209], v220 offset:55296
	ds_read_b128 v[232:235], v220 offset:56320
	global_load_lds_dwordx4 v[222:223], off
	s_add_i32 m0, s16, 0x2000
	s_add_u32 s14, s14, 0x80080
	v_lshl_add_u64 v[222:223], v[228:229], 0, s[36:37]
	s_addc_u32 s15, s15, 0
	s_add_i32 s16, s73, s26
	global_load_lds_dwordx4 v[222:223], off
	v_lshl_add_u64 v[222:223], s[14:15], 0, v[182:183]
	s_mov_b32 m0, s16
	s_nop 0
	global_load_lds_dwordx4 v[222:223], off
	v_lshl_add_u64 v[222:223], s[14:15], 0, v[186:187]
	s_add_i32 m0, s16, 0x2000
	s_nop 0
	global_load_lds_dwordx4 v[222:223], off
	v_lshl_add_u64 v[222:223], v[236:237], 0, s[36:37]
	s_mov_b32 m0, s44
	s_nop 0
	global_load_lds_dwordx4 v[222:223], off
	v_lshl_add_u64 v[222:223], v[238:239], 0, s[36:37]
	s_mov_b32 m0, s45
	s_nop 0
	global_load_lds_dwordx4 v[222:223], off
	s_waitcnt vmcnt(8)
	s_waitcnt lgkmcnt(0)
	s_setprio 1
	s_barrier
	v_mfma_f32_16x16x32_bf16 v[60:63], v[128:131], v[160:163], v[60:63]
	v_mfma_f32_16x16x32_bf16 v[56:59], v[136:139], v[160:163], v[56:59]
	v_mfma_f32_16x16x32_bf16 v[44:47], v[128:131], v[168:171], v[44:47]
	v_mfma_f32_16x16x32_bf16 v[40:43], v[136:139], v[168:171], v[40:43]
	v_mfma_f32_16x16x32_bf16 v[28:31], v[128:131], v[196:199], v[28:31]
	v_mfma_f32_16x16x32_bf16 v[24:27], v[136:139], v[196:199], v[24:27]
	v_mfma_f32_16x16x32_bf16 v[12:15], v[128:131], v[206:209], v[12:15]
	v_mfma_f32_16x16x32_bf16 v[8:11], v[136:139], v[206:209], v[8:11]
	v_mfma_f32_16x16x32_bf16 v[60:63], v[132:135], v[164:167], v[60:63]
	v_mfma_f32_16x16x32_bf16 v[56:59], v[140:143], v[164:167], v[56:59]
	v_mfma_f32_16x16x32_bf16 v[44:47], v[132:135], v[172:175], v[44:47]
	v_mfma_f32_16x16x32_bf16 v[40:43], v[140:143], v[172:175], v[40:43]
	v_mfma_f32_16x16x32_bf16 v[28:31], v[132:135], v[202:205], v[28:31]
	v_mfma_f32_16x16x32_bf16 v[24:27], v[140:143], v[202:205], v[24:27]
	v_mfma_f32_16x16x32_bf16 v[12:15], v[132:135], v[232:235], v[12:15]
	v_mfma_f32_16x16x32_bf16 v[8:11], v[140:143], v[232:235], v[8:11]
	v_mfma_f32_16x16x32_bf16 v[52:55], v[144:147], v[160:163], v[52:55]
	v_mfma_f32_16x16x32_bf16 v[48:51], v[152:155], v[160:163], v[48:51]
	v_mfma_f32_16x16x32_bf16 v[36:39], v[144:147], v[168:171], v[36:39]
	v_mfma_f32_16x16x32_bf16 v[32:35], v[152:155], v[168:171], v[32:35]
	v_mfma_f32_16x16x32_bf16 v[20:23], v[144:147], v[196:199], v[20:23]
	v_mfma_f32_16x16x32_bf16 v[16:19], v[152:155], v[196:199], v[16:19]
	v_mfma_f32_16x16x32_bf16 v[4:7], v[144:147], v[206:209], v[4:7]
	v_mfma_f32_16x16x32_bf16 v[0:3], v[152:155], v[206:209], v[0:3]
	v_mfma_f32_16x16x32_bf16 v[52:55], v[148:151], v[164:167], v[52:55]
	v_mfma_f32_16x16x32_bf16 v[48:51], v[156:159], v[164:167], v[48:51]
	v_mfma_f32_16x16x32_bf16 v[36:39], v[148:151], v[172:175], v[36:39]
	v_mfma_f32_16x16x32_bf16 v[32:35], v[156:159], v[172:175], v[32:35]
	v_mfma_f32_16x16x32_bf16 v[20:23], v[148:151], v[202:205], v[20:23]
	v_mfma_f32_16x16x32_bf16 v[16:19], v[156:159], v[202:205], v[16:19]
	v_mfma_f32_16x16x32_bf16 v[4:7], v[148:151], v[232:235], v[4:7]
	v_mfma_f32_16x16x32_bf16 v[0:3], v[156:159], v[232:235], v[0:3]
	s_barrier
	s_setprio 0
	s_add_i32 s71, s71, 2
	s_add_u32 s68, s68, 0x100
	s_addc_u32 s69, s69, 0
	s_add_u32 s67, s67, 0x100
	s_addc_u32 s70, s70, 0
.LBB0_896:
	ds_read_b128 v[128:131], v218
	ds_read_b128 v[132:135], v218 offset:1024
	ds_read_b128 v[136:139], v218 offset:2048
	ds_read_b128 v[140:143], v218 offset:3072
	ds_read_b128 v[144:147], v219
	ds_read_b128 v[148:151], v219 offset:1024
	ds_read_b128 v[152:155], v219 offset:2048
	ds_read_b128 v[156:159], v219 offset:3072
	s_add_u32 s14, s68, 0xfff80080
	s_addc_u32 s15, s69, -1
	s_cmp_eq_u32 s71, 28
	s_cselect_b32 s17, s18, s15
	s_cselect_b32 s16, s19, s14
	s_cselect_b32 s15, s41, s70
	s_cselect_b32 s14, s61, s67
	v_lshl_add_u64 v[222:223], s[68:69], 0, v[188:189]
	s_add_i32 m0, s27, 0xc000
	ds_read_b128 v[160:163], v220
	ds_read_b128 v[164:167], v220 offset:1024
	ds_read_b128 v[168:171], v220 offset:2048
	ds_read_b128 v[172:175], v220 offset:3072
	ds_read_b128 v[196:199], v220 offset:4096
	ds_read_b128 v[202:205], v220 offset:5120
	ds_read_b128 v[206:209], v220 offset:6144
	ds_read_b128 v[232:235], v220 offset:7168
	global_load_lds_dwordx4 v[222:223], off
	v_lshl_add_u64 v[222:223], s[68:69], 0, v[190:191]
	s_add_i32 m0, s27, 0xe000
	s_nop 0
	global_load_lds_dwordx4 v[222:223], off
	s_waitcnt vmcnt(8)
	s_waitcnt lgkmcnt(0)
	s_setprio 1
	s_barrier
; #define PG8_STAGE(bufoff, gbase, voff) do { _Pragma("unroll") for (int _i = 0; _i < 2; ++_i) \
;         __builtin_amdgcn_global_load_lds((const unsigned*)((const char*)(gbase) + (voff)[_i]), (PG8_LAS unsigned*)(lds + (bufoff) + ldsw + _i * 8192), 16, 0, 0); } while (0)
; #define PG8_LDA(dst, b, h) do { _Pragma("unroll") for (int m = 0; m < 4; ++m) _Pragma("unroll") for (int k = 0; k < 2; ++k) dst[m][k] = *(const PG8_LAS bf16x8*)(lds + PG8_SA(b, h) + aoff + m * 2048 + k * 1024); } while (0)
; #define PG8_MMA(ai, bj, At, Bt) do { __builtin_amdgcn_s_setprio(1); _Pragma("unroll") for (int m = 0; m < 4; ++m) _Pragma("unroll") for (int n = 0; n < 2; ++n) _Pragma("unroll") for (int k = 0; k < 2; ++k) \
;         acc[ai][bj][m][n] = __builtin_amdgcn_mfma_f32_16x16x32_bf16(Bt[n][k], At[m][k], acc[ai][bj][m][n], 0, 0, 0); __builtin_amdgcn_s_setprio(0); } while (0)
; #define PG8_WAIT_V(n) asm volatile("s_waitcnt vmcnt(" #n ")" ::: "memory")
; #define PG8_WAIT_L(n) asm volatile("s_waitcnt lgkmcnt(" #n ")" ::: "memory")
; #define PG8_BAR __builtin_amdgcn_s_barrier()
; #define PG8_SCHED __builtin_amdgcn_sched_barrier(0)
; template <class Epi, class Sched, bool ALIGN_EPI = false, bool SP2 = false, bool DUAL = false>
; __device__ __forceinline__ void gemm_phase(PG8_LAS unsigned char* lds, const Gemm g, const Sched& S, const Epi& E) {
;     ...
;             PG8_WAIT_V(8); PG8_WAIT_L(0); PG8_BAR; PG8_MMA(0, 0, At, B0); PG8_MMA(0, 1, At, B1); PG8_BAR; PG8_SCHED;
;             PG8_LDA(At, 0, 1); PG8_STAGE(PG8_SB(0, 0), b2, voffB); PG8_STAGE(PG8_SB(0, 1), b2 + hstep, voffB); PG8_STAGE(PG8_SA(0, 0), a2, voffA);
;             PG8_WAIT_V(8); PG8_WAIT_L(0); PG8_BAR; PG8_MMA(1, 0, At, B0); PG8_MMA(1, 1, At, B1); PG8_BAR; PG8_SCHED;
	v_mfma_f32_16x16x32_bf16 v[124:127], v[128:131], v[160:163], v[124:127]
	v_mfma_f32_16x16x32_bf16 v[120:123], v[136:139], v[160:163], v[120:123]
	v_mfma_f32_16x16x32_bf16 v[108:111], v[128:131], v[168:171], v[108:111]
	v_mfma_f32_16x16x32_bf16 v[104:107], v[136:139], v[168:171], v[104:107]
	v_mfma_f32_16x16x32_bf16 v[92:95], v[128:131], v[196:199], v[92:95]
	v_mfma_f32_16x16x32_bf16 v[88:91], v[136:139], v[196:199], v[88:91]
	v_mfma_f32_16x16x32_bf16 v[76:79], v[128:131], v[206:209], v[76:79]
	v_mfma_f32_16x16x32_bf16 v[72:75], v[136:139], v[206:209], v[72:75]
	v_mfma_f32_16x16x32_bf16 v[124:127], v[132:135], v[164:167], v[124:127]
	v_mfma_f32_16x16x32_bf16 v[120:123], v[140:143], v[164:167], v[120:123]
	v_mfma_f32_16x16x32_bf16 v[108:111], v[132:135], v[172:175], v[108:111]
	v_mfma_f32_16x16x32_bf16 v[104:107], v[140:143], v[172:175], v[104:107]
	v_mfma_f32_16x16x32_bf16 v[92:95], v[132:135], v[202:205], v[92:95]
	v_mfma_f32_16x16x32_bf16 v[88:91], v[140:143], v[202:205], v[88:91]
	v_mfma_f32_16x16x32_bf16 v[76:79], v[132:135], v[232:235], v[76:79]
	v_mfma_f32_16x16x32_bf16 v[72:75], v[140:143], v[232:235], v[72:75]
	v_mfma_f32_16x16x32_bf16 v[116:119], v[144:147], v[160:163], v[116:119]
	v_mfma_f32_16x16x32_bf16 v[112:115], v[152:155], v[160:163], v[112:115]
	v_mfma_f32_16x16x32_bf16 v[100:103], v[144:147], v[168:171], v[100:103]
	v_mfma_f32_16x16x32_bf16 v[96:99], v[152:155], v[168:171], v[96:99]
	v_mfma_f32_16x16x32_bf16 v[84:87], v[144:147], v[196:199], v[84:87]
	v_mfma_f32_16x16x32_bf16 v[80:83], v[152:155], v[196:199], v[80:83]
	v_mfma_f32_16x16x32_bf16 v[68:71], v[144:147], v[206:209], v[68:71]
	v_mfma_f32_16x16x32_bf16 v[64:67], v[152:155], v[206:209], v[64:67]
	v_mfma_f32_16x16x32_bf16 v[116:119], v[148:151], v[164:167], v[116:119]
	v_mfma_f32_16x16x32_bf16 v[112:115], v[156:159], v[164:167], v[112:115]
	v_mfma_f32_16x16x32_bf16 v[100:103], v[148:151], v[172:175], v[100:103]
	v_mfma_f32_16x16x32_bf16 v[96:99], v[156:159], v[172:175], v[96:99]
	v_mfma_f32_16x16x32_bf16 v[84:87], v[148:151], v[202:205], v[84:87]
	v_mfma_f32_16x16x32_bf16 v[80:83], v[156:159], v[202:205], v[80:83]
	v_mfma_f32_16x16x32_bf16 v[68:71], v[148:151], v[232:235], v[68:71]
	v_mfma_f32_16x16x32_bf16 v[64:67], v[156:159], v[232:235], v[64:67]
	s_barrier
	s_setprio 0
	s_add_i32 s72, s48, s26
	v_lshl_add_u64 v[222:223], s[14:15], 0, v[182:183]
	s_mov_b32 m0, s72
	ds_read_b128 v[160:163], v220 offset:16384
	ds_read_b128 v[164:167], v220 offset:17408
	ds_read_b128 v[168:171], v220 offset:18432
	ds_read_b128 v[172:175], v220 offset:19456
	ds_read_b128 v[196:199], v220 offset:20480
	ds_read_b128 v[202:205], v220 offset:21504
	ds_read_b128 v[206:209], v220 offset:22528
	ds_read_b128 v[232:235], v220 offset:23552
	global_load_lds_dwordx4 v[222:223], off
	s_add_i32 m0, s72, 0x2000
	s_add_u32 s72, s14, 0x80000
	v_lshl_add_u64 v[228:229], s[14:15], 0, v[186:187]
	s_addc_u32 s73, s15, 0
	s_add_i32 s74, s49, s26
	global_load_lds_dwordx4 v[228:229], off
	v_lshl_add_u64 v[236:237], s[72:73], 0, v[182:183]
	s_mov_b32 m0, s74
	v_lshl_add_u64 v[238:239], s[16:17], 0, v[184:185]
	global_load_lds_dwordx4 v[236:237], off
	v_lshl_add_u64 v[236:237], s[72:73], 0, v[186:187]
	s_add_i32 m0, s74, 0x2000
	s_nop 0
	global_load_lds_dwordx4 v[236:237], off
	v_lshl_add_u64 v[236:237], s[16:17], 0, v[180:181]
	s_mov_b32 m0, s27
	s_nop 0
	global_load_lds_dwordx4 v[236:237], off
	s_mov_b32 m0, s28
	s_nop 0
	global_load_lds_dwordx4 v[238:239], off
	s_waitcnt vmcnt(8)
	s_waitcnt lgkmcnt(0)
	s_setprio 1
	s_barrier
	v_mfma_f32_16x16x32_bf16 v[60:63], v[128:131], v[160:163], v[60:63]
	v_mfma_f32_16x16x32_bf16 v[56:59], v[136:139], v[160:163], v[56:59]
	v_mfma_f32_16x16x32_bf16 v[44:47], v[128:131], v[168:171], v[44:47]
	v_mfma_f32_16x16x32_bf16 v[40:43], v[136:139], v[168:171], v[40:43]
	v_mfma_f32_16x16x32_bf16 v[28:31], v[128:131], v[196:199], v[28:31]
	v_mfma_f32_16x16x32_bf16 v[24:27], v[136:139], v[196:199], v[24:27]
	v_mfma_f32_16x16x32_bf16 v[12:15], v[128:131], v[206:209], v[12:15]
	v_mfma_f32_16x16x32_bf16 v[8:11], v[136:139], v[206:209], v[8:11]
	v_mfma_f32_16x16x32_bf16 v[60:63], v[132:135], v[164:167], v[60:63]
	v_mfma_f32_16x16x32_bf16 v[56:59], v[140:143], v[164:167], v[56:59]
	v_mfma_f32_16x16x32_bf16 v[44:47], v[132:135], v[172:175], v[44:47]
	v_mfma_f32_16x16x32_bf16 v[40:43], v[140:143], v[172:175], v[40:43]
	v_mfma_f32_16x16x32_bf16 v[28:31], v[132:135], v[202:205], v[28:31]
	v_mfma_f32_16x16x32_bf16 v[24:27], v[140:143], v[202:205], v[24:27]
	v_mfma_f32_16x16x32_bf16 v[12:15], v[132:135], v[232:235], v[12:15]
	v_mfma_f32_16x16x32_bf16 v[8:11], v[140:143], v[232:235], v[8:11]
	v_mfma_f32_16x16x32_bf16 v[52:55], v[144:147], v[160:163], v[52:55]
	v_mfma_f32_16x16x32_bf16 v[48:51], v[152:155], v[160:163], v[48:51]
	v_mfma_f32_16x16x32_bf16 v[36:39], v[144:147], v[168:171], v[36:39]
	v_mfma_f32_16x16x32_bf16 v[32:35], v[152:155], v[168:171], v[32:35]
	v_mfma_f32_16x16x32_bf16 v[20:23], v[144:147], v[196:199], v[20:23]
	v_mfma_f32_16x16x32_bf16 v[16:19], v[152:155], v[196:199], v[16:19]
	v_mfma_f32_16x16x32_bf16 v[4:7], v[144:147], v[206:209], v[4:7]
	v_mfma_f32_16x16x32_bf16 v[0:3], v[152:155], v[206:209], v[0:3]
	v_mfma_f32_16x16x32_bf16 v[52:55], v[148:151], v[164:167], v[52:55]
	v_mfma_f32_16x16x32_bf16 v[48:51], v[156:159], v[164:167], v[48:51]
	v_mfma_f32_16x16x32_bf16 v[36:39], v[148:151], v[172:175], v[36:39]
	v_mfma_f32_16x16x32_bf16 v[32:35], v[156:159], v[172:175], v[32:35]
	v_mfma_f32_16x16x32_bf16 v[20:23], v[148:151], v[202:205], v[20:23]
	v_mfma_f32_16x16x32_bf16 v[16:19], v[156:159], v[202:205], v[16:19]
	v_mfma_f32_16x16x32_bf16 v[4:7], v[148:151], v[232:235], v[4:7]
	v_mfma_f32_16x16x32_bf16 v[0:3], v[156:159], v[232:235], v[0:3]
	s_barrier
; #define PG8_STAGE(bufoff, gbase, voff) do { _Pragma("unroll") for (int _i = 0; _i < 2; ++_i) \
;         __builtin_amdgcn_global_load_lds((const unsigned*)((const char*)(gbase) + (voff)[_i]), (PG8_LAS unsigned*)(lds + (bufoff) + ldsw + _i * 8192), 16, 0, 0); } while (0)
; #define PG8_LDA(dst, b, h) do { _Pragma("unroll") for (int m = 0; m < 4; ++m) _Pragma("unroll") for (int k = 0; k < 2; ++k) dst[m][k] = *(const PG8_LAS bf16x8*)(lds + PG8_SA(b, h) + aoff + m * 2048 + k * 1024); } while (0)
; #define PG8_LDB(dst, b, h) do { _Pragma("unroll") for (int n = 0; n < 2; ++n) _Pragma("unroll") for (int k = 0; k < 2; ++k) dst[n][k] = *(const PG8_LAS bf16x8*)(lds + PG8_SB(b, h) + boff + n * 2048 + k * 1024); } while (0)
; #define PG8_MMA(ai, bj, At, Bt) do { __builtin_amdgcn_s_setprio(1); _Pragma("unroll") for (int m = 0; m < 4; ++m) _Pragma("unroll") for (int n = 0; n < 2; ++n) _Pragma("unroll") for (int k = 0; k < 2; ++k) \
;         acc[ai][bj][m][n] = __builtin_amdgcn_mfma_f32_16x16x32_bf16(Bt[n][k], At[m][k], acc[ai][bj][m][n], 0, 0, 0); __builtin_amdgcn_s_setprio(0); } while (0)
; #define PG8_WAIT_V(n) asm volatile("s_waitcnt vmcnt(" #n ")" ::: "memory")
; #define PG8_WAIT_L(n) asm volatile("s_waitcnt lgkmcnt(" #n ")" ::: "memory")
; #define PG8_BAR __builtin_amdgcn_s_barrier()
; #define PG8_SCHED __builtin_amdgcn_sched_barrier(0)
; template <class Epi, class Sched, bool ALIGN_EPI = false, bool SP2 = false, bool DUAL = false>
; __device__ __forceinline__ void gemm_phase(PG8_LAS unsigned char* lds, const Gemm g, const Sched& S, const Epi& E) {
;     ...
;             PG8_LDB(B0, 1, 0); PG8_LDB(B1, 1, 1); PG8_SCHED; PG8_LDA(At, 1, 0); PG8_STAGE(PG8_SA(0, 1), a2 + hstep, voffA);
;             PG8_WAIT_V(8); PG8_WAIT_L(0); PG8_BAR; PG8_MMA(0, 0, At, B0); PG8_MMA(0, 1, At, B1); PG8_BAR; PG8_SCHED;
	s_setprio 0
	s_add_i32 s72, 0, 0x18000
	s_add_i32 s73, 0, 0x1c000
	v_add_u32_e32 v140, s72, v216
	v_add_u32_e32 v156, s73, v216
	ds_read_b128 v[128:131], v140
	ds_read_b128 v[132:135], v140 offset:1024
	ds_read_b128 v[136:139], v140 offset:2048
	ds_read_b128 v[140:143], v140 offset:3072
	ds_read_b128 v[144:147], v156
	ds_read_b128 v[148:151], v156 offset:1024
	ds_read_b128 v[152:155], v156 offset:2048
	ds_read_b128 v[156:159], v156 offset:3072
	s_add_u32 s16, s16, 0x80000
	s_addc_u32 s17, s17, 0
	s_mov_b32 m0, s29
	v_lshl_add_u64 v[240:241], s[16:17], 0, v[180:181]
	ds_read_b128 v[160:163], v220 offset:32768
	ds_read_b128 v[164:167], v220 offset:33792
	ds_read_b128 v[168:171], v220 offset:34816
	ds_read_b128 v[172:175], v220 offset:35840
	ds_read_b128 v[196:199], v220 offset:36864
	ds_read_b128 v[202:205], v220 offset:37888
	ds_read_b128 v[206:209], v220 offset:38912
	ds_read_b128 v[232:235], v220 offset:39936
	global_load_lds_dwordx4 v[240:241], off
	v_lshl_add_u64 v[240:241], s[16:17], 0, v[184:185]
	s_mov_b32 m0, s34
	s_nop 0
	global_load_lds_dwordx4 v[240:241], off
	s_waitcnt vmcnt(8)
	s_waitcnt lgkmcnt(0)
	s_setprio 1
	s_barrier
	v_mfma_f32_16x16x32_bf16 v[124:127], v[128:131], v[160:163], v[124:127]
	v_mfma_f32_16x16x32_bf16 v[120:123], v[136:139], v[160:163], v[120:123]
	v_mfma_f32_16x16x32_bf16 v[108:111], v[128:131], v[168:171], v[108:111]
	v_mfma_f32_16x16x32_bf16 v[104:107], v[136:139], v[168:171], v[104:107]
	v_mfma_f32_16x16x32_bf16 v[92:95], v[128:131], v[196:199], v[92:95]
	v_mfma_f32_16x16x32_bf16 v[88:91], v[136:139], v[196:199], v[88:91]
	v_mfma_f32_16x16x32_bf16 v[76:79], v[128:131], v[206:209], v[76:79]
	v_mfma_f32_16x16x32_bf16 v[72:75], v[136:139], v[206:209], v[72:75]
	v_mfma_f32_16x16x32_bf16 v[124:127], v[132:135], v[164:167], v[124:127]
	v_mfma_f32_16x16x32_bf16 v[120:123], v[140:143], v[164:167], v[120:123]
	v_mfma_f32_16x16x32_bf16 v[108:111], v[132:135], v[172:175], v[108:111]
	v_mfma_f32_16x16x32_bf16 v[104:107], v[140:143], v[172:175], v[104:107]
	v_mfma_f32_16x16x32_bf16 v[92:95], v[132:135], v[202:205], v[92:95]
	v_mfma_f32_16x16x32_bf16 v[88:91], v[140:143], v[202:205], v[88:91]
	v_mfma_f32_16x16x32_bf16 v[76:79], v[132:135], v[232:235], v[76:79]
	v_mfma_f32_16x16x32_bf16 v[72:75], v[140:143], v[232:235], v[72:75]
	v_mfma_f32_16x16x32_bf16 v[116:119], v[144:147], v[160:163], v[116:119]
	v_mfma_f32_16x16x32_bf16 v[112:115], v[152:155], v[160:163], v[112:115]
	v_mfma_f32_16x16x32_bf16 v[100:103], v[144:147], v[168:171], v[100:103]
	v_mfma_f32_16x16x32_bf16 v[96:99], v[152:155], v[168:171], v[96:99]
	v_mfma_f32_16x16x32_bf16 v[84:87], v[144:147], v[196:199], v[84:87]
	v_mfma_f32_16x16x32_bf16 v[80:83], v[152:155], v[196:199], v[80:83]
	v_mfma_f32_16x16x32_bf16 v[68:71], v[144:147], v[206:209], v[68:71]
	v_mfma_f32_16x16x32_bf16 v[64:67], v[152:155], v[206:209], v[64:67]
	v_mfma_f32_16x16x32_bf16 v[116:119], v[148:151], v[164:167], v[116:119]
	v_mfma_f32_16x16x32_bf16 v[112:115], v[156:159], v[164:167], v[112:115]
	v_mfma_f32_16x16x32_bf16 v[100:103], v[148:151], v[172:175], v[100:103]
	v_mfma_f32_16x16x32_bf16 v[96:99], v[156:159], v[172:175], v[96:99]
	v_mfma_f32_16x16x32_bf16 v[84:87], v[148:151], v[202:205], v[84:87]
	v_mfma_f32_16x16x32_bf16 v[80:83], v[156:159], v[202:205], v[80:83]
	v_mfma_f32_16x16x32_bf16 v[68:71], v[148:151], v[232:235], v[68:71]
	v_mfma_f32_16x16x32_bf16 v[64:67], v[156:159], v[232:235], v[64:67]
	s_barrier
; #define PG8_STAGE(bufoff, gbase, voff) do { _Pragma("unroll") for (int _i = 0; _i < 2; ++_i) \
;         __builtin_amdgcn_global_load_lds((const unsigned*)((const char*)(gbase) + (voff)[_i]), (PG8_LAS unsigned*)(lds + (bufoff) + ldsw + _i * 8192), 16, 0, 0); } while (0)
; #define PG8_LDA(dst, b, h) do { _Pragma("unroll") for (int m = 0; m < 4; ++m) _Pragma("unroll") for (int k = 0; k < 2; ++k) dst[m][k] = *(const PG8_LAS bf16x8*)(lds + PG8_SA(b, h) + aoff + m * 2048 + k * 1024); } while (0)
; #define PG8_MMA(ai, bj, At, Bt) do { __builtin_amdgcn_s_setprio(1); _Pragma("unroll") for (int m = 0; m < 4; ++m) _Pragma("unroll") for (int n = 0; n < 2; ++n) _Pragma("unroll") for (int k = 0; k < 2; ++k) \
;         acc[ai][bj][m][n] = __builtin_amdgcn_mfma_f32_16x16x32_bf16(Bt[n][k], At[m][k], acc[ai][bj][m][n], 0, 0, 0); __builtin_amdgcn_s_setprio(0); } while (0)
; #define PG8_WAIT_V(n) asm volatile("s_waitcnt vmcnt(" #n ")" ::: "memory")
; #define PG8_WAIT_L(n) asm volatile("s_waitcnt lgkmcnt(" #n ")" ::: "memory")
; #define PG8_BAR __builtin_amdgcn_s_barrier()
; #define PG8_SCHED __builtin_amdgcn_sched_barrier(0)
; template <class Epi, class Sched, bool ALIGN_EPI = false, bool SP2 = false, bool DUAL = false>
; __device__ __forceinline__ void gemm_phase(PG8_LAS unsigned char* lds, const Gemm g, const Sched& S, const Epi& E) {
;     ...
;             PG8_LDA(At, 1, 1); PG8_STAGE(PG8_SB(1, 0), b3, voffB); PG8_STAGE(PG8_SB(1, 1), b3 + hstep, voffB); PG8_STAGE(PG8_SA(1, 0), a3, voffA);
;             PG8_WAIT_V(8); PG8_WAIT_L(0); PG8_BAR; PG8_MMA(1, 0, At, B0); PG8_MMA(1, 1, At, B1); PG8_BAR; PG8_SCHED;
;     ...
;         if constexpr (ALIGN_EPI) { if (wr == 0) PG8_BAR; }
	s_setprio 0
	s_add_i32 s16, s72, s26
	v_lshl_add_u64 v[222:223], v[222:223], 0, s[36:37]
	s_mov_b32 m0, s16
	ds_read_b128 v[160:163], v220 offset:49152
	ds_read_b128 v[164:167], v220 offset:50176
	ds_read_b128 v[168:171], v220 offset:51200
	ds_read_b128 v[172:175], v220 offset:52224
	ds_read_b128 v[196:199], v220 offset:53248
	ds_read_b128 v[202:205], v220 offset:54272
	ds_read_b128 v[206:209], v220 offset:55296
	ds_read_b128 v[232:235], v220 offset:56320
	global_load_lds_dwordx4 v[222:223], off
	s_add_i32 m0, s16, 0x2000
	s_add_u32 s14, s14, 0x80080
	v_lshl_add_u64 v[222:223], v[228:229], 0, s[36:37]
	s_addc_u32 s15, s15, 0
	s_add_i32 s16, s73, s26
	global_load_lds_dwordx4 v[222:223], off
	v_lshl_add_u64 v[222:223], s[14:15], 0, v[182:183]
	s_mov_b32 m0, s16
	s_nop 0
	global_load_lds_dwordx4 v[222:223], off
	v_lshl_add_u64 v[222:223], s[14:15], 0, v[186:187]
	s_add_i32 m0, s16, 0x2000
	s_nop 0
	global_load_lds_dwordx4 v[222:223], off
	v_lshl_add_u64 v[222:223], v[236:237], 0, s[36:37]
	s_mov_b32 m0, s44
	s_nop 0
	global_load_lds_dwordx4 v[222:223], off
	v_lshl_add_u64 v[222:223], v[238:239], 0, s[36:37]
	s_mov_b32 m0, s45
	s_nop 0
	global_load_lds_dwordx4 v[222:223], off
	s_waitcnt vmcnt(8)
	s_waitcnt lgkmcnt(0)
	s_setprio 1
	s_barrier
	v_mfma_f32_16x16x32_bf16 v[60:63], v[128:131], v[160:163], v[60:63]
	v_mfma_f32_16x16x32_bf16 v[56:59], v[136:139], v[160:163], v[56:59]
	v_mfma_f32_16x16x32_bf16 v[44:47], v[128:131], v[168:171], v[44:47]
	v_mfma_f32_16x16x32_bf16 v[40:43], v[136:139], v[168:171], v[40:43]
	v_mfma_f32_16x16x32_bf16 v[28:31], v[128:131], v[196:199], v[28:31]
	v_mfma_f32_16x16x32_bf16 v[24:27], v[136:139], v[196:199], v[24:27]
	v_mfma_f32_16x16x32_bf16 v[12:15], v[128:131], v[206:209], v[12:15]
	v_mfma_f32_16x16x32_bf16 v[8:11], v[136:139], v[206:209], v[8:11]
	v_mfma_f32_16x16x32_bf16 v[60:63], v[132:135], v[164:167], v[60:63]
	v_mfma_f32_16x16x32_bf16 v[56:59], v[140:143], v[164:167], v[56:59]
	v_mfma_f32_16x16x32_bf16 v[44:47], v[132:135], v[172:175], v[44:47]
	v_mfma_f32_16x16x32_bf16 v[40:43], v[140:143], v[172:175], v[40:43]
	v_mfma_f32_16x16x32_bf16 v[28:31], v[132:135], v[202:205], v[28:31]
	v_mfma_f32_16x16x32_bf16 v[24:27], v[140:143], v[202:205], v[24:27]
	v_mfma_f32_16x16x32_bf16 v[12:15], v[132:135], v[232:235], v[12:15]
	v_mfma_f32_16x16x32_bf16 v[8:11], v[140:143], v[232:235], v[8:11]
	v_mfma_f32_16x16x32_bf16 v[52:55], v[144:147], v[160:163], v[52:55]
	v_mfma_f32_16x16x32_bf16 v[48:51], v[152:155], v[160:163], v[48:51]
	v_mfma_f32_16x16x32_bf16 v[36:39], v[144:147], v[168:171], v[36:39]
	v_mfma_f32_16x16x32_bf16 v[32:35], v[152:155], v[168:171], v[32:35]
	v_mfma_f32_16x16x32_bf16 v[20:23], v[144:147], v[196:199], v[20:23]
	v_mfma_f32_16x16x32_bf16 v[16:19], v[152:155], v[196:199], v[16:19]
	v_mfma_f32_16x16x32_bf16 v[4:7], v[144:147], v[206:209], v[4:7]
	v_mfma_f32_16x16x32_bf16 v[0:3], v[152:155], v[206:209], v[0:3]
	v_mfma_f32_16x16x32_bf16 v[52:55], v[148:151], v[164:167], v[52:55]
	v_mfma_f32_16x16x32_bf16 v[48:51], v[156:159], v[164:167], v[48:51]
	v_mfma_f32_16x16x32_bf16 v[36:39], v[148:151], v[172:175], v[36:39]
	v_mfma_f32_16x16x32_bf16 v[32:35], v[156:159], v[172:175], v[32:35]
	v_mfma_f32_16x16x32_bf16 v[20:23], v[148:151], v[202:205], v[20:23]
	v_mfma_f32_16x16x32_bf16 v[16:19], v[156:159], v[202:205], v[16:19]
	v_mfma_f32_16x16x32_bf16 v[4:7], v[148:151], v[232:235], v[4:7]
	v_mfma_f32_16x16x32_bf16 v[0:3], v[156:159], v[232:235], v[0:3]
	s_barrier
	s_setprio 0
	s_add_i32 s71, s71, 2
	s_add_u32 s68, s68, 0x100
	s_addc_u32 s69, s69, 0
	s_add_u32 s67, s67, 0x100
	s_addc_u32 s70, s70, 0
	s_cmp_gt_u32 s71, 29
	s_cbranch_scc0 .LBB0_896
	s_and_b64 vcc, exec, s[38:39]
	s_cbranch_vccz .LBB0_899
	s_barrier

; #define PG8_STAGE(bufoff, gbase, voff) do { _Pragma("unroll") for (int _i = 0; _i < 2; ++_i) \
;         __builtin_amdgcn_global_load_lds((const unsigned*)((const char*)(gbase) + (voff)[_i]), (PG8_LAS unsigned*)(lds + (bufoff) + ldsw + _i * 8192), 16, 0, 0); } while (0)
; #define PG8_LDA(dst, b, h) do { _Pragma("unroll") for (int m = 0; m < 4; ++m) _Pragma("unroll") for (int k = 0; k < 2; ++k) dst[m][k] = *(const PG8_LAS bf16x8*)(lds + PG8_SA(b, h) + aoff + m * 2048 + k * 1024); } while (0)
; #define PG8_LDB(dst, b, h) do { _Pragma("unroll") for (int n = 0; n < 2; ++n) _Pragma("unroll") for (int k = 0; k < 2; ++k) dst[n][k] = *(const PG8_LAS bf16x8*)(lds + PG8_SB(b, h) + boff + n * 2048 + k * 1024); } while (0)
; #define PG8_WAIT_V(n) asm volatile("s_waitcnt vmcnt(" #n ")" ::: "memory")
; #define PG8_WAIT_L(n) asm volatile("s_waitcnt lgkmcnt(" #n ")" ::: "memory")
; #define PG8_BAR __builtin_amdgcn_s_barrier()
; #define PG8_SCHED __builtin_amdgcn_sched_barrier(0)
; template <class Epi, class Sched, bool ALIGN_EPI = false, bool SP2 = false, bool DUAL = false>
; __device__ __forceinline__ void gemm_phase(PG8_LAS unsigned char* lds, const Gemm g, const Sched& S, const Epi& E) {
;     ...
;         const char* nA = has_next ? (const char*)((DUAL && nxt.sub) ? g.A2 : g.A) + (size_t)nxt.pm * tstep : cA; const char* nB = has_next ? (const char*)((DUAL && nxt.sub) ? g.Bt2 : g.Bt) + (size_t)nxt.pn * tstep : cB;
;         for (int t = 0; t < nt; t += 2) {
;             const bool last = (t == nt - 2);
;             const char* a1 = cA + (size_t)(t + 1) * kstep;
;             const char* a2 = last ? nA : cA + (size_t)(t + 2) * kstep; const char* b2 = last ? nB : cB + (size_t)(t + 2) * kstep;
;             const char* a3 = a2 + kstep; const char* b3 = b2 + kstep;
;             if (last && has_next) S.a_ready(nxt);
;             if constexpr (SP2) {
;             PG8_LDB(B0, 0, 0); PG8_LDB(B1, 0, 1); PG8_SCHED; PG8_LDA(At, 0, 0); PG8_STAGE(PG8_SA(1, 1), a1 + hstep, voffA);
;             PG8_WAIT_V(8); PG8_WAIT_L(0); PG8_BAR; PG8_MMA(0, 0, At, B0); PG8_MMA(0, 1, At, B1); PG8_BAR; PG8_SCHED;
;             PG8_LDA(At, 0, 1); PG8_STAGE(PG8_SB(0, 0), b2, voffB); PG8_STAGE(PG8_SB(0, 1), b2 + hstep, voffB); PG8_STAGE(PG8_SA(0, 0), a2, voffA);
;             PG8_WAIT_V(8); PG8_WAIT_L(0); PG8_BAR; PG8_MMA(1, 0, At, B0); PG8_MMA(1, 1, At, B1); PG8_BAR; PG8_SCHED;
.LBB0_991:
	s_ashr_i32 s25, s24, 31
	s_lshl_b64 s[28:29], s[24:25], 20
	s_add_u32 s30, s19, s28
	s_addc_u32 s31, s21, s29
	s_and_b64 s[28:29], s[4:5], exec
	s_cselect_b32 s25, s31, s27
	s_cselect_b32 s28, s30, s26
	s_ashr_i32 s23, s22, 31
	s_lshl_b64 s[36:37], s[22:23], 20
	s_add_u32 s36, s8, s36
	s_addc_u32 s37, s9, s37
	s_and_b64 s[40:41], s[4:5], exec
	s_cselect_b32 s23, s37, s15
	s_cselect_b32 s29, s36, s14
	s_add_u32 s40, s26, 0x80080
	s_addc_u32 s41, s27, 0
	s_add_u32 s63, s14, 0x100
	s_addc_u32 s64, s15, 0
	s_mov_b32 s65, -2
	ds_read_b128 v[128:131], v215
	ds_read_b128 v[132:135], v215 offset:1024
	ds_read_b128 v[136:139], v215 offset:2048
	ds_read_b128 v[140:143], v215 offset:3072
	ds_read_b128 v[144:147], v216
	ds_read_b128 v[148:151], v216 offset:1024
	ds_read_b128 v[152:155], v216 offset:2048
	ds_read_b128 v[156:159], v216 offset:3072
	s_add_u32 s14, s40, 0xfff80080
	s_addc_u32 s15, s41, -1
	s_cmp_eq_u32 s65, 28
	s_cselect_b32 s27, s25, s15
	s_cselect_b32 s26, s28, s14
	s_cselect_b32 s15, s23, s64
	s_cselect_b32 s14, s29, s63
	v_lshl_add_u64 v[228:229], s[40:41], 0, v[180:181]
	s_add_i32 m0, s39, 0xc000
	ds_read_b128 v[160:163], v217
	ds_read_b128 v[164:167], v217 offset:1024
	ds_read_b128 v[188:191], v217 offset:2048
	ds_read_b128 v[192:195], v217 offset:3072
	ds_read_b128 v[196:199], v217 offset:4096
	ds_read_b128 v[202:205], v217 offset:5120
	ds_read_b128 v[206:209], v217 offset:6144
	ds_read_b128 v[220:223], v217 offset:7168
	global_load_lds_dwordx4 v[228:229], off
	v_lshl_add_u64 v[228:229], s[40:41], 0, v[182:183]
	s_add_i32 m0, s39, 0xe000
	s_nop 0
	global_load_lds_dwordx4 v[228:229], off
	s_waitcnt vmcnt(8)
	s_waitcnt lgkmcnt(0)
	s_setprio 1
	s_barrier
	v_mfma_f32_16x16x32_bf16 v[124:127], v[128:131], v[160:163], 0
	v_mfma_f32_16x16x32_bf16 v[120:123], v[136:139], v[160:163], 0
	v_mfma_f32_16x16x32_bf16 v[108:111], v[128:131], v[188:191], 0
	v_mfma_f32_16x16x32_bf16 v[104:107], v[136:139], v[188:191], 0
	v_mfma_f32_16x16x32_bf16 v[92:95], v[128:131], v[196:199], 0
	v_mfma_f32_16x16x32_bf16 v[88:91], v[136:139], v[196:199], 0
	v_mfma_f32_16x16x32_bf16 v[76:79], v[128:131], v[206:209], 0
	v_mfma_f32_16x16x32_bf16 v[72:75], v[136:139], v[206:209], 0
	v_mfma_f32_16x16x32_bf16 v[124:127], v[132:135], v[164:167], v[124:127]
	v_mfma_f32_16x16x32_bf16 v[120:123], v[140:143], v[164:167], v[120:123]
	v_mfma_f32_16x16x32_bf16 v[108:111], v[132:135], v[192:195], v[108:111]
	v_mfma_f32_16x16x32_bf16 v[104:107], v[140:143], v[192:195], v[104:107]
	v_mfma_f32_16x16x32_bf16 v[92:95], v[132:135], v[202:205], v[92:95]
	v_mfma_f32_16x16x32_bf16 v[88:91], v[140:143], v[202:205], v[88:91]
	v_mfma_f32_16x16x32_bf16 v[76:79], v[132:135], v[220:223], v[76:79]
	v_mfma_f32_16x16x32_bf16 v[72:75], v[140:143], v[220:223], v[72:75]
	v_mfma_f32_16x16x32_bf16 v[116:119], v[144:147], v[160:163], 0
	v_mfma_f32_16x16x32_bf16 v[112:115], v[152:155], v[160:163], 0
	v_mfma_f32_16x16x32_bf16 v[100:103], v[144:147], v[188:191], 0
	v_mfma_f32_16x16x32_bf16 v[96:99], v[152:155], v[188:191], 0
	v_mfma_f32_16x16x32_bf16 v[84:87], v[144:147], v[196:199], 0
	v_mfma_f32_16x16x32_bf16 v[80:83], v[152:155], v[196:199], 0
	v_mfma_f32_16x16x32_bf16 v[68:71], v[144:147], v[206:209], 0
	v_mfma_f32_16x16x32_bf16 v[64:67], v[152:155], v[206:209], 0
	v_mfma_f32_16x16x32_bf16 v[116:119], v[148:151], v[164:167], v[116:119]
	v_mfma_f32_16x16x32_bf16 v[112:115], v[156:159], v[164:167], v[112:115]
	v_mfma_f32_16x16x32_bf16 v[100:103], v[148:151], v[192:195], v[100:103]
	v_mfma_f32_16x16x32_bf16 v[96:99], v[156:159], v[192:195], v[96:99]
	v_mfma_f32_16x16x32_bf16 v[84:87], v[148:151], v[202:205], v[84:87]
	v_mfma_f32_16x16x32_bf16 v[80:83], v[156:159], v[202:205], v[80:83]
	v_mfma_f32_16x16x32_bf16 v[68:71], v[148:151], v[220:223], v[68:71]
	v_mfma_f32_16x16x32_bf16 v[64:67], v[156:159], v[220:223], v[64:67]
	s_barrier
	s_setprio 0
	s_add_i32 s66, s50, s34
	v_lshl_add_u64 v[228:229], s[14:15], 0, v[170:171]
	s_mov_b32 m0, s66
	ds_read_b128 v[160:163], v217 offset:16384
	ds_read_b128 v[164:167], v217 offset:17408
	ds_read_b128 v[188:191], v217 offset:18432
	ds_read_b128 v[192:195], v217 offset:19456
	ds_read_b128 v[196:199], v217 offset:20480
	ds_read_b128 v[202:205], v217 offset:21504
	ds_read_b128 v[206:209], v217 offset:22528
	ds_read_b128 v[220:223], v217 offset:23552
	global_load_lds_dwordx4 v[228:229], off
	s_add_i32 m0, s66, 0x2000
	s_add_u32 s66, s14, 0x80000
	v_lshl_add_u64 v[232:233], s[14:15], 0, v[174:175]
	s_addc_u32 s67, s15, 0
	s_add_i32 s68, s51, s34
	global_load_lds_dwordx4 v[232:233], off
	v_lshl_add_u64 v[234:235], s[66:67], 0, v[170:171]
	s_mov_b32 m0, s68
	v_lshl_add_u64 v[236:237], s[26:27], 0, v[172:173]
	global_load_lds_dwordx4 v[234:235], off
	v_lshl_add_u64 v[234:235], s[66:67], 0, v[174:175]
	s_add_i32 m0, s68, 0x2000
	s_nop 0
	global_load_lds_dwordx4 v[234:235], off
	v_lshl_add_u64 v[234:235], s[26:27], 0, v[168:169]
	s_mov_b32 m0, s39
	s_nop 0
	global_load_lds_dwordx4 v[234:235], off
	s_mov_b32 m0, s42
	s_nop 0
	global_load_lds_dwordx4 v[236:237], off
	s_waitcnt vmcnt(8)
	s_waitcnt lgkmcnt(0)
	s_setprio 1
	s_barrier
; #define PG8_STAGE(bufoff, gbase, voff) do { _Pragma("unroll") for (int _i = 0; _i < 2; ++_i) \
;         __builtin_amdgcn_global_load_lds((const unsigned*)((const char*)(gbase) + (voff)[_i]), (PG8_LAS unsigned*)(lds + (bufoff) + ldsw + _i * 8192), 16, 0, 0); } while (0)
; #define PG8_LDA(dst, b, h) do { _Pragma("unroll") for (int m = 0; m < 4; ++m) _Pragma("unroll") for (int k = 0; k < 2; ++k) dst[m][k] = *(const PG8_LAS bf16x8*)(lds + PG8_SA(b, h) + aoff + m * 2048 + k * 1024); } while (0)
; #define PG8_LDB(dst, b, h) do { _Pragma("unroll") for (int n = 0; n < 2; ++n) _Pragma("unroll") for (int k = 0; k < 2; ++k) dst[n][k] = *(const PG8_LAS bf16x8*)(lds + PG8_SB(b, h) + boff + n * 2048 + k * 1024); } while (0)
; #define PG8_MMA(ai, bj, At, Bt) do { __builtin_amdgcn_s_setprio(1); _Pragma("unroll") for (int m = 0; m < 4; ++m) _Pragma("unroll") for (int n = 0; n < 2; ++n) _Pragma("unroll") for (int k = 0; k < 2; ++k) \
;         acc[ai][bj][m][n] = __builtin_amdgcn_mfma_f32_16x16x32_bf16(Bt[n][k], At[m][k], acc[ai][bj][m][n], 0, 0, 0); __builtin_amdgcn_s_setprio(0); } while (0)
; #define PG8_WAIT_V(n) asm volatile("s_waitcnt vmcnt(" #n ")" ::: "memory")
; #define PG8_WAIT_L(n) asm volatile("s_waitcnt lgkmcnt(" #n ")" ::: "memory")
; #define PG8_BAR __builtin_amdgcn_s_barrier()
; #define PG8_SCHED __builtin_amdgcn_sched_barrier(0)
; template <class Epi, class Sched, bool ALIGN_EPI = false, bool SP2 = false, bool DUAL = false>
; __device__ __forceinline__ void gemm_phase(PG8_LAS unsigned char* lds, const Gemm g, const Sched& S, const Epi& E) {
;     ...
;             PG8_WAIT_V(8); PG8_WAIT_L(0); PG8_BAR; PG8_MMA(1, 0, At, B0); PG8_MMA(1, 1, At, B1); PG8_BAR; PG8_SCHED;
;             PG8_LDB(B0, 1, 0); PG8_LDB(B1, 1, 1); PG8_SCHED; PG8_LDA(At, 1, 0); PG8_STAGE(PG8_SA(0, 1), a2 + hstep, voffA);
;             PG8_WAIT_V(8); PG8_WAIT_L(0); PG8_BAR; PG8_MMA(0, 0, At, B0); PG8_MMA(0, 1, At, B1); PG8_BAR; PG8_SCHED;
	v_mfma_f32_16x16x32_bf16 v[60:63], v[128:131], v[160:163], 0
	v_mfma_f32_16x16x32_bf16 v[56:59], v[136:139], v[160:163], 0
	v_mfma_f32_16x16x32_bf16 v[44:47], v[128:131], v[188:191], 0
	v_mfma_f32_16x16x32_bf16 v[40:43], v[136:139], v[188:191], 0
	v_mfma_f32_16x16x32_bf16 v[28:31], v[128:131], v[196:199], 0
	v_mfma_f32_16x16x32_bf16 v[24:27], v[136:139], v[196:199], 0
	v_mfma_f32_16x16x32_bf16 v[12:15], v[128:131], v[206:209], 0
	v_mfma_f32_16x16x32_bf16 v[8:11], v[136:139], v[206:209], 0
	v_mfma_f32_16x16x32_bf16 v[60:63], v[132:135], v[164:167], v[60:63]
	v_mfma_f32_16x16x32_bf16 v[56:59], v[140:143], v[164:167], v[56:59]
	v_mfma_f32_16x16x32_bf16 v[44:47], v[132:135], v[192:195], v[44:47]
	v_mfma_f32_16x16x32_bf16 v[40:43], v[140:143], v[192:195], v[40:43]
	v_mfma_f32_16x16x32_bf16 v[28:31], v[132:135], v[202:205], v[28:31]
	v_mfma_f32_16x16x32_bf16 v[24:27], v[140:143], v[202:205], v[24:27]
	v_mfma_f32_16x16x32_bf16 v[12:15], v[132:135], v[220:223], v[12:15]
	v_mfma_f32_16x16x32_bf16 v[8:11], v[140:143], v[220:223], v[8:11]
	v_mfma_f32_16x16x32_bf16 v[52:55], v[144:147], v[160:163], 0
	v_mfma_f32_16x16x32_bf16 v[48:51], v[152:155], v[160:163], 0
	v_mfma_f32_16x16x32_bf16 v[36:39], v[144:147], v[188:191], 0
	v_mfma_f32_16x16x32_bf16 v[32:35], v[152:155], v[188:191], 0
	v_mfma_f32_16x16x32_bf16 v[20:23], v[144:147], v[196:199], 0
	v_mfma_f32_16x16x32_bf16 v[16:19], v[152:155], v[196:199], 0
	v_mfma_f32_16x16x32_bf16 v[4:7], v[144:147], v[206:209], 0
	v_mfma_f32_16x16x32_bf16 v[0:3], v[152:155], v[206:209], 0
	v_mfma_f32_16x16x32_bf16 v[52:55], v[148:151], v[164:167], v[52:55]
	v_mfma_f32_16x16x32_bf16 v[48:51], v[156:159], v[164:167], v[48:51]
	v_mfma_f32_16x16x32_bf16 v[36:39], v[148:151], v[192:195], v[36:39]
	v_mfma_f32_16x16x32_bf16 v[32:35], v[156:159], v[192:195], v[32:35]
	v_mfma_f32_16x16x32_bf16 v[20:23], v[148:151], v[202:205], v[20:23]
	v_mfma_f32_16x16x32_bf16 v[16:19], v[156:159], v[202:205], v[16:19]
	v_mfma_f32_16x16x32_bf16 v[4:7], v[148:151], v[220:223], v[4:7]
	v_mfma_f32_16x16x32_bf16 v[0:3], v[156:159], v[220:223], v[0:3]
	s_barrier
	s_setprio 0
	s_add_i32 s66, 0, 0x18000
	s_add_i32 s67, 0, 0x1c000
	v_add_u32_e32 v140, s66, v213
	v_add_u32_e32 v156, s67, v213
	ds_read_b128 v[128:131], v140
	ds_read_b128 v[132:135], v140 offset:1024
	ds_read_b128 v[136:139], v140 offset:2048
	ds_read_b128 v[140:143], v140 offset:3072
	ds_read_b128 v[144:147], v156
	ds_read_b128 v[148:151], v156 offset:1024
	ds_read_b128 v[152:155], v156 offset:2048
	ds_read_b128 v[156:159], v156 offset:3072
	s_add_u32 s26, s26, 0x80000
	s_addc_u32 s27, s27, 0
	s_mov_b32 m0, s43
	v_lshl_add_u64 v[238:239], s[26:27], 0, v[168:169]
	ds_read_b128 v[160:163], v217 offset:32768
	ds_read_b128 v[164:167], v217 offset:33792
	ds_read_b128 v[188:191], v217 offset:34816
	ds_read_b128 v[192:195], v217 offset:35840
	ds_read_b128 v[196:199], v217 offset:36864
	ds_read_b128 v[202:205], v217 offset:37888
	ds_read_b128 v[206:209], v217 offset:38912
	ds_read_b128 v[220:223], v217 offset:39936
	global_load_lds_dwordx4 v[238:239], off
	v_lshl_add_u64 v[238:239], s[26:27], 0, v[172:173]
	s_mov_b32 m0, s44
	s_nop 0
	global_load_lds_dwordx4 v[238:239], off
	s_waitcnt vmcnt(8)
	s_waitcnt lgkmcnt(0)
	s_setprio 1
	s_barrier
	v_mfma_f32_16x16x32_bf16 v[124:127], v[128:131], v[160:163], v[124:127]
	v_mfma_f32_16x16x32_bf16 v[120:123], v[136:139], v[160:163], v[120:123]
	v_mfma_f32_16x16x32_bf16 v[108:111], v[128:131], v[188:191], v[108:111]
	v_mfma_f32_16x16x32_bf16 v[104:107], v[136:139], v[188:191], v[104:107]
	v_mfma_f32_16x16x32_bf16 v[92:95], v[128:131], v[196:199], v[92:95]
	v_mfma_f32_16x16x32_bf16 v[88:91], v[136:139], v[196:199], v[88:91]
	v_mfma_f32_16x16x32_bf16 v[76:79], v[128:131], v[206:209], v[76:79]
	v_mfma_f32_16x16x32_bf16 v[72:75], v[136:139], v[206:209], v[72:75]
	v_mfma_f32_16x16x32_bf16 v[124:127], v[132:135], v[164:167], v[124:127]
	v_mfma_f32_16x16x32_bf16 v[120:123], v[140:143], v[164:167], v[120:123]
	v_mfma_f32_16x16x32_bf16 v[108:111], v[132:135], v[192:195], v[108:111]
	v_mfma_f32_16x16x32_bf16 v[104:107], v[140:143], v[192:195], v[104:107]
	v_mfma_f32_16x16x32_bf16 v[92:95], v[132:135], v[202:205], v[92:95]
	v_mfma_f32_16x16x32_bf16 v[88:91], v[140:143], v[202:205], v[88:91]
	v_mfma_f32_16x16x32_bf16 v[76:79], v[132:135], v[220:223], v[76:79]
	v_mfma_f32_16x16x32_bf16 v[72:75], v[140:143], v[220:223], v[72:75]
	v_mfma_f32_16x16x32_bf16 v[116:119], v[144:147], v[160:163], v[116:119]
	v_mfma_f32_16x16x32_bf16 v[112:115], v[152:155], v[160:163], v[112:115]
	v_mfma_f32_16x16x32_bf16 v[100:103], v[144:147], v[188:191], v[100:103]
	v_mfma_f32_16x16x32_bf16 v[96:99], v[152:155], v[188:191], v[96:99]
	v_mfma_f32_16x16x32_bf16 v[84:87], v[144:147], v[196:199], v[84:87]
	v_mfma_f32_16x16x32_bf16 v[80:83], v[152:155], v[196:199], v[80:83]
	v_mfma_f32_16x16x32_bf16 v[68:71], v[144:147], v[206:209], v[68:71]
	v_mfma_f32_16x16x32_bf16 v[64:67], v[152:155], v[206:209], v[64:67]
	v_mfma_f32_16x16x32_bf16 v[116:119], v[148:151], v[164:167], v[116:119]
	v_mfma_f32_16x16x32_bf16 v[112:115], v[156:159], v[164:167], v[112:115]
	v_mfma_f32_16x16x32_bf16 v[100:103], v[148:151], v[192:195], v[100:103]
	v_mfma_f32_16x16x32_bf16 v[96:99], v[156:159], v[192:195], v[96:99]
	v_mfma_f32_16x16x32_bf16 v[84:87], v[148:151], v[202:205], v[84:87]
	v_mfma_f32_16x16x32_bf16 v[80:83], v[156:159], v[202:205], v[80:83]
	v_mfma_f32_16x16x32_bf16 v[68:71], v[148:151], v[220:223], v[68:71]
	v_mfma_f32_16x16x32_bf16 v[64:67], v[156:159], v[220:223], v[64:67]
	s_barrier
; #define PG8_STAGE(bufoff, gbase, voff) do { _Pragma("unroll") for (int _i = 0; _i < 2; ++_i) \
;         __builtin_amdgcn_global_load_lds((const unsigned*)((const char*)(gbase) + (voff)[_i]), (PG8_LAS unsigned*)(lds + (bufoff) + ldsw + _i * 8192), 16, 0, 0); } while (0)
; #define PG8_LDA(dst, b, h) do { _Pragma("unroll") for (int m = 0; m < 4; ++m) _Pragma("unroll") for (int k = 0; k < 2; ++k) dst[m][k] = *(const PG8_LAS bf16x8*)(lds + PG8_SA(b, h) + aoff + m * 2048 + k * 1024); } while (0)
; #define PG8_LDB(dst, b, h) do { _Pragma("unroll") for (int n = 0; n < 2; ++n) _Pragma("unroll") for (int k = 0; k < 2; ++k) dst[n][k] = *(const PG8_LAS bf16x8*)(lds + PG8_SB(b, h) + boff + n * 2048 + k * 1024); } while (0)
; #define PG8_MMA(ai, bj, At, Bt) do { __builtin_amdgcn_s_setprio(1); _Pragma("unroll") for (int m = 0; m < 4; ++m) _Pragma("unroll") for (int n = 0; n < 2; ++n) _Pragma("unroll") for (int k = 0; k < 2; ++k) \
;         acc[ai][bj][m][n] = __builtin_amdgcn_mfma_f32_16x16x32_bf16(Bt[n][k], At[m][k], acc[ai][bj][m][n], 0, 0, 0); __builtin_amdgcn_s_setprio(0); } while (0)
; #define PG8_WAIT_V(n) asm volatile("s_waitcnt vmcnt(" #n ")" ::: "memory")
; #define PG8_WAIT_L(n) asm volatile("s_waitcnt lgkmcnt(" #n ")" ::: "memory")
; #define PG8_BAR __builtin_amdgcn_s_barrier()
; #define PG8_SCHED __builtin_amdgcn_sched_barrier(0)
; template <class Epi, class Sched, bool ALIGN_EPI = false, bool SP2 = false, bool DUAL = false>
; __device__ __forceinline__ void gemm_phase(PG8_LAS unsigned char* lds, const Gemm g, const Sched& S, const Epi& E) {
;     ...
;             PG8_LDB(B0, 0, 0); PG8_LDB(B1, 0, 1); PG8_SCHED; PG8_LDA(At, 0, 0); PG8_STAGE(PG8_SA(1, 1), a1 + hstep, voffA);
;             PG8_WAIT_V(8); PG8_WAIT_L(0); PG8_BAR; PG8_MMA(0, 0, At, B0); PG8_MMA(0, 1, At, B1); PG8_BAR; PG8_SCHED;
;     ...
;             PG8_LDA(At, 1, 1); PG8_STAGE(PG8_SB(1, 0), b3, voffB); PG8_STAGE(PG8_SB(1, 1), b3 + hstep, voffB); PG8_STAGE(PG8_SA(1, 0), a3, voffA);
;             PG8_WAIT_V(8); PG8_WAIT_L(0); PG8_BAR; PG8_MMA(1, 0, At, B0); PG8_MMA(1, 1, At, B1); PG8_BAR; PG8_SCHED;
	s_setprio 0
	s_add_i32 s26, s66, s34
	v_lshl_add_u64 v[228:229], v[228:229], 0, s[12:13]
	s_mov_b32 m0, s26
	ds_read_b128 v[160:163], v217 offset:49152
	ds_read_b128 v[164:167], v217 offset:50176
	ds_read_b128 v[188:191], v217 offset:51200
	ds_read_b128 v[192:195], v217 offset:52224
	ds_read_b128 v[196:199], v217 offset:53248
	ds_read_b128 v[202:205], v217 offset:54272
	ds_read_b128 v[206:209], v217 offset:55296
	ds_read_b128 v[220:223], v217 offset:56320
	global_load_lds_dwordx4 v[228:229], off
	s_add_i32 m0, s26, 0x2000
	s_add_u32 s14, s14, 0x80080
	v_lshl_add_u64 v[228:229], v[232:233], 0, s[12:13]
	s_addc_u32 s15, s15, 0
	s_add_i32 s26, s67, s34
	global_load_lds_dwordx4 v[228:229], off
	v_lshl_add_u64 v[228:229], s[14:15], 0, v[170:171]
	s_mov_b32 m0, s26
	s_nop 0
	global_load_lds_dwordx4 v[228:229], off
	v_lshl_add_u64 v[228:229], s[14:15], 0, v[174:175]
	s_add_i32 m0, s26, 0x2000
	s_nop 0
	global_load_lds_dwordx4 v[228:229], off
	v_lshl_add_u64 v[228:229], v[234:235], 0, s[12:13]
	s_mov_b32 m0, s47
	s_nop 0
	global_load_lds_dwordx4 v[228:229], off
	v_lshl_add_u64 v[228:229], v[236:237], 0, s[12:13]
	s_mov_b32 m0, s48
	s_nop 0
	global_load_lds_dwordx4 v[228:229], off
	s_waitcnt vmcnt(8)
	s_waitcnt lgkmcnt(0)
	s_setprio 1
	s_barrier
	v_mfma_f32_16x16x32_bf16 v[60:63], v[128:131], v[160:163], v[60:63]
	v_mfma_f32_16x16x32_bf16 v[56:59], v[136:139], v[160:163], v[56:59]
	v_mfma_f32_16x16x32_bf16 v[44:47], v[128:131], v[188:191], v[44:47]
	v_mfma_f32_16x16x32_bf16 v[40:43], v[136:139], v[188:191], v[40:43]
	v_mfma_f32_16x16x32_bf16 v[28:31], v[128:131], v[196:199], v[28:31]
	v_mfma_f32_16x16x32_bf16 v[24:27], v[136:139], v[196:199], v[24:27]
	v_mfma_f32_16x16x32_bf16 v[12:15], v[128:131], v[206:209], v[12:15]
	v_mfma_f32_16x16x32_bf16 v[8:11], v[136:139], v[206:209], v[8:11]
	v_mfma_f32_16x16x32_bf16 v[60:63], v[132:135], v[164:167], v[60:63]
	v_mfma_f32_16x16x32_bf16 v[56:59], v[140:143], v[164:167], v[56:59]
	v_mfma_f32_16x16x32_bf16 v[44:47], v[132:135], v[192:195], v[44:47]
	v_mfma_f32_16x16x32_bf16 v[40:43], v[140:143], v[192:195], v[40:43]
	v_mfma_f32_16x16x32_bf16 v[28:31], v[132:135], v[202:205], v[28:31]
	v_mfma_f32_16x16x32_bf16 v[24:27], v[140:143], v[202:205], v[24:27]
	v_mfma_f32_16x16x32_bf16 v[12:15], v[132:135], v[220:223], v[12:15]
	v_mfma_f32_16x16x32_bf16 v[8:11], v[140:143], v[220:223], v[8:11]
	v_mfma_f32_16x16x32_bf16 v[52:55], v[144:147], v[160:163], v[52:55]
	v_mfma_f32_16x16x32_bf16 v[48:51], v[152:155], v[160:163], v[48:51]
	v_mfma_f32_16x16x32_bf16 v[36:39], v[144:147], v[188:191], v[36:39]
	v_mfma_f32_16x16x32_bf16 v[32:35], v[152:155], v[188:191], v[32:35]
	v_mfma_f32_16x16x32_bf16 v[20:23], v[144:147], v[196:199], v[20:23]
	v_mfma_f32_16x16x32_bf16 v[16:19], v[152:155], v[196:199], v[16:19]
	v_mfma_f32_16x16x32_bf16 v[4:7], v[144:147], v[206:209], v[4:7]
	v_mfma_f32_16x16x32_bf16 v[0:3], v[152:155], v[206:209], v[0:3]
	v_mfma_f32_16x16x32_bf16 v[52:55], v[148:151], v[164:167], v[52:55]
	v_mfma_f32_16x16x32_bf16 v[48:51], v[156:159], v[164:167], v[48:51]
	v_mfma_f32_16x16x32_bf16 v[36:39], v[148:151], v[192:195], v[36:39]
	v_mfma_f32_16x16x32_bf16 v[32:35], v[156:159], v[192:195], v[32:35]
	v_mfma_f32_16x16x32_bf16 v[20:23], v[148:151], v[202:205], v[20:23]
	v_mfma_f32_16x16x32_bf16 v[16:19], v[156:159], v[202:205], v[16:19]
	v_mfma_f32_16x16x32_bf16 v[4:7], v[148:151], v[220:223], v[4:7]
	v_mfma_f32_16x16x32_bf16 v[0:3], v[156:159], v[220:223], v[0:3]
	s_barrier
	s_setprio 0
	s_add_i32 s65, s65, 2
	s_add_u32 s40, s40, 0x100
	s_addc_u32 s41, s41, 0
	s_add_u32 s63, s63, 0x100
	s_addc_u32 s64, s64, 0
.LBB0_992:
	ds_read_b128 v[128:131], v215
	ds_read_b128 v[132:135], v215 offset:1024
	ds_read_b128 v[136:139], v215 offset:2048
	ds_read_b128 v[140:143], v215 offset:3072
	ds_read_b128 v[144:147], v216
	ds_read_b128 v[148:151], v216 offset:1024
	ds_read_b128 v[152:155], v216 offset:2048
	ds_read_b128 v[156:159], v216 offset:3072
	s_add_u32 s14, s40, 0xfff80080
	s_addc_u32 s15, s41, -1
	s_cmp_eq_u32 s65, 28
	s_cselect_b32 s27, s25, s15
	s_cselect_b32 s26, s28, s14
	s_cselect_b32 s15, s23, s64
	s_cselect_b32 s14, s29, s63
	v_lshl_add_u64 v[228:229], s[40:41], 0, v[180:181]
	s_add_i32 m0, s39, 0xc000
	ds_read_b128 v[160:163], v217
	ds_read_b128 v[164:167], v217 offset:1024
	ds_read_b128 v[188:191], v217 offset:2048
	ds_read_b128 v[192:195], v217 offset:3072
	ds_read_b128 v[196:199], v217 offset:4096
	ds_read_b128 v[202:205], v217 offset:5120
	ds_read_b128 v[206:209], v217 offset:6144
	ds_read_b128 v[220:223], v217 offset:7168
	global_load_lds_dwordx4 v[228:229], off
	v_lshl_add_u64 v[228:229], s[40:41], 0, v[182:183]
	s_add_i32 m0, s39, 0xe000
	s_nop 0
	global_load_lds_dwordx4 v[228:229], off
	s_waitcnt vmcnt(8)
	s_waitcnt lgkmcnt(0)
	s_setprio 1
	s_barrier
; #define PG8_STAGE(bufoff, gbase, voff) do { _Pragma("unroll") for (int _i = 0; _i < 2; ++_i) \
;         __builtin_amdgcn_global_load_lds((const unsigned*)((const char*)(gbase) + (voff)[_i]), (PG8_LAS unsigned*)(lds + (bufoff) + ldsw + _i * 8192), 16, 0, 0); } while (0)
; #define PG8_LDA(dst, b, h) do { _Pragma("unroll") for (int m = 0; m < 4; ++m) _Pragma("unroll") for (int k = 0; k < 2; ++k) dst[m][k] = *(const PG8_LAS bf16x8*)(lds + PG8_SA(b, h) + aoff + m * 2048 + k * 1024); } while (0)
; #define PG8_LDB(dst, b, h) do { _Pragma("unroll") for (int n = 0; n < 2; ++n) _Pragma("unroll") for (int k = 0; k < 2; ++k) dst[n][k] = *(const PG8_LAS bf16x8*)(lds + PG8_SB(b, h) + boff + n * 2048 + k * 1024); } while (0)
; #define PG8_MMA(ai, bj, At, Bt) do { __builtin_amdgcn_s_setprio(1); _Pragma("unroll") for (int m = 0; m < 4; ++m) _Pragma("unroll") for (int n = 0; n < 2; ++n) _Pragma("unroll") for (int k = 0; k < 2; ++k) \
;         acc[ai][bj][m][n] = __builtin_amdgcn_mfma_f32_16x16x32_bf16(Bt[n][k], At[m][k], acc[ai][bj][m][n], 0, 0, 0); __builtin_amdgcn_s_setprio(0); } while (0)
; #define PG8_WAIT_V(n) asm volatile("s_waitcnt vmcnt(" #n ")" ::: "memory")
; #define PG8_WAIT_L(n) asm volatile("s_waitcnt lgkmcnt(" #n ")" ::: "memory")
; #define PG8_BAR __builtin_amdgcn_s_barrier()
; #define PG8_SCHED __builtin_amdgcn_sched_barrier(0)
; template <class Epi, class Sched, bool ALIGN_EPI = false, bool SP2 = false, bool DUAL = false>
; __device__ __forceinline__ void gemm_phase(PG8_LAS unsigned char* lds, const Gemm g, const Sched& S, const Epi& E) {
;     ...
;             PG8_LDB(B0, 0, 0); PG8_LDB(B1, 0, 1); PG8_SCHED; PG8_LDA(At, 0, 0); PG8_STAGE(PG8_SA(1, 1), a1 + hstep, voffA);
;             PG8_WAIT_V(8); PG8_WAIT_L(0); PG8_BAR; PG8_MMA(0, 0, At, B0); PG8_MMA(0, 1, At, B1); PG8_BAR; PG8_SCHED;
;             PG8_LDA(At, 0, 1); PG8_STAGE(PG8_SB(0, 0), b2, voffB); PG8_STAGE(PG8_SB(0, 1), b2 + hstep, voffB); PG8_STAGE(PG8_SA(0, 0), a2, voffA);
;             PG8_WAIT_V(8); PG8_WAIT_L(0); PG8_BAR; PG8_MMA(1, 0, At, B0); PG8_MMA(1, 1, At, B1); PG8_BAR; PG8_SCHED;
	v_mfma_f32_16x16x32_bf16 v[124:127], v[128:131], v[160:163], v[124:127]
	v_mfma_f32_16x16x32_bf16 v[120:123], v[136:139], v[160:163], v[120:123]
	v_mfma_f32_16x16x32_bf16 v[108:111], v[128:131], v[188:191], v[108:111]
	v_mfma_f32_16x16x32_bf16 v[104:107], v[136:139], v[188:191], v[104:107]
	v_mfma_f32_16x16x32_bf16 v[92:95], v[128:131], v[196:199], v[92:95]
	v_mfma_f32_16x16x32_bf16 v[88:91], v[136:139], v[196:199], v[88:91]
	v_mfma_f32_16x16x32_bf16 v[76:79], v[128:131], v[206:209], v[76:79]
	v_mfma_f32_16x16x32_bf16 v[72:75], v[136:139], v[206:209], v[72:75]
	v_mfma_f32_16x16x32_bf16 v[124:127], v[132:135], v[164:167], v[124:127]
	v_mfma_f32_16x16x32_bf16 v[120:123], v[140:143], v[164:167], v[120:123]
	v_mfma_f32_16x16x32_bf16 v[108:111], v[132:135], v[192:195], v[108:111]
	v_mfma_f32_16x16x32_bf16 v[104:107], v[140:143], v[192:195], v[104:107]
	v_mfma_f32_16x16x32_bf16 v[92:95], v[132:135], v[202:205], v[92:95]
	v_mfma_f32_16x16x32_bf16 v[88:91], v[140:143], v[202:205], v[88:91]
	v_mfma_f32_16x16x32_bf16 v[76:79], v[132:135], v[220:223], v[76:79]
	v_mfma_f32_16x16x32_bf16 v[72:75], v[140:143], v[220:223], v[72:75]
	v_mfma_f32_16x16x32_bf16 v[116:119], v[144:147], v[160:163], v[116:119]
	v_mfma_f32_16x16x32_bf16 v[112:115], v[152:155], v[160:163], v[112:115]
	v_mfma_f32_16x16x32_bf16 v[100:103], v[144:147], v[188:191], v[100:103]
	v_mfma_f32_16x16x32_bf16 v[96:99], v[152:155], v[188:191], v[96:99]
	v_mfma_f32_16x16x32_bf16 v[84:87], v[144:147], v[196:199], v[84:87]
	v_mfma_f32_16x16x32_bf16 v[80:83], v[152:155], v[196:199], v[80:83]
	v_mfma_f32_16x16x32_bf16 v[68:71], v[144:147], v[206:209], v[68:71]
	v_mfma_f32_16x16x32_bf16 v[64:67], v[152:155], v[206:209], v[64:67]
	v_mfma_f32_16x16x32_bf16 v[116:119], v[148:151], v[164:167], v[116:119]
	v_mfma_f32_16x16x32_bf16 v[112:115], v[156:159], v[164:167], v[112:115]
	v_mfma_f32_16x16x32_bf16 v[100:103], v[148:151], v[192:195], v[100:103]
	v_mfma_f32_16x16x32_bf16 v[96:99], v[156:159], v[192:195], v[96:99]
	v_mfma_f32_16x16x32_bf16 v[84:87], v[148:151], v[202:205], v[84:87]
	v_mfma_f32_16x16x32_bf16 v[80:83], v[156:159], v[202:205], v[80:83]
	v_mfma_f32_16x16x32_bf16 v[68:71], v[148:151], v[220:223], v[68:71]
	v_mfma_f32_16x16x32_bf16 v[64:67], v[156:159], v[220:223], v[64:67]
	s_barrier
	s_setprio 0
	s_add_i32 s66, s50, s34
	v_lshl_add_u64 v[228:229], s[14:15], 0, v[170:171]
	s_mov_b32 m0, s66
	ds_read_b128 v[160:163], v217 offset:16384
	ds_read_b128 v[164:167], v217 offset:17408
	ds_read_b128 v[188:191], v217 offset:18432
	ds_read_b128 v[192:195], v217 offset:19456
	ds_read_b128 v[196:199], v217 offset:20480
	ds_read_b128 v[202:205], v217 offset:21504
	ds_read_b128 v[206:209], v217 offset:22528
	ds_read_b128 v[220:223], v217 offset:23552
	global_load_lds_dwordx4 v[228:229], off
	s_add_i32 m0, s66, 0x2000
	s_add_u32 s66, s14, 0x80000
	v_lshl_add_u64 v[232:233], s[14:15], 0, v[174:175]
	s_addc_u32 s67, s15, 0
	s_add_i32 s68, s51, s34
	global_load_lds_dwordx4 v[232:233], off
	v_lshl_add_u64 v[234:235], s[66:67], 0, v[170:171]
	s_mov_b32 m0, s68
	v_lshl_add_u64 v[236:237], s[26:27], 0, v[172:173]
	global_load_lds_dwordx4 v[234:235], off
	v_lshl_add_u64 v[234:235], s[66:67], 0, v[174:175]
	s_add_i32 m0, s68, 0x2000
	s_nop 0
	global_load_lds_dwordx4 v[234:235], off
	v_lshl_add_u64 v[234:235], s[26:27], 0, v[168:169]
	s_mov_b32 m0, s39
	s_nop 0
	global_load_lds_dwordx4 v[234:235], off
	s_mov_b32 m0, s42
	s_nop 0
	global_load_lds_dwordx4 v[236:237], off
	s_waitcnt vmcnt(8)
	s_waitcnt lgkmcnt(0)
	s_setprio 1
	s_barrier
	v_mfma_f32_16x16x32_bf16 v[60:63], v[128:131], v[160:163], v[60:63]
	v_mfma_f32_16x16x32_bf16 v[56:59], v[136:139], v[160:163], v[56:59]
	v_mfma_f32_16x16x32_bf16 v[44:47], v[128:131], v[188:191], v[44:47]
	v_mfma_f32_16x16x32_bf16 v[40:43], v[136:139], v[188:191], v[40:43]
	v_mfma_f32_16x16x32_bf16 v[28:31], v[128:131], v[196:199], v[28:31]
	v_mfma_f32_16x16x32_bf16 v[24:27], v[136:139], v[196:199], v[24:27]
	v_mfma_f32_16x16x32_bf16 v[12:15], v[128:131], v[206:209], v[12:15]
	v_mfma_f32_16x16x32_bf16 v[8:11], v[136:139], v[206:209], v[8:11]
	v_mfma_f32_16x16x32_bf16 v[60:63], v[132:135], v[164:167], v[60:63]
	v_mfma_f32_16x16x32_bf16 v[56:59], v[140:143], v[164:167], v[56:59]
	v_mfma_f32_16x16x32_bf16 v[44:47], v[132:135], v[192:195], v[44:47]
	v_mfma_f32_16x16x32_bf16 v[40:43], v[140:143], v[192:195], v[40:43]
	v_mfma_f32_16x16x32_bf16 v[28:31], v[132:135], v[202:205], v[28:31]
	v_mfma_f32_16x16x32_bf16 v[24:27], v[140:143], v[202:205], v[24:27]
	v_mfma_f32_16x16x32_bf16 v[12:15], v[132:135], v[220:223], v[12:15]
	v_mfma_f32_16x16x32_bf16 v[8:11], v[140:143], v[220:223], v[8:11]
	v_mfma_f32_16x16x32_bf16 v[52:55], v[144:147], v[160:163], v[52:55]
	v_mfma_f32_16x16x32_bf16 v[48:51], v[152:155], v[160:163], v[48:51]
	v_mfma_f32_16x16x32_bf16 v[36:39], v[144:147], v[188:191], v[36:39]
	v_mfma_f32_16x16x32_bf16 v[32:35], v[152:155], v[188:191], v[32:35]
	v_mfma_f32_16x16x32_bf16 v[20:23], v[144:147], v[196:199], v[20:23]
	v_mfma_f32_16x16x32_bf16 v[16:19], v[152:155], v[196:199], v[16:19]
	v_mfma_f32_16x16x32_bf16 v[4:7], v[144:147], v[206:209], v[4:7]
	v_mfma_f32_16x16x32_bf16 v[0:3], v[152:155], v[206:209], v[0:3]
	v_mfma_f32_16x16x32_bf16 v[52:55], v[148:151], v[164:167], v[52:55]
	v_mfma_f32_16x16x32_bf16 v[48:51], v[156:159], v[164:167], v[48:51]
	v_mfma_f32_16x16x32_bf16 v[36:39], v[148:151], v[192:195], v[36:39]
	v_mfma_f32_16x16x32_bf16 v[32:35], v[156:159], v[192:195], v[32:35]
	v_mfma_f32_16x16x32_bf16 v[20:23], v[148:151], v[202:205], v[20:23]
	v_mfma_f32_16x16x32_bf16 v[16:19], v[156:159], v[202:205], v[16:19]
	v_mfma_f32_16x16x32_bf16 v[4:7], v[148:151], v[220:223], v[4:7]
	v_mfma_f32_16x16x32_bf16 v[0:3], v[156:159], v[220:223], v[0:3]
	s_barrier
; #define PG8_STAGE(bufoff, gbase, voff) do { _Pragma("unroll") for (int _i = 0; _i < 2; ++_i) \
;         __builtin_amdgcn_global_load_lds((const unsigned*)((const char*)(gbase) + (voff)[_i]), (PG8_LAS unsigned*)(lds + (bufoff) + ldsw + _i * 8192), 16, 0, 0); } while (0)
; #define PG8_LDA(dst, b, h) do { _Pragma("unroll") for (int m = 0; m < 4; ++m) _Pragma("unroll") for (int k = 0; k < 2; ++k) dst[m][k] = *(const PG8_LAS bf16x8*)(lds + PG8_SA(b, h) + aoff + m * 2048 + k * 1024); } while (0)
; #define PG8_LDB(dst, b, h) do { _Pragma("unroll") for (int n = 0; n < 2; ++n) _Pragma("unroll") for (int k = 0; k < 2; ++k) dst[n][k] = *(const PG8_LAS bf16x8*)(lds + PG8_SB(b, h) + boff + n * 2048 + k * 1024); } while (0)
; #define PG8_MMA(ai, bj, At, Bt) do { __builtin_amdgcn_s_setprio(1); _Pragma("unroll") for (int m = 0; m < 4; ++m) _Pragma("unroll") for (int n = 0; n < 2; ++n) _Pragma("unroll") for (int k = 0; k < 2; ++k) \
;         acc[ai][bj][m][n] = __builtin_amdgcn_mfma_f32_16x16x32_bf16(Bt[n][k], At[m][k], acc[ai][bj][m][n], 0, 0, 0); __builtin_amdgcn_s_setprio(0); } while (0)
; #define PG8_WAIT_V(n) asm volatile("s_waitcnt vmcnt(" #n ")" ::: "memory")
; #define PG8_WAIT_L(n) asm volatile("s_waitcnt lgkmcnt(" #n ")" ::: "memory")
; #define PG8_BAR __builtin_amdgcn_s_barrier()
; #define PG8_SCHED __builtin_amdgcn_sched_barrier(0)
; template <class Epi, class Sched, bool ALIGN_EPI = false, bool SP2 = false, bool DUAL = false>
; __device__ __forceinline__ void gemm_phase(PG8_LAS unsigned char* lds, const Gemm g, const Sched& S, const Epi& E) {
;     ...
;             PG8_LDB(B0, 1, 0); PG8_LDB(B1, 1, 1); PG8_SCHED; PG8_LDA(At, 1, 0); PG8_STAGE(PG8_SA(0, 1), a2 + hstep, voffA);
;             PG8_WAIT_V(8); PG8_WAIT_L(0); PG8_BAR; PG8_MMA(0, 0, At, B0); PG8_MMA(0, 1, At, B1); PG8_BAR; PG8_SCHED;
	s_setprio 0
	s_add_i32 s66, 0, 0x18000
	s_add_i32 s67, 0, 0x1c000
	v_add_u32_e32 v140, s66, v213
	v_add_u32_e32 v156, s67, v213
	ds_read_b128 v[128:131], v140
	ds_read_b128 v[132:135], v140 offset:1024
	ds_read_b128 v[136:139], v140 offset:2048
	ds_read_b128 v[140:143], v140 offset:3072
	ds_read_b128 v[144:147], v156
	ds_read_b128 v[148:151], v156 offset:1024
	ds_read_b128 v[152:155], v156 offset:2048
	ds_read_b128 v[156:159], v156 offset:3072
	s_add_u32 s26, s26, 0x80000
	s_addc_u32 s27, s27, 0
	s_mov_b32 m0, s43
	v_lshl_add_u64 v[238:239], s[26:27], 0, v[168:169]
	ds_read_b128 v[160:163], v217 offset:32768
	ds_read_b128 v[164:167], v217 offset:33792
	ds_read_b128 v[188:191], v217 offset:34816
	ds_read_b128 v[192:195], v217 offset:35840
	ds_read_b128 v[196:199], v217 offset:36864
	ds_read_b128 v[202:205], v217 offset:37888
	ds_read_b128 v[206:209], v217 offset:38912
	ds_read_b128 v[220:223], v217 offset:39936
	global_load_lds_dwordx4 v[238:239], off
	v_lshl_add_u64 v[238:239], s[26:27], 0, v[172:173]
	s_mov_b32 m0, s44
	s_nop 0
	global_load_lds_dwordx4 v[238:239], off
	s_waitcnt vmcnt(8)
	s_waitcnt lgkmcnt(0)
	s_setprio 1
	s_barrier
	v_mfma_f32_16x16x32_bf16 v[124:127], v[128:131], v[160:163], v[124:127]
	v_mfma_f32_16x16x32_bf16 v[120:123], v[136:139], v[160:163], v[120:123]
	v_mfma_f32_16x16x32_bf16 v[108:111], v[128:131], v[188:191], v[108:111]
	v_mfma_f32_16x16x32_bf16 v[104:107], v[136:139], v[188:191], v[104:107]
	v_mfma_f32_16x16x32_bf16 v[92:95], v[128:131], v[196:199], v[92:95]
	v_mfma_f32_16x16x32_bf16 v[88:91], v[136:139], v[196:199], v[88:91]
	v_mfma_f32_16x16x32_bf16 v[76:79], v[128:131], v[206:209], v[76:79]
	v_mfma_f32_16x16x32_bf16 v[72:75], v[136:139], v[206:209], v[72:75]
	v_mfma_f32_16x16x32_bf16 v[124:127], v[132:135], v[164:167], v[124:127]
	v_mfma_f32_16x16x32_bf16 v[120:123], v[140:143], v[164:167], v[120:123]
	v_mfma_f32_16x16x32_bf16 v[108:111], v[132:135], v[192:195], v[108:111]
	v_mfma_f32_16x16x32_bf16 v[104:107], v[140:143], v[192:195], v[104:107]
	v_mfma_f32_16x16x32_bf16 v[92:95], v[132:135], v[202:205], v[92:95]
	v_mfma_f32_16x16x32_bf16 v[88:91], v[140:143], v[202:205], v[88:91]
	v_mfma_f32_16x16x32_bf16 v[76:79], v[132:135], v[220:223], v[76:79]
	v_mfma_f32_16x16x32_bf16 v[72:75], v[140:143], v[220:223], v[72:75]
	v_mfma_f32_16x16x32_bf16 v[116:119], v[144:147], v[160:163], v[116:119]
	v_mfma_f32_16x16x32_bf16 v[112:115], v[152:155], v[160:163], v[112:115]
	v_mfma_f32_16x16x32_bf16 v[100:103], v[144:147], v[188:191], v[100:103]
	v_mfma_f32_16x16x32_bf16 v[96:99], v[152:155], v[188:191], v[96:99]
	v_mfma_f32_16x16x32_bf16 v[84:87], v[144:147], v[196:199], v[84:87]
	v_mfma_f32_16x16x32_bf16 v[80:83], v[152:155], v[196:199], v[80:83]
	v_mfma_f32_16x16x32_bf16 v[68:71], v[144:147], v[206:209], v[68:71]
	v_mfma_f32_16x16x32_bf16 v[64:67], v[152:155], v[206:209], v[64:67]
	v_mfma_f32_16x16x32_bf16 v[116:119], v[148:151], v[164:167], v[116:119]
	v_mfma_f32_16x16x32_bf16 v[112:115], v[156:159], v[164:167], v[112:115]
	v_mfma_f32_16x16x32_bf16 v[100:103], v[148:151], v[192:195], v[100:103]
	v_mfma_f32_16x16x32_bf16 v[96:99], v[156:159], v[192:195], v[96:99]
	v_mfma_f32_16x16x32_bf16 v[84:87], v[148:151], v[202:205], v[84:87]
	v_mfma_f32_16x16x32_bf16 v[80:83], v[156:159], v[202:205], v[80:83]
	v_mfma_f32_16x16x32_bf16 v[68:71], v[148:151], v[220:223], v[68:71]
	v_mfma_f32_16x16x32_bf16 v[64:67], v[156:159], v[220:223], v[64:67]
	s_barrier
; #define PG8_STAGE(bufoff, gbase, voff) do { _Pragma("unroll") for (int _i = 0; _i < 2; ++_i) \
;         __builtin_amdgcn_global_load_lds((const unsigned*)((const char*)(gbase) + (voff)[_i]), (PG8_LAS unsigned*)(lds + (bufoff) + ldsw + _i * 8192), 16, 0, 0); } while (0)
; #define PG8_LDA(dst, b, h) do { _Pragma("unroll") for (int m = 0; m < 4; ++m) _Pragma("unroll") for (int k = 0; k < 2; ++k) dst[m][k] = *(const PG8_LAS bf16x8*)(lds + PG8_SA(b, h) + aoff + m * 2048 + k * 1024); } while (0)
; #define PG8_MMA(ai, bj, At, Bt) do { __builtin_amdgcn_s_setprio(1); _Pragma("unroll") for (int m = 0; m < 4; ++m) _Pragma("unroll") for (int n = 0; n < 2; ++n) _Pragma("unroll") for (int k = 0; k < 2; ++k) \
;         acc[ai][bj][m][n] = __builtin_amdgcn_mfma_f32_16x16x32_bf16(Bt[n][k], At[m][k], acc[ai][bj][m][n], 0, 0, 0); __builtin_amdgcn_s_setprio(0); } while (0)
; #define PG8_WAIT_V(n) asm volatile("s_waitcnt vmcnt(" #n ")" ::: "memory")
; #define PG8_WAIT_L(n) asm volatile("s_waitcnt lgkmcnt(" #n ")" ::: "memory")
; #define PG8_BAR __builtin_amdgcn_s_barrier()
; #define PG8_SCHED __builtin_amdgcn_sched_barrier(0)
; template <class Epi, class Sched, bool ALIGN_EPI = false, bool SP2 = false, bool DUAL = false>
; __device__ __forceinline__ void gemm_phase(PG8_LAS unsigned char* lds, const Gemm g, const Sched& S, const Epi& E) {
;     ...
;         for (int t = 0; t < nt; t += 2) {
;             const bool last = (t == nt - 2);
;             const char* a1 = cA + (size_t)(t + 1) * kstep;
;             const char* a2 = last ? nA : cA + (size_t)(t + 2) * kstep; const char* b2 = last ? nB : cB + (size_t)(t + 2) * kstep;
;     ...
;             PG8_LDA(At, 1, 1); PG8_STAGE(PG8_SB(1, 0), b3, voffB); PG8_STAGE(PG8_SB(1, 1), b3 + hstep, voffB); PG8_STAGE(PG8_SA(1, 0), a3, voffA);
;             PG8_WAIT_V(8); PG8_WAIT_L(0); PG8_BAR; PG8_MMA(1, 0, At, B0); PG8_MMA(1, 1, At, B1); PG8_BAR; PG8_SCHED;
	s_setprio 0
	s_add_i32 s26, s66, s34
	v_lshl_add_u64 v[228:229], v[228:229], 0, s[12:13]
	s_mov_b32 m0, s26
	ds_read_b128 v[160:163], v217 offset:49152
	ds_read_b128 v[164:167], v217 offset:50176
	ds_read_b128 v[188:191], v217 offset:51200
	ds_read_b128 v[192:195], v217 offset:52224
	ds_read_b128 v[196:199], v217 offset:53248
	ds_read_b128 v[202:205], v217 offset:54272
	ds_read_b128 v[206:209], v217 offset:55296
	ds_read_b128 v[220:223], v217 offset:56320
	global_load_lds_dwordx4 v[228:229], off
	s_add_i32 m0, s26, 0x2000
	s_add_u32 s14, s14, 0x80080
	v_lshl_add_u64 v[228:229], v[232:233], 0, s[12:13]
	s_addc_u32 s15, s15, 0
	s_add_i32 s26, s67, s34
	global_load_lds_dwordx4 v[228:229], off
	v_lshl_add_u64 v[228:229], s[14:15], 0, v[170:171]
	s_mov_b32 m0, s26
	s_nop 0
	global_load_lds_dwordx4 v[228:229], off
	v_lshl_add_u64 v[228:229], s[14:15], 0, v[174:175]
	s_add_i32 m0, s26, 0x2000
	s_nop 0
	global_load_lds_dwordx4 v[228:229], off
	v_lshl_add_u64 v[228:229], v[234:235], 0, s[12:13]
	s_mov_b32 m0, s47
	s_nop 0
	global_load_lds_dwordx4 v[228:229], off
	v_lshl_add_u64 v[228:229], v[236:237], 0, s[12:13]
	s_mov_b32 m0, s48
	s_nop 0
	global_load_lds_dwordx4 v[228:229], off
	s_waitcnt vmcnt(8)
	s_waitcnt lgkmcnt(0)
	s_setprio 1
	s_barrier
	v_mfma_f32_16x16x32_bf16 v[60:63], v[128:131], v[160:163], v[60:63]
	v_mfma_f32_16x16x32_bf16 v[56:59], v[136:139], v[160:163], v[56:59]
	v_mfma_f32_16x16x32_bf16 v[44:47], v[128:131], v[188:191], v[44:47]
	v_mfma_f32_16x16x32_bf16 v[40:43], v[136:139], v[188:191], v[40:43]
	v_mfma_f32_16x16x32_bf16 v[28:31], v[128:131], v[196:199], v[28:31]
	v_mfma_f32_16x16x32_bf16 v[24:27], v[136:139], v[196:199], v[24:27]
	v_mfma_f32_16x16x32_bf16 v[12:15], v[128:131], v[206:209], v[12:15]
	v_mfma_f32_16x16x32_bf16 v[8:11], v[136:139], v[206:209], v[8:11]
	v_mfma_f32_16x16x32_bf16 v[60:63], v[132:135], v[164:167], v[60:63]
	v_mfma_f32_16x16x32_bf16 v[56:59], v[140:143], v[164:167], v[56:59]
	v_mfma_f32_16x16x32_bf16 v[44:47], v[132:135], v[192:195], v[44:47]
	v_mfma_f32_16x16x32_bf16 v[40:43], v[140:143], v[192:195], v[40:43]
	v_mfma_f32_16x16x32_bf16 v[28:31], v[132:135], v[202:205], v[28:31]
	v_mfma_f32_16x16x32_bf16 v[24:27], v[140:143], v[202:205], v[24:27]
	v_mfma_f32_16x16x32_bf16 v[12:15], v[132:135], v[220:223], v[12:15]
	v_mfma_f32_16x16x32_bf16 v[8:11], v[140:143], v[220:223], v[8:11]
	v_mfma_f32_16x16x32_bf16 v[52:55], v[144:147], v[160:163], v[52:55]
	v_mfma_f32_16x16x32_bf16 v[48:51], v[152:155], v[160:163], v[48:51]
	v_mfma_f32_16x16x32_bf16 v[36:39], v[144:147], v[188:191], v[36:39]
	v_mfma_f32_16x16x32_bf16 v[32:35], v[152:155], v[188:191], v[32:35]
	v_mfma_f32_16x16x32_bf16 v[20:23], v[144:147], v[196:199], v[20:23]
	v_mfma_f32_16x16x32_bf16 v[16:19], v[152:155], v[196:199], v[16:19]
	v_mfma_f32_16x16x32_bf16 v[4:7], v[144:147], v[206:209], v[4:7]
	v_mfma_f32_16x16x32_bf16 v[0:3], v[152:155], v[206:209], v[0:3]
	v_mfma_f32_16x16x32_bf16 v[52:55], v[148:151], v[164:167], v[52:55]
	v_mfma_f32_16x16x32_bf16 v[48:51], v[156:159], v[164:167], v[48:51]
	v_mfma_f32_16x16x32_bf16 v[36:39], v[148:151], v[192:195], v[36:39]
	v_mfma_f32_16x16x32_bf16 v[32:35], v[156:159], v[192:195], v[32:35]
	v_mfma_f32_16x16x32_bf16 v[20:23], v[148:151], v[202:205], v[20:23]
	v_mfma_f32_16x16x32_bf16 v[16:19], v[156:159], v[202:205], v[16:19]
	v_mfma_f32_16x16x32_bf16 v[4:7], v[148:151], v[220:223], v[4:7]
	v_mfma_f32_16x16x32_bf16 v[0:3], v[156:159], v[220:223], v[0:3]
	s_barrier
	s_setprio 0
	s_add_i32 s65, s65, 2
	s_add_u32 s40, s40, 0x100
	s_addc_u32 s41, s41, 0
	s_add_u32 s63, s63, 0x100
	s_addc_u32 s64, s64, 0
	s_cmp_gt_u32 s65, 29
	s_cbranch_scc0 .LBB0_992
	v_readlane_b32 s64, v254, 20
	v_readlane_b32 s70, v254, 26
	v_readlane_b32 s71, v254, 27
	v_readlane_b32 s72, v254, 28
	v_readlane_b32 s73, v254, 29
	v_readlane_b32 s74, v254, 30
	v_readlane_b32 s75, v254, 31
	v_readlane_b32 s76, v254, 32
	v_readlane_b32 s77, v254, 33
	s_and_b64 vcc, exec, s[16:17]
	s_mov_b64 s[70:71], s[74:75]
	s_mov_b64 s[72:73], s[76:77]
	v_readlane_b32 s65, v254, 21
	v_readlane_b32 s66, v254, 22
	v_readlane_b32 s67, v254, 23
	v_readlane_b32 s68, v254, 24
	v_readlane_b32 s69, v254, 25
	v_readlane_b32 s78, v254, 34
	v_readlane_b32 s79, v254, 35
	s_cbranch_vccz .LBB0_995
	s_barrier

; #define PG8_STAGE(bufoff, gbase, voff) do { _Pragma("unroll") for (int _i = 0; _i < 2; ++_i) \
;         __builtin_amdgcn_global_load_lds((const unsigned*)((const char*)(gbase) + (voff)[_i]), (PG8_LAS unsigned*)(lds + (bufoff) + ldsw + _i * 8192), 16, 0, 0); } while (0)
; #define PG8_LDA(dst, b, h) do { _Pragma("unroll") for (int m = 0; m < 4; ++m) _Pragma("unroll") for (int k = 0; k < 2; ++k) dst[m][k] = *(const PG8_LAS bf16x8*)(lds + PG8_SA(b, h) + aoff + m * 2048 + k * 1024); } while (0)
; #define PG8_LDB(dst, b, h) do { _Pragma("unroll") for (int n = 0; n < 2; ++n) _Pragma("unroll") for (int k = 0; k < 2; ++k) dst[n][k] = *(const PG8_LAS bf16x8*)(lds + PG8_SB(b, h) + boff + n * 2048 + k * 1024); } while (0)
; #define PG8_MMA(ai, bj, At, Bt) do { __builtin_amdgcn_s_setprio(1); _Pragma("unroll") for (int m = 0; m < 4; ++m) _Pragma("unroll") for (int n = 0; n < 2; ++n) _Pragma("unroll") for (int k = 0; k < 2; ++k) \
;         acc[ai][bj][m][n] = __builtin_amdgcn_mfma_f32_16x16x32_bf16(Bt[n][k], At[m][k], acc[ai][bj][m][n], 0, 0, 0); __builtin_amdgcn_s_setprio(0); } while (0)
; #define PG8_WAIT_V(n) asm volatile("s_waitcnt vmcnt(" #n ")" ::: "memory")
; #define PG8_WAIT_L(n) asm volatile("s_waitcnt lgkmcnt(" #n ")" ::: "memory")
; #define PG8_BAR __builtin_amdgcn_s_barrier()
; #define PG8_SCHED __builtin_amdgcn_sched_barrier(0)
; template <class Epi, class Sched, bool ALIGN_EPI = false, bool SP2 = false, bool DUAL = false>
; __device__ __forceinline__ void gemm_phase(PG8_LAS unsigned char* lds, const Gemm g, const Sched& S, const Epi& E) {
;     ...
;             PG8_LDB(B0, 0, 0); PG8_LDB(B1, 0, 1); PG8_SCHED; PG8_LDA(At, 0, 0); PG8_STAGE(PG8_SA(1, 1), a1 + hstep, voffA);
;             PG8_WAIT_V(8); PG8_WAIT_L(0); PG8_BAR; PG8_MMA(0, 0, At, B0); PG8_MMA(0, 1, At, B1); PG8_BAR; PG8_SCHED;
;             PG8_LDA(At, 0, 1); PG8_STAGE(PG8_SB(0, 0), b2, voffB); PG8_STAGE(PG8_SB(0, 1), b2 + hstep, voffB); PG8_STAGE(PG8_SA(0, 0), a2, voffA);
;             PG8_WAIT_V(8); PG8_WAIT_L(0); PG8_BAR; PG8_MMA(1, 0, At, B0); PG8_MMA(1, 1, At, B1); PG8_BAR; PG8_SCHED;
;     ...
;         if (!keep)
; #pragma unroll
;         for (int a = 0; a < 2; ++a)
; #pragma unroll
;             for (int b = 0; b < 2; ++b)
; #pragma unroll
;                 for (int m = 0; m < 4; ++m)
; #pragma unroll
;                     for (int n = 0; n < 2; ++n) acc[a][b][m][n] = (f32x4){0.f, 0.f, 0.f, 0.f};
.LBB0_1192:
	s_add_u32 s24, s24, 0x160080
	s_addc_u32 s25, s25, 0
	s_add_u32 s46, s14, 0x100
	s_addc_u32 s47, s15, 0
	s_mov_b32 s48, -2
	ds_read_b128 v[128:131], v201
	ds_read_b128 v[132:135], v201 offset:1024
	ds_read_b128 v[136:139], v201 offset:2048
	ds_read_b128 v[140:143], v201 offset:3072
	ds_read_b128 v[144:147], v202
	ds_read_b128 v[148:151], v202 offset:1024
	ds_read_b128 v[152:155], v202 offset:2048
	ds_read_b128 v[156:159], v202 offset:3072
	s_add_u32 s14, s24, 0xffea0080
	s_addc_u32 s15, s25, -1
	s_cmpk_eq_i32 s48, 0x54
	s_cselect_b32 s27, s5, s15
	s_cselect_b32 s26, s4, s14
	s_cselect_b32 s15, s23, s47
	s_cselect_b32 s14, s22, s46
	v_lshl_add_u64 v[220:221], s[24:25], 0, v[172:173]
	s_add_i32 m0, s31, 0xc000
	ds_read_b128 v[160:163], v203
	ds_read_b128 v[182:185], v203 offset:1024
	ds_read_b128 v[186:189], v203 offset:2048
	ds_read_b128 v[190:193], v203 offset:3072
	ds_read_b128 v[204:207], v203 offset:4096
	ds_read_b128 v[208:211], v203 offset:5120
	ds_read_b128 v[212:215], v203 offset:6144
	ds_read_b128 v[216:219], v203 offset:7168
	global_load_lds_dwordx4 v[220:221], off
	v_lshl_add_u64 v[220:221], s[24:25], 0, v[174:175]
	s_add_i32 m0, s31, 0xe000
	s_nop 0
	global_load_lds_dwordx4 v[220:221], off
	s_waitcnt vmcnt(8)
	s_waitcnt lgkmcnt(0)
	s_setprio 1
	s_barrier
	v_mfma_f32_16x16x32_bf16 v[124:127], v[128:131], v[160:163], 0
	v_mfma_f32_16x16x32_bf16 v[120:123], v[136:139], v[160:163], 0
	v_mfma_f32_16x16x32_bf16 v[112:115], v[128:131], v[186:189], 0
	v_mfma_f32_16x16x32_bf16 v[104:107], v[136:139], v[186:189], 0
	v_mfma_f32_16x16x32_bf16 v[96:99], v[128:131], v[204:207], 0
	v_mfma_f32_16x16x32_bf16 v[88:91], v[136:139], v[204:207], 0
	v_mfma_f32_16x16x32_bf16 v[80:83], v[128:131], v[212:215], 0
	v_mfma_f32_16x16x32_bf16 v[72:75], v[136:139], v[212:215], 0
	v_mfma_f32_16x16x32_bf16 v[124:127], v[132:135], v[182:185], v[124:127]
	v_mfma_f32_16x16x32_bf16 v[120:123], v[140:143], v[182:185], v[120:123]
	v_mfma_f32_16x16x32_bf16 v[112:115], v[132:135], v[190:193], v[112:115]
	v_mfma_f32_16x16x32_bf16 v[104:107], v[140:143], v[190:193], v[104:107]
	v_mfma_f32_16x16x32_bf16 v[96:99], v[132:135], v[208:211], v[96:99]
	v_mfma_f32_16x16x32_bf16 v[88:91], v[140:143], v[208:211], v[88:91]
	v_mfma_f32_16x16x32_bf16 v[80:83], v[132:135], v[216:219], v[80:83]
	v_mfma_f32_16x16x32_bf16 v[72:75], v[140:143], v[216:219], v[72:75]
	v_mfma_f32_16x16x32_bf16 v[116:119], v[144:147], v[160:163], 0
	v_mfma_f32_16x16x32_bf16 v[108:111], v[152:155], v[160:163], 0
	v_mfma_f32_16x16x32_bf16 v[100:103], v[144:147], v[186:189], 0
	v_mfma_f32_16x16x32_bf16 v[92:95], v[152:155], v[186:189], 0
	v_mfma_f32_16x16x32_bf16 v[84:87], v[144:147], v[204:207], 0
	v_mfma_f32_16x16x32_bf16 v[76:79], v[152:155], v[204:207], 0
	v_mfma_f32_16x16x32_bf16 v[68:71], v[144:147], v[212:215], 0
	v_mfma_f32_16x16x32_bf16 v[64:67], v[152:155], v[212:215], 0
	v_mfma_f32_16x16x32_bf16 v[116:119], v[148:151], v[182:185], v[116:119]
	v_mfma_f32_16x16x32_bf16 v[108:111], v[156:159], v[182:185], v[108:111]
	v_mfma_f32_16x16x32_bf16 v[100:103], v[148:151], v[190:193], v[100:103]
	v_mfma_f32_16x16x32_bf16 v[92:95], v[156:159], v[190:193], v[92:95]
	v_mfma_f32_16x16x32_bf16 v[84:87], v[148:151], v[208:211], v[84:87]
	v_mfma_f32_16x16x32_bf16 v[76:79], v[156:159], v[208:211], v[76:79]
	v_mfma_f32_16x16x32_bf16 v[68:71], v[148:151], v[216:219], v[68:71]
	v_mfma_f32_16x16x32_bf16 v[64:67], v[156:159], v[216:219], v[64:67]
	s_barrier
	s_setprio 0
	s_add_i32 s49, s40, s30
	v_lshl_add_u64 v[220:221], s[14:15], 0, v[166:167]
	s_mov_b32 m0, s49
	ds_read_b128 v[160:163], v203 offset:16384
	ds_read_b128 v[182:185], v203 offset:17408
	ds_read_b128 v[186:189], v203 offset:18432
	ds_read_b128 v[190:193], v203 offset:19456
	ds_read_b128 v[204:207], v203 offset:20480
	ds_read_b128 v[208:211], v203 offset:21504
	ds_read_b128 v[212:215], v203 offset:22528
	ds_read_b128 v[216:219], v203 offset:23552
	global_load_lds_dwordx4 v[220:221], off
	s_add_i32 m0, s49, 0x2000
	s_add_u32 s50, s14, 0x160000
	v_lshl_add_u64 v[222:223], s[14:15], 0, v[170:171]
	s_addc_u32 s51, s15, 0
	s_add_i32 s49, s41, s30
	global_load_lds_dwordx4 v[222:223], off
	v_lshl_add_u64 v[224:225], s[50:51], 0, v[166:167]
	s_mov_b32 m0, s49
	v_lshl_add_u64 v[226:227], s[26:27], 0, v[168:169]
	global_load_lds_dwordx4 v[224:225], off
	v_lshl_add_u64 v[224:225], s[50:51], 0, v[170:171]
	s_add_i32 m0, s49, 0x2000
	s_nop 0
	global_load_lds_dwordx4 v[224:225], off
	v_lshl_add_u64 v[224:225], s[26:27], 0, v[164:165]
	s_mov_b32 m0, s31
	s_nop 0
	global_load_lds_dwordx4 v[224:225], off
	s_mov_b32 m0, s33
	s_nop 0
	global_load_lds_dwordx4 v[226:227], off
	s_waitcnt vmcnt(8)
	s_waitcnt lgkmcnt(0)
	s_setprio 1
	s_barrier
; #define PG8_STAGE(bufoff, gbase, voff) do { _Pragma("unroll") for (int _i = 0; _i < 2; ++_i) \
;         __builtin_amdgcn_global_load_lds((const unsigned*)((const char*)(gbase) + (voff)[_i]), (PG8_LAS unsigned*)(lds + (bufoff) + ldsw + _i * 8192), 16, 0, 0); } while (0)
; #define PG8_LDA(dst, b, h) do { _Pragma("unroll") for (int m = 0; m < 4; ++m) _Pragma("unroll") for (int k = 0; k < 2; ++k) dst[m][k] = *(const PG8_LAS bf16x8*)(lds + PG8_SA(b, h) + aoff + m * 2048 + k * 1024); } while (0)
; #define PG8_LDB(dst, b, h) do { _Pragma("unroll") for (int n = 0; n < 2; ++n) _Pragma("unroll") for (int k = 0; k < 2; ++k) dst[n][k] = *(const PG8_LAS bf16x8*)(lds + PG8_SB(b, h) + boff + n * 2048 + k * 1024); } while (0)
; #define PG8_MMA(ai, bj, At, Bt) do { __builtin_amdgcn_s_setprio(1); _Pragma("unroll") for (int m = 0; m < 4; ++m) _Pragma("unroll") for (int n = 0; n < 2; ++n) _Pragma("unroll") for (int k = 0; k < 2; ++k) \
;         acc[ai][bj][m][n] = __builtin_amdgcn_mfma_f32_16x16x32_bf16(Bt[n][k], At[m][k], acc[ai][bj][m][n], 0, 0, 0); __builtin_amdgcn_s_setprio(0); } while (0)
; #define PG8_WAIT_V(n) asm volatile("s_waitcnt vmcnt(" #n ")" ::: "memory")
; #define PG8_WAIT_L(n) asm volatile("s_waitcnt lgkmcnt(" #n ")" ::: "memory")
; #define PG8_BAR __builtin_amdgcn_s_barrier()
; #define PG8_SCHED __builtin_amdgcn_sched_barrier(0)
; template <class Epi, class Sched, bool ALIGN_EPI = false, bool SP2 = false, bool DUAL = false>
; __device__ __forceinline__ void gemm_phase(PG8_LAS unsigned char* lds, const Gemm g, const Sched& S, const Epi& E) {
;     ...
;             PG8_WAIT_V(8); PG8_WAIT_L(0); PG8_BAR; PG8_MMA(1, 0, At, B0); PG8_MMA(1, 1, At, B1); PG8_BAR; PG8_SCHED;
;             PG8_LDB(B0, 1, 0); PG8_LDB(B1, 1, 1); PG8_SCHED; PG8_LDA(At, 1, 0); PG8_STAGE(PG8_SA(0, 1), a2 + hstep, voffA);
;             PG8_WAIT_V(8); PG8_WAIT_L(0); PG8_BAR; PG8_MMA(0, 0, At, B0); PG8_MMA(0, 1, At, B1); PG8_BAR; PG8_SCHED;
	v_mfma_f32_16x16x32_bf16 v[60:63], v[128:131], v[160:163], 0
	v_mfma_f32_16x16x32_bf16 v[56:59], v[136:139], v[160:163], 0
	v_mfma_f32_16x16x32_bf16 v[48:51], v[128:131], v[186:189], 0
	v_mfma_f32_16x16x32_bf16 v[40:43], v[136:139], v[186:189], 0
	v_mfma_f32_16x16x32_bf16 v[32:35], v[128:131], v[204:207], 0
	v_mfma_f32_16x16x32_bf16 v[24:27], v[136:139], v[204:207], 0
	v_mfma_f32_16x16x32_bf16 v[16:19], v[128:131], v[212:215], 0
	v_mfma_f32_16x16x32_bf16 v[8:11], v[136:139], v[212:215], 0
	v_mfma_f32_16x16x32_bf16 v[60:63], v[132:135], v[182:185], v[60:63]
	v_mfma_f32_16x16x32_bf16 v[56:59], v[140:143], v[182:185], v[56:59]
	v_mfma_f32_16x16x32_bf16 v[48:51], v[132:135], v[190:193], v[48:51]
	v_mfma_f32_16x16x32_bf16 v[40:43], v[140:143], v[190:193], v[40:43]
	v_mfma_f32_16x16x32_bf16 v[32:35], v[132:135], v[208:211], v[32:35]
	v_mfma_f32_16x16x32_bf16 v[24:27], v[140:143], v[208:211], v[24:27]
	v_mfma_f32_16x16x32_bf16 v[16:19], v[132:135], v[216:219], v[16:19]
	v_mfma_f32_16x16x32_bf16 v[8:11], v[140:143], v[216:219], v[8:11]
	v_mfma_f32_16x16x32_bf16 v[52:55], v[144:147], v[160:163], 0
	v_mfma_f32_16x16x32_bf16 v[44:47], v[152:155], v[160:163], 0
	v_mfma_f32_16x16x32_bf16 v[36:39], v[144:147], v[186:189], 0
	v_mfma_f32_16x16x32_bf16 v[28:31], v[152:155], v[186:189], 0
	v_mfma_f32_16x16x32_bf16 v[20:23], v[144:147], v[204:207], 0
	v_mfma_f32_16x16x32_bf16 v[12:15], v[152:155], v[204:207], 0
	v_mfma_f32_16x16x32_bf16 v[4:7], v[144:147], v[212:215], 0
	v_mfma_f32_16x16x32_bf16 v[0:3], v[152:155], v[212:215], 0
	v_mfma_f32_16x16x32_bf16 v[52:55], v[148:151], v[182:185], v[52:55]
	v_mfma_f32_16x16x32_bf16 v[44:47], v[156:159], v[182:185], v[44:47]
	v_mfma_f32_16x16x32_bf16 v[36:39], v[148:151], v[190:193], v[36:39]
	v_mfma_f32_16x16x32_bf16 v[28:31], v[156:159], v[190:193], v[28:31]
	v_mfma_f32_16x16x32_bf16 v[20:23], v[148:151], v[208:211], v[20:23]
	v_mfma_f32_16x16x32_bf16 v[12:15], v[156:159], v[208:211], v[12:15]
	v_mfma_f32_16x16x32_bf16 v[4:7], v[148:151], v[216:219], v[4:7]
	v_mfma_f32_16x16x32_bf16 v[0:3], v[156:159], v[216:219], v[0:3]
	s_barrier
	s_setprio 0
	s_add_i32 s49, 0, 0x18000
	s_add_i32 s50, 0, 0x1c000
	v_add_u32_e32 v140, s49, v198
	v_add_u32_e32 v156, s50, v198
	ds_read_b128 v[128:131], v140
	ds_read_b128 v[132:135], v140 offset:1024
	ds_read_b128 v[136:139], v140 offset:2048
	ds_read_b128 v[140:143], v140 offset:3072
	ds_read_b128 v[144:147], v156
	ds_read_b128 v[148:151], v156 offset:1024
	ds_read_b128 v[152:155], v156 offset:2048
	ds_read_b128 v[156:159], v156 offset:3072
	s_add_u32 s26, s26, 0x160000
	s_addc_u32 s27, s27, 0
	s_mov_b32 m0, s34
	v_lshl_add_u64 v[228:229], s[26:27], 0, v[164:165]
	ds_read_b128 v[160:163], v203 offset:32768
	ds_read_b128 v[182:185], v203 offset:33792
	ds_read_b128 v[186:189], v203 offset:34816
	ds_read_b128 v[190:193], v203 offset:35840
	ds_read_b128 v[204:207], v203 offset:36864
	ds_read_b128 v[208:211], v203 offset:37888
	ds_read_b128 v[212:215], v203 offset:38912
	ds_read_b128 v[216:219], v203 offset:39936
	global_load_lds_dwordx4 v[228:229], off
	v_lshl_add_u64 v[228:229], s[26:27], 0, v[168:169]
	s_mov_b32 m0, s35
	s_nop 0
	global_load_lds_dwordx4 v[228:229], off
	s_waitcnt vmcnt(8)
	s_waitcnt lgkmcnt(0)
	s_setprio 1
	s_barrier
	v_mfma_f32_16x16x32_bf16 v[124:127], v[128:131], v[160:163], v[124:127]
	v_mfma_f32_16x16x32_bf16 v[120:123], v[136:139], v[160:163], v[120:123]
	v_mfma_f32_16x16x32_bf16 v[112:115], v[128:131], v[186:189], v[112:115]
	v_mfma_f32_16x16x32_bf16 v[104:107], v[136:139], v[186:189], v[104:107]
	v_mfma_f32_16x16x32_bf16 v[96:99], v[128:131], v[204:207], v[96:99]
	v_mfma_f32_16x16x32_bf16 v[88:91], v[136:139], v[204:207], v[88:91]
	v_mfma_f32_16x16x32_bf16 v[80:83], v[128:131], v[212:215], v[80:83]
	v_mfma_f32_16x16x32_bf16 v[72:75], v[136:139], v[212:215], v[72:75]
	v_mfma_f32_16x16x32_bf16 v[124:127], v[132:135], v[182:185], v[124:127]
	v_mfma_f32_16x16x32_bf16 v[120:123], v[140:143], v[182:185], v[120:123]
	v_mfma_f32_16x16x32_bf16 v[112:115], v[132:135], v[190:193], v[112:115]
	v_mfma_f32_16x16x32_bf16 v[104:107], v[140:143], v[190:193], v[104:107]
	v_mfma_f32_16x16x32_bf16 v[96:99], v[132:135], v[208:211], v[96:99]
	v_mfma_f32_16x16x32_bf16 v[88:91], v[140:143], v[208:211], v[88:91]
	v_mfma_f32_16x16x32_bf16 v[80:83], v[132:135], v[216:219], v[80:83]
	v_mfma_f32_16x16x32_bf16 v[72:75], v[140:143], v[216:219], v[72:75]
	v_mfma_f32_16x16x32_bf16 v[116:119], v[144:147], v[160:163], v[116:119]
	v_mfma_f32_16x16x32_bf16 v[108:111], v[152:155], v[160:163], v[108:111]
	v_mfma_f32_16x16x32_bf16 v[100:103], v[144:147], v[186:189], v[100:103]
	v_mfma_f32_16x16x32_bf16 v[92:95], v[152:155], v[186:189], v[92:95]
	v_mfma_f32_16x16x32_bf16 v[84:87], v[144:147], v[204:207], v[84:87]
	v_mfma_f32_16x16x32_bf16 v[76:79], v[152:155], v[204:207], v[76:79]
	v_mfma_f32_16x16x32_bf16 v[68:71], v[144:147], v[212:215], v[68:71]
	v_mfma_f32_16x16x32_bf16 v[64:67], v[152:155], v[212:215], v[64:67]
	v_mfma_f32_16x16x32_bf16 v[116:119], v[148:151], v[182:185], v[116:119]
	v_mfma_f32_16x16x32_bf16 v[108:111], v[156:159], v[182:185], v[108:111]
	v_mfma_f32_16x16x32_bf16 v[100:103], v[148:151], v[190:193], v[100:103]
	v_mfma_f32_16x16x32_bf16 v[92:95], v[156:159], v[190:193], v[92:95]
	v_mfma_f32_16x16x32_bf16 v[84:87], v[148:151], v[208:211], v[84:87]
	v_mfma_f32_16x16x32_bf16 v[76:79], v[156:159], v[208:211], v[76:79]
	v_mfma_f32_16x16x32_bf16 v[68:71], v[148:151], v[216:219], v[68:71]
	v_mfma_f32_16x16x32_bf16 v[64:67], v[156:159], v[216:219], v[64:67]
	s_barrier
; #define PG8_STAGE(bufoff, gbase, voff) do { _Pragma("unroll") for (int _i = 0; _i < 2; ++_i) \
;         __builtin_amdgcn_global_load_lds((const unsigned*)((const char*)(gbase) + (voff)[_i]), (PG8_LAS unsigned*)(lds + (bufoff) + ldsw + _i * 8192), 16, 0, 0); } while (0)
; #define PG8_LDA(dst, b, h) do { _Pragma("unroll") for (int m = 0; m < 4; ++m) _Pragma("unroll") for (int k = 0; k < 2; ++k) dst[m][k] = *(const PG8_LAS bf16x8*)(lds + PG8_SA(b, h) + aoff + m * 2048 + k * 1024); } while (0)
; #define PG8_LDB(dst, b, h) do { _Pragma("unroll") for (int n = 0; n < 2; ++n) _Pragma("unroll") for (int k = 0; k < 2; ++k) dst[n][k] = *(const PG8_LAS bf16x8*)(lds + PG8_SB(b, h) + boff + n * 2048 + k * 1024); } while (0)
; #define PG8_MMA(ai, bj, At, Bt) do { __builtin_amdgcn_s_setprio(1); _Pragma("unroll") for (int m = 0; m < 4; ++m) _Pragma("unroll") for (int n = 0; n < 2; ++n) _Pragma("unroll") for (int k = 0; k < 2; ++k) \
;         acc[ai][bj][m][n] = __builtin_amdgcn_mfma_f32_16x16x32_bf16(Bt[n][k], At[m][k], acc[ai][bj][m][n], 0, 0, 0); __builtin_amdgcn_s_setprio(0); } while (0)
; #define PG8_WAIT_V(n) asm volatile("s_waitcnt vmcnt(" #n ")" ::: "memory")
; #define PG8_WAIT_L(n) asm volatile("s_waitcnt lgkmcnt(" #n ")" ::: "memory")
; #define PG8_BAR __builtin_amdgcn_s_barrier()
; #define PG8_SCHED __builtin_amdgcn_sched_barrier(0)
; template <class Epi, class Sched, bool ALIGN_EPI = false, bool SP2 = false, bool DUAL = false>
; __device__ __forceinline__ void gemm_phase(PG8_LAS unsigned char* lds, const Gemm g, const Sched& S, const Epi& E) {
;     ...
;             PG8_LDB(B0, 0, 0); PG8_LDB(B1, 0, 1); PG8_SCHED; PG8_LDA(At, 0, 0); PG8_STAGE(PG8_SA(1, 1), a1 + hstep, voffA);
;             PG8_WAIT_V(8); PG8_WAIT_L(0); PG8_BAR; PG8_MMA(0, 0, At, B0); PG8_MMA(0, 1, At, B1); PG8_BAR; PG8_SCHED;
;     ...
;             PG8_LDA(At, 1, 1); PG8_STAGE(PG8_SB(1, 0), b3, voffB); PG8_STAGE(PG8_SB(1, 1), b3 + hstep, voffB); PG8_STAGE(PG8_SA(1, 0), a3, voffA);
;             PG8_WAIT_V(8); PG8_WAIT_L(0); PG8_BAR; PG8_MMA(1, 0, At, B0); PG8_MMA(1, 1, At, B1); PG8_BAR; PG8_SCHED;
	s_setprio 0
	s_add_i32 s26, s49, s30
	v_lshl_add_u64 v[220:221], v[220:221], 0, s[18:19]
	s_mov_b32 m0, s26
	ds_read_b128 v[160:163], v203 offset:49152
	ds_read_b128 v[182:185], v203 offset:50176
	ds_read_b128 v[186:189], v203 offset:51200
	ds_read_b128 v[190:193], v203 offset:52224
	ds_read_b128 v[204:207], v203 offset:53248
	ds_read_b128 v[208:211], v203 offset:54272
	ds_read_b128 v[212:215], v203 offset:55296
	ds_read_b128 v[216:219], v203 offset:56320
	global_load_lds_dwordx4 v[220:221], off
	s_add_i32 m0, s26, 0x2000
	s_add_u32 s14, s14, 0x160080
	v_lshl_add_u64 v[220:221], v[222:223], 0, s[18:19]
	s_addc_u32 s15, s15, 0
	s_add_i32 s26, s50, s30
	global_load_lds_dwordx4 v[220:221], off
	v_lshl_add_u64 v[220:221], s[14:15], 0, v[166:167]
	s_mov_b32 m0, s26
	s_nop 0
	global_load_lds_dwordx4 v[220:221], off
	v_lshl_add_u64 v[220:221], s[14:15], 0, v[170:171]
	s_add_i32 m0, s26, 0x2000
	s_nop 0
	global_load_lds_dwordx4 v[220:221], off
	v_lshl_add_u64 v[220:221], v[224:225], 0, s[18:19]
	s_mov_b32 m0, s37
	s_nop 0
	global_load_lds_dwordx4 v[220:221], off
	v_lshl_add_u64 v[220:221], v[226:227], 0, s[18:19]
	s_mov_b32 m0, s38
	s_nop 0
	global_load_lds_dwordx4 v[220:221], off
	s_waitcnt vmcnt(8)
	s_waitcnt lgkmcnt(0)
	s_setprio 1
	s_barrier
	v_mfma_f32_16x16x32_bf16 v[60:63], v[128:131], v[160:163], v[60:63]
	v_mfma_f32_16x16x32_bf16 v[56:59], v[136:139], v[160:163], v[56:59]
	v_mfma_f32_16x16x32_bf16 v[48:51], v[128:131], v[186:189], v[48:51]
	v_mfma_f32_16x16x32_bf16 v[40:43], v[136:139], v[186:189], v[40:43]
	v_mfma_f32_16x16x32_bf16 v[32:35], v[128:131], v[204:207], v[32:35]
	v_mfma_f32_16x16x32_bf16 v[24:27], v[136:139], v[204:207], v[24:27]
	v_mfma_f32_16x16x32_bf16 v[16:19], v[128:131], v[212:215], v[16:19]
	v_mfma_f32_16x16x32_bf16 v[8:11], v[136:139], v[212:215], v[8:11]
	v_mfma_f32_16x16x32_bf16 v[60:63], v[132:135], v[182:185], v[60:63]
	v_mfma_f32_16x16x32_bf16 v[56:59], v[140:143], v[182:185], v[56:59]
	v_mfma_f32_16x16x32_bf16 v[48:51], v[132:135], v[190:193], v[48:51]
	v_mfma_f32_16x16x32_bf16 v[40:43], v[140:143], v[190:193], v[40:43]
	v_mfma_f32_16x16x32_bf16 v[32:35], v[132:135], v[208:211], v[32:35]
	v_mfma_f32_16x16x32_bf16 v[24:27], v[140:143], v[208:211], v[24:27]
	v_mfma_f32_16x16x32_bf16 v[16:19], v[132:135], v[216:219], v[16:19]
	v_mfma_f32_16x16x32_bf16 v[8:11], v[140:143], v[216:219], v[8:11]
	v_mfma_f32_16x16x32_bf16 v[52:55], v[144:147], v[160:163], v[52:55]
	v_mfma_f32_16x16x32_bf16 v[44:47], v[152:155], v[160:163], v[44:47]
	v_mfma_f32_16x16x32_bf16 v[36:39], v[144:147], v[186:189], v[36:39]
	v_mfma_f32_16x16x32_bf16 v[28:31], v[152:155], v[186:189], v[28:31]
	v_mfma_f32_16x16x32_bf16 v[20:23], v[144:147], v[204:207], v[20:23]
	v_mfma_f32_16x16x32_bf16 v[12:15], v[152:155], v[204:207], v[12:15]
	v_mfma_f32_16x16x32_bf16 v[4:7], v[144:147], v[212:215], v[4:7]
	v_mfma_f32_16x16x32_bf16 v[0:3], v[152:155], v[212:215], v[0:3]
	v_mfma_f32_16x16x32_bf16 v[52:55], v[148:151], v[182:185], v[52:55]
	v_mfma_f32_16x16x32_bf16 v[44:47], v[156:159], v[182:185], v[44:47]
	v_mfma_f32_16x16x32_bf16 v[36:39], v[148:151], v[190:193], v[36:39]
	v_mfma_f32_16x16x32_bf16 v[28:31], v[156:159], v[190:193], v[28:31]
	v_mfma_f32_16x16x32_bf16 v[20:23], v[148:151], v[208:211], v[20:23]
	v_mfma_f32_16x16x32_bf16 v[12:15], v[156:159], v[208:211], v[12:15]
	v_mfma_f32_16x16x32_bf16 v[4:7], v[148:151], v[216:219], v[4:7]
	v_mfma_f32_16x16x32_bf16 v[0:3], v[156:159], v[216:219], v[0:3]
	s_barrier
	s_setprio 0
	s_add_i32 s48, s48, 2
	s_add_u32 s24, s24, 0x100
	s_addc_u32 s25, s25, 0
	s_add_u32 s46, s46, 0x100
	s_addc_u32 s47, s47, 0
.LBB0_1193:
	ds_read_b128 v[128:131], v201
	ds_read_b128 v[132:135], v201 offset:1024
	ds_read_b128 v[136:139], v201 offset:2048
	ds_read_b128 v[140:143], v201 offset:3072
	ds_read_b128 v[144:147], v202
	ds_read_b128 v[148:151], v202 offset:1024
	ds_read_b128 v[152:155], v202 offset:2048
	ds_read_b128 v[156:159], v202 offset:3072
	s_add_u32 s14, s24, 0xffea0080
	s_addc_u32 s15, s25, -1
	s_cmpk_eq_i32 s48, 0x54
	s_cselect_b32 s27, s5, s15
	s_cselect_b32 s26, s4, s14
	s_cselect_b32 s15, s23, s47
	s_cselect_b32 s14, s22, s46
	v_lshl_add_u64 v[220:221], s[24:25], 0, v[172:173]
	s_add_i32 m0, s31, 0xc000
	ds_read_b128 v[160:163], v203
	ds_read_b128 v[182:185], v203 offset:1024
	ds_read_b128 v[186:189], v203 offset:2048
	ds_read_b128 v[190:193], v203 offset:3072
	ds_read_b128 v[204:207], v203 offset:4096
	ds_read_b128 v[208:211], v203 offset:5120
	ds_read_b128 v[212:215], v203 offset:6144
	ds_read_b128 v[216:219], v203 offset:7168
	global_load_lds_dwordx4 v[220:221], off
	v_lshl_add_u64 v[220:221], s[24:25], 0, v[174:175]
	s_add_i32 m0, s31, 0xe000
	s_nop 0
	global_load_lds_dwordx4 v[220:221], off
	s_waitcnt vmcnt(8)
	s_waitcnt lgkmcnt(0)
	s_setprio 1
	s_barrier
; #define PG8_STAGE(bufoff, gbase, voff) do { _Pragma("unroll") for (int _i = 0; _i < 2; ++_i) \
;         __builtin_amdgcn_global_load_lds((const unsigned*)((const char*)(gbase) + (voff)[_i]), (PG8_LAS unsigned*)(lds + (bufoff) + ldsw + _i * 8192), 16, 0, 0); } while (0)
; #define PG8_LDA(dst, b, h) do { _Pragma("unroll") for (int m = 0; m < 4; ++m) _Pragma("unroll") for (int k = 0; k < 2; ++k) dst[m][k] = *(const PG8_LAS bf16x8*)(lds + PG8_SA(b, h) + aoff + m * 2048 + k * 1024); } while (0)
; #define PG8_MMA(ai, bj, At, Bt) do { __builtin_amdgcn_s_setprio(1); _Pragma("unroll") for (int m = 0; m < 4; ++m) _Pragma("unroll") for (int n = 0; n < 2; ++n) _Pragma("unroll") for (int k = 0; k < 2; ++k) \
;         acc[ai][bj][m][n] = __builtin_amdgcn_mfma_f32_16x16x32_bf16(Bt[n][k], At[m][k], acc[ai][bj][m][n], 0, 0, 0); __builtin_amdgcn_s_setprio(0); } while (0)
; #define PG8_WAIT_V(n) asm volatile("s_waitcnt vmcnt(" #n ")" ::: "memory")
; #define PG8_WAIT_L(n) asm volatile("s_waitcnt lgkmcnt(" #n ")" ::: "memory")
; #define PG8_BAR __builtin_amdgcn_s_barrier()
; #define PG8_SCHED __builtin_amdgcn_sched_barrier(0)
; template <class Epi, class Sched, bool ALIGN_EPI = false, bool SP2 = false, bool DUAL = false>
; __device__ __forceinline__ void gemm_phase(PG8_LAS unsigned char* lds, const Gemm g, const Sched& S, const Epi& E) {
;     ...
;             PG8_WAIT_V(8); PG8_WAIT_L(0); PG8_BAR; PG8_MMA(0, 0, At, B0); PG8_MMA(0, 1, At, B1); PG8_BAR; PG8_SCHED;
;             PG8_LDA(At, 0, 1); PG8_STAGE(PG8_SB(0, 0), b2, voffB); PG8_STAGE(PG8_SB(0, 1), b2 + hstep, voffB); PG8_STAGE(PG8_SA(0, 0), a2, voffA);
;             PG8_WAIT_V(8); PG8_WAIT_L(0); PG8_BAR; PG8_MMA(1, 0, At, B0); PG8_MMA(1, 1, At, B1); PG8_BAR; PG8_SCHED;
	v_mfma_f32_16x16x32_bf16 v[124:127], v[128:131], v[160:163], v[124:127]
	v_mfma_f32_16x16x32_bf16 v[120:123], v[136:139], v[160:163], v[120:123]
	v_mfma_f32_16x16x32_bf16 v[112:115], v[128:131], v[186:189], v[112:115]
	v_mfma_f32_16x16x32_bf16 v[104:107], v[136:139], v[186:189], v[104:107]
	v_mfma_f32_16x16x32_bf16 v[96:99], v[128:131], v[204:207], v[96:99]
	v_mfma_f32_16x16x32_bf16 v[88:91], v[136:139], v[204:207], v[88:91]
	v_mfma_f32_16x16x32_bf16 v[80:83], v[128:131], v[212:215], v[80:83]
	v_mfma_f32_16x16x32_bf16 v[72:75], v[136:139], v[212:215], v[72:75]
	v_mfma_f32_16x16x32_bf16 v[124:127], v[132:135], v[182:185], v[124:127]
	v_mfma_f32_16x16x32_bf16 v[120:123], v[140:143], v[182:185], v[120:123]
	v_mfma_f32_16x16x32_bf16 v[112:115], v[132:135], v[190:193], v[112:115]
	v_mfma_f32_16x16x32_bf16 v[104:107], v[140:143], v[190:193], v[104:107]
	v_mfma_f32_16x16x32_bf16 v[96:99], v[132:135], v[208:211], v[96:99]
	v_mfma_f32_16x16x32_bf16 v[88:91], v[140:143], v[208:211], v[88:91]
	v_mfma_f32_16x16x32_bf16 v[80:83], v[132:135], v[216:219], v[80:83]
	v_mfma_f32_16x16x32_bf16 v[72:75], v[140:143], v[216:219], v[72:75]
	v_mfma_f32_16x16x32_bf16 v[116:119], v[144:147], v[160:163], v[116:119]
	v_mfma_f32_16x16x32_bf16 v[108:111], v[152:155], v[160:163], v[108:111]
	v_mfma_f32_16x16x32_bf16 v[100:103], v[144:147], v[186:189], v[100:103]
	v_mfma_f32_16x16x32_bf16 v[92:95], v[152:155], v[186:189], v[92:95]
	v_mfma_f32_16x16x32_bf16 v[84:87], v[144:147], v[204:207], v[84:87]
	v_mfma_f32_16x16x32_bf16 v[76:79], v[152:155], v[204:207], v[76:79]
	v_mfma_f32_16x16x32_bf16 v[68:71], v[144:147], v[212:215], v[68:71]
	v_mfma_f32_16x16x32_bf16 v[64:67], v[152:155], v[212:215], v[64:67]
	v_mfma_f32_16x16x32_bf16 v[116:119], v[148:151], v[182:185], v[116:119]
	v_mfma_f32_16x16x32_bf16 v[108:111], v[156:159], v[182:185], v[108:111]
	v_mfma_f32_16x16x32_bf16 v[100:103], v[148:151], v[190:193], v[100:103]
	v_mfma_f32_16x16x32_bf16 v[92:95], v[156:159], v[190:193], v[92:95]
	v_mfma_f32_16x16x32_bf16 v[84:87], v[148:151], v[208:211], v[84:87]
	v_mfma_f32_16x16x32_bf16 v[76:79], v[156:159], v[208:211], v[76:79]
	v_mfma_f32_16x16x32_bf16 v[68:71], v[148:151], v[216:219], v[68:71]
	v_mfma_f32_16x16x32_bf16 v[64:67], v[156:159], v[216:219], v[64:67]
	s_barrier
	s_setprio 0
	s_add_i32 s49, s40, s30
	v_lshl_add_u64 v[220:221], s[14:15], 0, v[166:167]
	s_mov_b32 m0, s49
	ds_read_b128 v[160:163], v203 offset:16384
	ds_read_b128 v[182:185], v203 offset:17408
	ds_read_b128 v[186:189], v203 offset:18432
	ds_read_b128 v[190:193], v203 offset:19456
	ds_read_b128 v[204:207], v203 offset:20480
	ds_read_b128 v[208:211], v203 offset:21504
	ds_read_b128 v[212:215], v203 offset:22528
	ds_read_b128 v[216:219], v203 offset:23552
	global_load_lds_dwordx4 v[220:221], off
	s_add_i32 m0, s49, 0x2000
	s_add_u32 s50, s14, 0x160000
	v_lshl_add_u64 v[222:223], s[14:15], 0, v[170:171]
	s_addc_u32 s51, s15, 0
	s_add_i32 s49, s41, s30
	global_load_lds_dwordx4 v[222:223], off
	v_lshl_add_u64 v[224:225], s[50:51], 0, v[166:167]
	s_mov_b32 m0, s49
	v_lshl_add_u64 v[226:227], s[26:27], 0, v[168:169]
	global_load_lds_dwordx4 v[224:225], off
	v_lshl_add_u64 v[224:225], s[50:51], 0, v[170:171]
	s_add_i32 m0, s49, 0x2000
	s_nop 0
	global_load_lds_dwordx4 v[224:225], off
	v_lshl_add_u64 v[224:225], s[26:27], 0, v[164:165]
	s_mov_b32 m0, s31
	s_nop 0
	global_load_lds_dwordx4 v[224:225], off
	s_mov_b32 m0, s33
	s_nop 0
	global_load_lds_dwordx4 v[226:227], off
	s_waitcnt vmcnt(8)
	s_waitcnt lgkmcnt(0)
	s_setprio 1
	s_barrier
	v_mfma_f32_16x16x32_bf16 v[60:63], v[128:131], v[160:163], v[60:63]
	v_mfma_f32_16x16x32_bf16 v[56:59], v[136:139], v[160:163], v[56:59]
	v_mfma_f32_16x16x32_bf16 v[48:51], v[128:131], v[186:189], v[48:51]
	v_mfma_f32_16x16x32_bf16 v[40:43], v[136:139], v[186:189], v[40:43]
	v_mfma_f32_16x16x32_bf16 v[32:35], v[128:131], v[204:207], v[32:35]
	v_mfma_f32_16x16x32_bf16 v[24:27], v[136:139], v[204:207], v[24:27]
	v_mfma_f32_16x16x32_bf16 v[16:19], v[128:131], v[212:215], v[16:19]
	v_mfma_f32_16x16x32_bf16 v[8:11], v[136:139], v[212:215], v[8:11]
	v_mfma_f32_16x16x32_bf16 v[60:63], v[132:135], v[182:185], v[60:63]
	v_mfma_f32_16x16x32_bf16 v[56:59], v[140:143], v[182:185], v[56:59]
	v_mfma_f32_16x16x32_bf16 v[48:51], v[132:135], v[190:193], v[48:51]
	v_mfma_f32_16x16x32_bf16 v[40:43], v[140:143], v[190:193], v[40:43]
	v_mfma_f32_16x16x32_bf16 v[32:35], v[132:135], v[208:211], v[32:35]
	v_mfma_f32_16x16x32_bf16 v[24:27], v[140:143], v[208:211], v[24:27]
	v_mfma_f32_16x16x32_bf16 v[16:19], v[132:135], v[216:219], v[16:19]
	v_mfma_f32_16x16x32_bf16 v[8:11], v[140:143], v[216:219], v[8:11]
	v_mfma_f32_16x16x32_bf16 v[52:55], v[144:147], v[160:163], v[52:55]
	v_mfma_f32_16x16x32_bf16 v[44:47], v[152:155], v[160:163], v[44:47]
	v_mfma_f32_16x16x32_bf16 v[36:39], v[144:147], v[186:189], v[36:39]
	v_mfma_f32_16x16x32_bf16 v[28:31], v[152:155], v[186:189], v[28:31]
	v_mfma_f32_16x16x32_bf16 v[20:23], v[144:147], v[204:207], v[20:23]
	v_mfma_f32_16x16x32_bf16 v[12:15], v[152:155], v[204:207], v[12:15]
	v_mfma_f32_16x16x32_bf16 v[4:7], v[144:147], v[212:215], v[4:7]
	v_mfma_f32_16x16x32_bf16 v[0:3], v[152:155], v[212:215], v[0:3]
	v_mfma_f32_16x16x32_bf16 v[52:55], v[148:151], v[182:185], v[52:55]
	v_mfma_f32_16x16x32_bf16 v[44:47], v[156:159], v[182:185], v[44:47]
	v_mfma_f32_16x16x32_bf16 v[36:39], v[148:151], v[190:193], v[36:39]
	v_mfma_f32_16x16x32_bf16 v[28:31], v[156:159], v[190:193], v[28:31]
	v_mfma_f32_16x16x32_bf16 v[20:23], v[148:151], v[208:211], v[20:23]
	v_mfma_f32_16x16x32_bf16 v[12:15], v[156:159], v[208:211], v[12:15]
	v_mfma_f32_16x16x32_bf16 v[4:7], v[148:151], v[216:219], v[4:7]
	v_mfma_f32_16x16x32_bf16 v[0:3], v[156:159], v[216:219], v[0:3]
	s_barrier
; #define PG8_STAGE(bufoff, gbase, voff) do { _Pragma("unroll") for (int _i = 0; _i < 2; ++_i) \
;         __builtin_amdgcn_global_load_lds((const unsigned*)((const char*)(gbase) + (voff)[_i]), (PG8_LAS unsigned*)(lds + (bufoff) + ldsw + _i * 8192), 16, 0, 0); } while (0)
; #define PG8_LDA(dst, b, h) do { _Pragma("unroll") for (int m = 0; m < 4; ++m) _Pragma("unroll") for (int k = 0; k < 2; ++k) dst[m][k] = *(const PG8_LAS bf16x8*)(lds + PG8_SA(b, h) + aoff + m * 2048 + k * 1024); } while (0)
; #define PG8_LDB(dst, b, h) do { _Pragma("unroll") for (int n = 0; n < 2; ++n) _Pragma("unroll") for (int k = 0; k < 2; ++k) dst[n][k] = *(const PG8_LAS bf16x8*)(lds + PG8_SB(b, h) + boff + n * 2048 + k * 1024); } while (0)
; #define PG8_MMA(ai, bj, At, Bt) do { __builtin_amdgcn_s_setprio(1); _Pragma("unroll") for (int m = 0; m < 4; ++m) _Pragma("unroll") for (int n = 0; n < 2; ++n) _Pragma("unroll") for (int k = 0; k < 2; ++k) \
;         acc[ai][bj][m][n] = __builtin_amdgcn_mfma_f32_16x16x32_bf16(Bt[n][k], At[m][k], acc[ai][bj][m][n], 0, 0, 0); __builtin_amdgcn_s_setprio(0); } while (0)
; #define PG8_WAIT_V(n) asm volatile("s_waitcnt vmcnt(" #n ")" ::: "memory")
; #define PG8_WAIT_L(n) asm volatile("s_waitcnt lgkmcnt(" #n ")" ::: "memory")
; #define PG8_BAR __builtin_amdgcn_s_barrier()
; #define PG8_SCHED __builtin_amdgcn_sched_barrier(0)
; template <class Epi, class Sched, bool ALIGN_EPI = false, bool SP2 = false, bool DUAL = false>
; __device__ __forceinline__ void gemm_phase(PG8_LAS unsigned char* lds, const Gemm g, const Sched& S, const Epi& E) {
;     ...
;             PG8_LDB(B0, 1, 0); PG8_LDB(B1, 1, 1); PG8_SCHED; PG8_LDA(At, 1, 0); PG8_STAGE(PG8_SA(0, 1), a2 + hstep, voffA);
;             PG8_WAIT_V(8); PG8_WAIT_L(0); PG8_BAR; PG8_MMA(0, 0, At, B0); PG8_MMA(0, 1, At, B1); PG8_BAR; PG8_SCHED;
	s_setprio 0
	s_add_i32 s49, 0, 0x18000
	s_add_i32 s50, 0, 0x1c000
	v_add_u32_e32 v140, s49, v198
	v_add_u32_e32 v156, s50, v198
	ds_read_b128 v[128:131], v140
	ds_read_b128 v[132:135], v140 offset:1024
	ds_read_b128 v[136:139], v140 offset:2048
	ds_read_b128 v[140:143], v140 offset:3072
	ds_read_b128 v[144:147], v156
	ds_read_b128 v[148:151], v156 offset:1024
	ds_read_b128 v[152:155], v156 offset:2048
	ds_read_b128 v[156:159], v156 offset:3072
	s_add_u32 s26, s26, 0x160000
	s_addc_u32 s27, s27, 0
	s_mov_b32 m0, s34
	v_lshl_add_u64 v[228:229], s[26:27], 0, v[164:165]
	ds_read_b128 v[160:163], v203 offset:32768
	ds_read_b128 v[182:185], v203 offset:33792
	ds_read_b128 v[186:189], v203 offset:34816
	ds_read_b128 v[190:193], v203 offset:35840
	ds_read_b128 v[204:207], v203 offset:36864
	ds_read_b128 v[208:211], v203 offset:37888
	ds_read_b128 v[212:215], v203 offset:38912
	ds_read_b128 v[216:219], v203 offset:39936
	global_load_lds_dwordx4 v[228:229], off
	v_lshl_add_u64 v[228:229], s[26:27], 0, v[168:169]
	s_mov_b32 m0, s35
	s_nop 0
	global_load_lds_dwordx4 v[228:229], off
	s_waitcnt vmcnt(8)
	s_waitcnt lgkmcnt(0)
	s_setprio 1
	s_barrier
	v_mfma_f32_16x16x32_bf16 v[124:127], v[128:131], v[160:163], v[124:127]
	v_mfma_f32_16x16x32_bf16 v[120:123], v[136:139], v[160:163], v[120:123]
	v_mfma_f32_16x16x32_bf16 v[112:115], v[128:131], v[186:189], v[112:115]
	v_mfma_f32_16x16x32_bf16 v[104:107], v[136:139], v[186:189], v[104:107]
	v_mfma_f32_16x16x32_bf16 v[96:99], v[128:131], v[204:207], v[96:99]
	v_mfma_f32_16x16x32_bf16 v[88:91], v[136:139], v[204:207], v[88:91]
	v_mfma_f32_16x16x32_bf16 v[80:83], v[128:131], v[212:215], v[80:83]
	v_mfma_f32_16x16x32_bf16 v[72:75], v[136:139], v[212:215], v[72:75]
	v_mfma_f32_16x16x32_bf16 v[124:127], v[132:135], v[182:185], v[124:127]
	v_mfma_f32_16x16x32_bf16 v[120:123], v[140:143], v[182:185], v[120:123]
	v_mfma_f32_16x16x32_bf16 v[112:115], v[132:135], v[190:193], v[112:115]
	v_mfma_f32_16x16x32_bf16 v[104:107], v[140:143], v[190:193], v[104:107]
	v_mfma_f32_16x16x32_bf16 v[96:99], v[132:135], v[208:211], v[96:99]
	v_mfma_f32_16x16x32_bf16 v[88:91], v[140:143], v[208:211], v[88:91]
	v_mfma_f32_16x16x32_bf16 v[80:83], v[132:135], v[216:219], v[80:83]
	v_mfma_f32_16x16x32_bf16 v[72:75], v[140:143], v[216:219], v[72:75]
	v_mfma_f32_16x16x32_bf16 v[116:119], v[144:147], v[160:163], v[116:119]
	v_mfma_f32_16x16x32_bf16 v[108:111], v[152:155], v[160:163], v[108:111]
	v_mfma_f32_16x16x32_bf16 v[100:103], v[144:147], v[186:189], v[100:103]
	v_mfma_f32_16x16x32_bf16 v[92:95], v[152:155], v[186:189], v[92:95]
	v_mfma_f32_16x16x32_bf16 v[84:87], v[144:147], v[204:207], v[84:87]
	v_mfma_f32_16x16x32_bf16 v[76:79], v[152:155], v[204:207], v[76:79]
	v_mfma_f32_16x16x32_bf16 v[68:71], v[144:147], v[212:215], v[68:71]
	v_mfma_f32_16x16x32_bf16 v[64:67], v[152:155], v[212:215], v[64:67]
	v_mfma_f32_16x16x32_bf16 v[116:119], v[148:151], v[182:185], v[116:119]
	v_mfma_f32_16x16x32_bf16 v[108:111], v[156:159], v[182:185], v[108:111]
	v_mfma_f32_16x16x32_bf16 v[100:103], v[148:151], v[190:193], v[100:103]
	v_mfma_f32_16x16x32_bf16 v[92:95], v[156:159], v[190:193], v[92:95]
	v_mfma_f32_16x16x32_bf16 v[84:87], v[148:151], v[208:211], v[84:87]
	v_mfma_f32_16x16x32_bf16 v[76:79], v[156:159], v[208:211], v[76:79]
	v_mfma_f32_16x16x32_bf16 v[68:71], v[148:151], v[216:219], v[68:71]
	v_mfma_f32_16x16x32_bf16 v[64:67], v[156:159], v[216:219], v[64:67]
	s_barrier
; #define PG8_STAGE(bufoff, gbase, voff) do { _Pragma("unroll") for (int _i = 0; _i < 2; ++_i) \
;         __builtin_amdgcn_global_load_lds((const unsigned*)((const char*)(gbase) + (voff)[_i]), (PG8_LAS unsigned*)(lds + (bufoff) + ldsw + _i * 8192), 16, 0, 0); } while (0)
; #define PG8_LDA(dst, b, h) do { _Pragma("unroll") for (int m = 0; m < 4; ++m) _Pragma("unroll") for (int k = 0; k < 2; ++k) dst[m][k] = *(const PG8_LAS bf16x8*)(lds + PG8_SA(b, h) + aoff + m * 2048 + k * 1024); } while (0)
; #define PG8_MMA(ai, bj, At, Bt) do { __builtin_amdgcn_s_setprio(1); _Pragma("unroll") for (int m = 0; m < 4; ++m) _Pragma("unroll") for (int n = 0; n < 2; ++n) _Pragma("unroll") for (int k = 0; k < 2; ++k) \
;         acc[ai][bj][m][n] = __builtin_amdgcn_mfma_f32_16x16x32_bf16(Bt[n][k], At[m][k], acc[ai][bj][m][n], 0, 0, 0); __builtin_amdgcn_s_setprio(0); } while (0)
; #define PG8_WAIT_V(n) asm volatile("s_waitcnt vmcnt(" #n ")" ::: "memory")
; #define PG8_WAIT_L(n) asm volatile("s_waitcnt lgkmcnt(" #n ")" ::: "memory")
; #define PG8_BAR __builtin_amdgcn_s_barrier()
; #define PG8_SCHED __builtin_amdgcn_sched_barrier(0)
; template <class Epi, class Sched, bool ALIGN_EPI = false, bool SP2 = false, bool DUAL = false>
; __device__ __forceinline__ void gemm_phase(PG8_LAS unsigned char* lds, const Gemm g, const Sched& S, const Epi& E) {
;     ...
;         for (int t = 0; t < nt; t += 2) {
;     ...
;             PG8_LDA(At, 1, 1); PG8_STAGE(PG8_SB(1, 0), b3, voffB); PG8_STAGE(PG8_SB(1, 1), b3 + hstep, voffB); PG8_STAGE(PG8_SA(1, 0), a3, voffA);
;             PG8_WAIT_V(8); PG8_WAIT_L(0); PG8_BAR; PG8_MMA(1, 0, At, B0); PG8_MMA(1, 1, At, B1); PG8_BAR; PG8_SCHED;
	s_setprio 0
	s_add_i32 s26, s49, s30
	v_lshl_add_u64 v[220:221], v[220:221], 0, s[18:19]
	s_mov_b32 m0, s26
	ds_read_b128 v[160:163], v203 offset:49152
	ds_read_b128 v[182:185], v203 offset:50176
	ds_read_b128 v[186:189], v203 offset:51200
	ds_read_b128 v[190:193], v203 offset:52224
	ds_read_b128 v[204:207], v203 offset:53248
	ds_read_b128 v[208:211], v203 offset:54272
	ds_read_b128 v[212:215], v203 offset:55296
	ds_read_b128 v[216:219], v203 offset:56320
	global_load_lds_dwordx4 v[220:221], off
	s_add_i32 m0, s26, 0x2000
	s_add_u32 s14, s14, 0x160080
	v_lshl_add_u64 v[220:221], v[222:223], 0, s[18:19]
	s_addc_u32 s15, s15, 0
	s_add_i32 s26, s50, s30
	global_load_lds_dwordx4 v[220:221], off
	v_lshl_add_u64 v[220:221], s[14:15], 0, v[166:167]
	s_mov_b32 m0, s26
	s_nop 0
	global_load_lds_dwordx4 v[220:221], off
	v_lshl_add_u64 v[220:221], s[14:15], 0, v[170:171]
	s_add_i32 m0, s26, 0x2000
	s_nop 0
	global_load_lds_dwordx4 v[220:221], off
	v_lshl_add_u64 v[220:221], v[224:225], 0, s[18:19]
	s_mov_b32 m0, s37
	s_nop 0
	global_load_lds_dwordx4 v[220:221], off
	v_lshl_add_u64 v[220:221], v[226:227], 0, s[18:19]
	s_mov_b32 m0, s38
	s_nop 0
	global_load_lds_dwordx4 v[220:221], off
	s_waitcnt vmcnt(8)
	s_waitcnt lgkmcnt(0)
	s_setprio 1
	s_barrier
	v_mfma_f32_16x16x32_bf16 v[60:63], v[128:131], v[160:163], v[60:63]
	v_mfma_f32_16x16x32_bf16 v[56:59], v[136:139], v[160:163], v[56:59]
	v_mfma_f32_16x16x32_bf16 v[48:51], v[128:131], v[186:189], v[48:51]
	v_mfma_f32_16x16x32_bf16 v[40:43], v[136:139], v[186:189], v[40:43]
	v_mfma_f32_16x16x32_bf16 v[32:35], v[128:131], v[204:207], v[32:35]
	v_mfma_f32_16x16x32_bf16 v[24:27], v[136:139], v[204:207], v[24:27]
	v_mfma_f32_16x16x32_bf16 v[16:19], v[128:131], v[212:215], v[16:19]
	v_mfma_f32_16x16x32_bf16 v[8:11], v[136:139], v[212:215], v[8:11]
	v_mfma_f32_16x16x32_bf16 v[60:63], v[132:135], v[182:185], v[60:63]
	v_mfma_f32_16x16x32_bf16 v[56:59], v[140:143], v[182:185], v[56:59]
	v_mfma_f32_16x16x32_bf16 v[48:51], v[132:135], v[190:193], v[48:51]
	v_mfma_f32_16x16x32_bf16 v[40:43], v[140:143], v[190:193], v[40:43]
	v_mfma_f32_16x16x32_bf16 v[32:35], v[132:135], v[208:211], v[32:35]
	v_mfma_f32_16x16x32_bf16 v[24:27], v[140:143], v[208:211], v[24:27]
	v_mfma_f32_16x16x32_bf16 v[16:19], v[132:135], v[216:219], v[16:19]
	v_mfma_f32_16x16x32_bf16 v[8:11], v[140:143], v[216:219], v[8:11]
	v_mfma_f32_16x16x32_bf16 v[52:55], v[144:147], v[160:163], v[52:55]
	v_mfma_f32_16x16x32_bf16 v[44:47], v[152:155], v[160:163], v[44:47]
	v_mfma_f32_16x16x32_bf16 v[36:39], v[144:147], v[186:189], v[36:39]
	v_mfma_f32_16x16x32_bf16 v[28:31], v[152:155], v[186:189], v[28:31]
	v_mfma_f32_16x16x32_bf16 v[20:23], v[144:147], v[204:207], v[20:23]
	v_mfma_f32_16x16x32_bf16 v[12:15], v[152:155], v[204:207], v[12:15]
	v_mfma_f32_16x16x32_bf16 v[4:7], v[144:147], v[212:215], v[4:7]
	v_mfma_f32_16x16x32_bf16 v[0:3], v[152:155], v[212:215], v[0:3]
	v_mfma_f32_16x16x32_bf16 v[52:55], v[148:151], v[182:185], v[52:55]
	v_mfma_f32_16x16x32_bf16 v[44:47], v[156:159], v[182:185], v[44:47]
	v_mfma_f32_16x16x32_bf16 v[36:39], v[148:151], v[190:193], v[36:39]
	v_mfma_f32_16x16x32_bf16 v[28:31], v[156:159], v[190:193], v[28:31]
	v_mfma_f32_16x16x32_bf16 v[20:23], v[148:151], v[208:211], v[20:23]
	v_mfma_f32_16x16x32_bf16 v[12:15], v[156:159], v[208:211], v[12:15]
	v_mfma_f32_16x16x32_bf16 v[4:7], v[148:151], v[216:219], v[4:7]
	v_mfma_f32_16x16x32_bf16 v[0:3], v[156:159], v[216:219], v[0:3]
	s_barrier
	s_setprio 0
	s_add_i32 s48, s48, 2
	s_add_u32 s24, s24, 0x100
	s_addc_u32 s25, s25, 0
	s_add_u32 s46, s46, 0x100
	s_addc_u32 s47, s47, 0
	s_cmpk_gt_u32 s48, 0x55
	s_cbranch_scc0 .LBB0_1193
	s_and_b64 vcc, exec, s[20:21]
	s_cbranch_vccz .LBB0_1196
	s_barrier
